# s8p + last unit of every GEMM phase stores its tile write-through (sc1) so the grid-barrier release write-back finds a clean L2
# speedup vs baseline: 1.0138x; 1.0124x over previous
.LBB0_325:
	s_lshl_b32 s0, s89, 8
	v_add_u32_e32 v176, s0, v171
	v_ashrrev_i32_e32 v177, 31, v176
	v_or_b32_e32 v172, 16, v176
	v_lshlrev_b64 v[132:133], 6, v[176:177]
	v_ashrrev_i32_e32 v173, 31, v172
	v_or_b32_e32 v168, 32, v176
	v_lshl_add_u64 v[132:133], v[154:155], 0, v[132:133]
	v_lshlrev_b64 v[134:135], 6, v[172:173]
	v_ashrrev_i32_e32 v169, 31, v168
	v_lshl_add_u64 v[134:135], v[154:155], 0, v[134:135]
	global_load_dwordx4 v[180:183], v[132:133], off
	global_load_dwordx4 v[184:187], v[134:135], off
	v_lshlrev_b64 v[132:133], 6, v[168:169]
	v_lshl_add_u64 v[132:133], v[154:155], 0, v[132:133]
	global_load_dwordx4 v[188:191], v[132:133], off
	v_or_b32_e32 v166, 48, v176
	v_ashrrev_i32_e32 v167, 31, v166
	v_lshlrev_b64 v[132:133], 6, v[166:167]
	v_lshl_add_u64 v[132:133], v[154:155], 0, v[132:133]
	global_load_dwordx4 v[192:195], v[132:133], off
	v_add_u32_e32 v162, 0x80, v176
	v_ashrrev_i32_e32 v163, 31, v162
	v_lshlrev_b64 v[132:133], 6, v[162:163]
	v_lshl_add_u64 v[132:133], v[154:155], 0, v[132:133]
	global_load_dwordx4 v[204:207], v[132:133], off
	s_addk_i32 s0, 0xc000
	s_lshr_b32 s0, s0, 12
	v_add_u32_e32 v164, 0x90, v176
	s_ashr_i32 s1, s89, 5
	v_and_b32_e32 v132, 64, v229
	v_ashrrev_i32_e32 v165, 31, v164
	s_add_i32 s0, s0, 2
	v_add_u32_e32 v136, 64, v132
	v_lshlrev_b64 v[132:133], 6, v[164:165]
	v_add_u32_e32 v160, 0xa0, v176
	s_cmp_lt_i32 s89, 64
	v_lshl_add_u64 v[132:133], v[154:155], 0, v[132:133]
	v_ashrrev_i32_e32 v161, 31, v160
	s_cselect_b32 s0, s1, s0
	v_xor_b32_e32 v134, 16, v229
	global_load_dwordx4 v[208:211], v[132:133], off
	v_add_u32_e32 v158, 0xb0, v176
	v_lshlrev_b64 v[132:133], 6, v[160:161]
	s_mul_hi_i32 s1, s0, 0x1800
	s_mulk_i32 s0, 0x1800
	v_lshl_or_b32 v156, s90, 8, v178
	v_xor_b32_e32 v135, 32, v229
	v_cmp_lt_i32_e32 vcc, v134, v136
	v_ashrrev_i32_e32 v159, 31, v158
	v_lshl_add_u64 v[132:133], v[154:155], 0, v[132:133]
	s_add_u32 s0, s78, s0
	v_ashrrev_i32_e32 v157, 31, v156
	v_cndmask_b32_e32 v134, v229, v134, vcc
	v_cmp_lt_i32_e32 vcc, v135, v136
	global_load_dwordx4 v[212:215], v[132:133], off
	v_lshlrev_b64 v[132:133], 6, v[158:159]
	s_addc_u32 s1, s79, s1
	v_cndmask_b32_e32 v135, v229, v135, vcc
	v_lshl_add_u64 v[132:133], v[154:155], 0, v[132:133]
	v_lshl_add_u64 v[136:137], v[156:157], 2, s[0:1]
	v_lshlrev_b32_e32 v161, 2, v134
	v_lshlrev_b32_e32 v163, 2, v135
	global_load_dwordx4 v[216:219], v[132:133], off
	global_load_dwordx4 v[140:143], v[136:137], off offset:16
	global_load_dwordx4 v[144:147], v[136:137], off
	s_nop 0
	global_load_dwordx4 v[132:135], v[136:137], off offset:528
	s_nop 0
	global_load_dwordx4 v[136:139], v[136:137], off offset:512
	s_and_b64 vcc, exec, s[36:37]
	s_waitcnt vmcnt(0)
	v_mov_b32_e32 v200, v181
	v_mov_b32_e32 v201, v182
	v_mov_b32_e32 v181, v183
	v_pk_add_f32 v[180:181], v[200:201], v[180:181]
	v_mov_b32_e32 v182, v185
	v_mov_b32_e32 v183, v186
	v_mov_b32_e32 v185, v187
	v_add_f32_e32 v159, v180, v181
	v_pk_add_f32 v[180:181], v[182:183], v[184:185]
	v_mov_b32_e32 v186, v189
	v_mov_b32_e32 v187, v190
	v_mov_b32_e32 v189, v191
	ds_bpermute_b32 v165, v161, v159
	v_add_f32_e32 v167, v180, v181
	v_pk_add_f32 v[182:183], v[186:187], v[188:189]
	ds_bpermute_b32 v173, v161, v167
	v_add_f32_e32 v169, v182, v183
	ds_bpermute_b32 v174, v161, v169
	s_waitcnt lgkmcnt(2)
	v_add_f32_e32 v159, v159, v165
	v_mov_b32_e32 v190, v193
	v_mov_b32_e32 v191, v194
	v_mov_b32_e32 v193, v195
	ds_bpermute_b32 v165, v163, v159
	s_waitcnt lgkmcnt(2)
	v_add_f32_e32 v167, v167, v173
	v_pk_add_f32 v[184:185], v[190:191], v[192:193]
	ds_bpermute_b32 v173, v163, v167
	v_add_f32_e32 v170, v184, v185
	s_waitcnt lgkmcnt(2)
	v_add_f32_e32 v169, v169, v174
	ds_bpermute_b32 v177, v161, v170
	ds_bpermute_b32 v174, v163, v169
	s_waitcnt lgkmcnt(3)
	v_add_f32_e32 v159, v159, v165
	v_fmamk_f32 v159, v159, 0x3a800000, v1
	s_waitcnt lgkmcnt(2)
	v_add_f32_e32 v165, v167, v173
	v_mov_b32_e32 v184, v205
	v_mov_b32_e32 v185, v206
	v_mov_b32_e32 v205, v207
	v_rsq_f32_e32 v180, v159
	v_fmamk_f32 v159, v165, 0x3a800000, v1
	v_pk_add_f32 v[184:185], v[184:185], v[204:205]
	v_rsq_f32_e32 v182, v159
	s_waitcnt lgkmcnt(0)
	v_add_f32_e32 v159, v169, v174
	v_add_f32_e32 v165, v170, v177
	v_add_f32_e32 v169, v184, v185
	ds_bpermute_b32 v167, v163, v165
	ds_bpermute_b32 v170, v161, v169
	v_fmamk_f32 v159, v159, 0x3a800000, v1
	v_rsq_f32_e32 v184, v159
	v_mov_b32_e32 v186, v209
	s_waitcnt lgkmcnt(1)
	v_add_f32_e32 v159, v165, v167
	s_waitcnt lgkmcnt(0)
	v_add_f32_e32 v165, v169, v170
	v_mov_b32_e32 v187, v210
	v_mov_b32_e32 v209, v211
	ds_bpermute_b32 v167, v163, v165
	v_pk_add_f32 v[186:187], v[186:187], v[208:209]
	v_mad_i64_i32 v[176:177], s[0:1], v176, s29, v[156:157]
	v_add_f32_e32 v169, v186, v187
	v_pk_fma_f32 v[130:131], v[130:131], v[180:181], v[146:147] op_sel_hi:[1,0,1]
	v_pk_fma_f32 v[128:129], v[128:129], v[180:181], v[144:145] op_sel_hi:[1,0,1]
	v_pk_fma_f32 v[192:193], v[126:127], v[180:181], v[142:143] op_sel_hi:[1,0,1]
	v_pk_fma_f32 v[126:127], v[124:125], v[180:181], v[140:141] op_sel_hi:[1,0,1]
	ds_bpermute_b32 v170, v161, v169
	v_cvt_pk_bf16_f32 v124, v128, v129
	v_cvt_pk_bf16_f32 v125, v130, v131
	v_cvt_pk_bf16_f32 v126, v126, v127
	v_cvt_pk_bf16_f32 v127, v192, v193
	v_lshl_add_u64 v[128:129], v[176:177], 1, s[24:25]
	s_cbranch_vccz .Lmy_wt_g1_0
	global_store_dwordx4 v[128:129], v[124:127], off
.Lmy_wt_g1_0r:
	v_pk_fma_f32 v[118:119], v[118:119], v[180:181], v[138:139] op_sel_hi:[1,0,1]
	v_pk_fma_f32 v[116:117], v[116:117], v[180:181], v[136:137] op_sel_hi:[1,0,1]
	v_pk_fma_f32 v[124:125], v[110:111], v[180:181], v[134:135] op_sel_hi:[1,0,1]
	v_pk_fma_f32 v[110:111], v[108:109], v[180:181], v[132:133] op_sel_hi:[1,0,1]
	v_fmamk_f32 v159, v159, 0x3a800000, v1
	v_cvt_pk_bf16_f32 v108, v116, v117
	v_cvt_pk_bf16_f32 v109, v118, v119
	v_cvt_pk_bf16_f32 v110, v110, v111
	v_cvt_pk_bf16_f32 v111, v124, v125
	v_rsq_f32_e32 v186, v159
	s_waitcnt lgkmcnt(1)
	v_add_f32_e32 v159, v165, v167
	v_mov_b32_e32 v190, v213
	v_mov_b32_e32 v191, v214
	v_mov_b32_e32 v213, v215
	s_cbranch_vccz .Lmy_wt_g1_1
	global_store_dwordx4 v[128:129], v[108:111], off offset:256
.Lmy_wt_g1_1r:
	v_mad_i64_i32 v[116:117], s[0:1], v172, s29, v[156:157]
	s_nop 0
	v_pk_fma_f32 v[110:111], v[122:123], v[182:183], v[146:147] op_sel_hi:[1,0,1]
	v_pk_fma_f32 v[108:109], v[120:121], v[182:183], v[144:145] op_sel_hi:[1,0,1]
	v_pk_fma_f32 v[114:115], v[114:115], v[182:183], v[142:143] op_sel_hi:[1,0,1]
	v_pk_fma_f32 v[112:113], v[112:113], v[182:183], v[140:141] op_sel_hi:[1,0,1]
	v_fmamk_f32 v159, v159, 0x3a800000, v1
	v_pk_add_f32 v[190:191], v[190:191], v[212:213]
	v_cvt_pk_bf16_f32 v108, v108, v109
	v_cvt_pk_bf16_f32 v109, v110, v111
	v_cvt_pk_bf16_f32 v110, v112, v113
	v_cvt_pk_bf16_f32 v111, v114, v115
	v_lshl_add_u64 v[112:113], v[116:117], 1, s[24:25]
	v_rsq_f32_e32 v188, v159
	s_waitcnt lgkmcnt(0)
	v_add_f32_e32 v159, v169, v170
	v_add_f32_e32 v167, v190, v191
	s_cbranch_vccz .Lmy_wt_g1_2
	global_store_dwordx4 v[112:113], v[108:111], off
.Lmy_wt_g1_2r:
	v_pk_fma_f32 v[102:103], v[102:103], v[182:183], v[138:139] op_sel_hi:[1,0,1]
	v_pk_fma_f32 v[100:101], v[100:101], v[182:183], v[136:137] op_sel_hi:[1,0,1]
	v_pk_fma_f32 v[108:109], v[92:93], v[182:183], v[134:135] op_sel_hi:[1,0,1]
	v_pk_fma_f32 v[92:93], v[90:91], v[182:183], v[132:133] op_sel_hi:[1,0,1]
	ds_bpermute_b32 v165, v163, v159
	ds_bpermute_b32 v169, v161, v167
	v_cvt_pk_bf16_f32 v90, v100, v101
	v_cvt_pk_bf16_f32 v91, v102, v103
	v_cvt_pk_bf16_f32 v92, v92, v93
	v_cvt_pk_bf16_f32 v93, v108, v109
	v_mov_b32_e32 v190, v217
	v_mov_b32_e32 v191, v218
	v_mov_b32_e32 v217, v219
	s_cbranch_vccz .Lmy_wt_g1_3
	global_store_dwordx4 v[112:113], v[90:93], off offset:256
.Lmy_wt_g1_3r:
	v_mad_i64_i32 v[100:101], s[0:1], v168, s29, v[156:157]
	s_nop 0
	v_pk_fma_f32 v[92:93], v[106:107], v[184:185], v[146:147] op_sel_hi:[1,0,1]
	v_pk_fma_f32 v[90:91], v[104:105], v[184:185], v[144:145] op_sel_hi:[1,0,1]
	v_pk_fma_f32 v[96:97], v[96:97], v[184:185], v[142:143] op_sel_hi:[1,0,1]
	v_pk_fma_f32 v[94:95], v[94:95], v[184:185], v[140:141] op_sel_hi:[1,0,1]
	v_pk_add_f32 v[190:191], v[190:191], v[216:217]
	v_cvt_pk_bf16_f32 v90, v90, v91
	v_cvt_pk_bf16_f32 v91, v92, v93
	v_cvt_pk_bf16_f32 v92, v94, v95
	v_cvt_pk_bf16_f32 v93, v96, v97
	v_lshl_add_u64 v[94:95], v[100:101], 1, s[24:25]
	v_add_f32_e32 v170, v190, v191
	s_cbranch_vccz .Lmy_wt_g1_4
	global_store_dwordx4 v[94:95], v[90:93], off
.Lmy_wt_g1_4r:
	v_pk_fma_f32 v[84:85], v[84:85], v[184:185], v[138:139] op_sel_hi:[1,0,1]
	v_pk_fma_f32 v[82:83], v[82:83], v[184:185], v[136:137] op_sel_hi:[1,0,1]
	v_pk_fma_f32 v[90:91], v[76:77], v[184:185], v[134:135] op_sel_hi:[1,0,1]
	v_pk_fma_f32 v[76:77], v[74:75], v[184:185], v[132:133] op_sel_hi:[1,0,1]
	ds_bpermute_b32 v161, v161, v170
	v_cvt_pk_bf16_f32 v74, v82, v83
	v_cvt_pk_bf16_f32 v75, v84, v85
	v_cvt_pk_bf16_f32 v76, v76, v77
	v_cvt_pk_bf16_f32 v77, v90, v91
	s_waitcnt lgkmcnt(2)
	v_add_f32_e32 v159, v159, v165
	s_waitcnt lgkmcnt(1)
	v_add_f32_e32 v165, v167, v169
	s_cbranch_vccz .Lmy_wt_g1_5
	global_store_dwordx4 v[94:95], v[74:77], off offset:256
.Lmy_wt_g1_5r:
	v_mad_i64_i32 v[82:83], s[0:1], v166, s29, v[156:157]
	s_nop 0
	v_pk_fma_f32 v[76:77], v[88:89], v[186:187], v[146:147] op_sel_hi:[1,0,1]
	v_pk_fma_f32 v[74:75], v[86:87], v[186:187], v[144:145] op_sel_hi:[1,0,1]
	v_pk_fma_f32 v[80:81], v[80:81], v[186:187], v[142:143] op_sel_hi:[1,0,1]
	v_pk_fma_f32 v[78:79], v[78:79], v[186:187], v[140:141] op_sel_hi:[1,0,1]
	ds_bpermute_b32 v167, v163, v165
	v_cvt_pk_bf16_f32 v74, v74, v75
	v_cvt_pk_bf16_f32 v75, v76, v77
	v_cvt_pk_bf16_f32 v76, v78, v79
	v_cvt_pk_bf16_f32 v77, v80, v81
	v_lshl_add_u64 v[78:79], v[82:83], 1, s[24:25]
	s_cbranch_vccz .Lmy_wt_g1_6
	global_store_dwordx4 v[78:79], v[74:77], off
.Lmy_wt_g1_6r:
	v_pk_fma_f32 v[72:73], v[72:73], v[186:187], v[138:139] op_sel_hi:[1,0,1]
	v_pk_fma_f32 v[70:71], v[70:71], v[186:187], v[136:137] op_sel_hi:[1,0,1]
	v_pk_fma_f32 v[74:75], v[68:69], v[186:187], v[134:135] op_sel_hi:[1,0,1]
	v_pk_fma_f32 v[68:69], v[66:67], v[186:187], v[132:133] op_sel_hi:[1,0,1]
	v_fmamk_f32 v159, v159, 0x3a800000, v1
	v_cvt_pk_bf16_f32 v66, v70, v71
	v_cvt_pk_bf16_f32 v67, v72, v73
	v_cvt_pk_bf16_f32 v68, v68, v69
	v_cvt_pk_bf16_f32 v69, v74, v75
	s_waitcnt lgkmcnt(1)
	v_add_f32_e32 v161, v170, v161
	v_rsq_f32_e32 v190, v159
	s_cbranch_vccz .Lmy_wt_g1_7
	global_store_dwordx4 v[78:79], v[66:69], off offset:256
.Lmy_wt_g1_7r:
	v_pk_fma_f32 v[64:65], v[64:65], v[188:189], v[146:147] op_sel_hi:[1,0,1]
	v_pk_fma_f32 v[62:63], v[62:63], v[188:189], v[144:145] op_sel_hi:[1,0,1]
	v_mad_i64_i32 v[66:67], s[0:1], v162, s29, v[156:157]
	v_pk_fma_f32 v[68:69], v[60:61], v[188:189], v[142:143] op_sel_hi:[1,0,1]
	v_pk_fma_f32 v[60:61], v[58:59], v[188:189], v[140:141] op_sel_hi:[1,0,1]
	ds_bpermute_b32 v163, v163, v161
	v_cvt_pk_bf16_f32 v58, v62, v63
	v_cvt_pk_bf16_f32 v59, v64, v65
	v_cvt_pk_bf16_f32 v60, v60, v61
	v_cvt_pk_bf16_f32 v61, v68, v69
	v_lshl_add_u64 v[62:63], v[66:67], 1, s[24:25]
	s_waitcnt lgkmcnt(1)
	v_add_f32_e32 v159, v165, v167
	s_cbranch_vccz .Lmy_wt_g1_8
	global_store_dwordx4 v[62:63], v[58:61], off
.Lmy_wt_g1_8r:
	v_pk_fma_f32 v[52:53], v[52:53], v[188:189], v[138:139] op_sel_hi:[1,0,1]
	v_pk_fma_f32 v[50:51], v[50:51], v[188:189], v[136:137] op_sel_hi:[1,0,1]
	v_pk_fma_f32 v[58:59], v[44:45], v[188:189], v[134:135] op_sel_hi:[1,0,1]
	v_pk_fma_f32 v[44:45], v[42:43], v[188:189], v[132:133] op_sel_hi:[1,0,1]
	v_fmamk_f32 v159, v159, 0x3a800000, v1
	v_cvt_pk_bf16_f32 v42, v50, v51
	v_cvt_pk_bf16_f32 v43, v52, v53
	v_cvt_pk_bf16_f32 v44, v44, v45
	v_cvt_pk_bf16_f32 v45, v58, v59
	v_rsq_f32_e32 v174, v159
	s_cbranch_vccz .Lmy_wt_g1_9
	global_store_dwordx4 v[62:63], v[42:45], off offset:256
.Lmy_wt_g1_9r:
	v_mad_i64_i32 v[50:51], s[0:1], v164, s29, v[156:157]
	s_nop 0
	v_pk_fma_f32 v[44:45], v[56:57], v[190:191], v[146:147] op_sel_hi:[1,0,1]
	v_pk_fma_f32 v[42:43], v[54:55], v[190:191], v[144:145] op_sel_hi:[1,0,1]
	v_pk_fma_f32 v[48:49], v[48:49], v[190:191], v[142:143] op_sel_hi:[1,0,1]
	v_pk_fma_f32 v[46:47], v[46:47], v[190:191], v[140:141] op_sel_hi:[1,0,1]
	v_cvt_pk_bf16_f32 v42, v42, v43
	v_cvt_pk_bf16_f32 v43, v44, v45
	v_cvt_pk_bf16_f32 v44, v46, v47
	v_cvt_pk_bf16_f32 v45, v48, v49
	v_lshl_add_u64 v[46:47], v[50:51], 1, s[24:25]
	s_waitcnt lgkmcnt(0)
	v_add_f32_e32 v159, v161, v163
	s_cbranch_vccz .Lmy_wt_g1_10
	global_store_dwordx4 v[46:47], v[42:45], off
.Lmy_wt_g1_10r:
	v_pk_fma_f32 v[36:37], v[36:37], v[190:191], v[138:139] op_sel_hi:[1,0,1]
	v_pk_fma_f32 v[34:35], v[34:35], v[190:191], v[136:137] op_sel_hi:[1,0,1]
	v_pk_fma_f32 v[42:43], v[28:29], v[190:191], v[134:135] op_sel_hi:[1,0,1]
	v_pk_fma_f32 v[28:29], v[26:27], v[190:191], v[132:133] op_sel_hi:[1,0,1]
	v_fmamk_f32 v159, v159, 0x3a800000, v1
	v_cvt_pk_bf16_f32 v26, v34, v35
	v_cvt_pk_bf16_f32 v27, v36, v37
	v_cvt_pk_bf16_f32 v28, v28, v29
	v_cvt_pk_bf16_f32 v29, v42, v43
	v_rsq_f32_e32 v170, v159
	s_cbranch_vccz .Lmy_wt_g1_11
	global_store_dwordx4 v[46:47], v[26:29], off offset:256
.Lmy_wt_g1_11r:
	v_mad_i64_i32 v[34:35], s[0:1], v160, s29, v[156:157]
	s_nop 0
	v_pk_fma_f32 v[28:29], v[40:41], v[174:175], v[146:147] op_sel_hi:[1,0,1]
	v_pk_fma_f32 v[26:27], v[38:39], v[174:175], v[144:145] op_sel_hi:[1,0,1]
	v_pk_fma_f32 v[32:33], v[32:33], v[174:175], v[142:143] op_sel_hi:[1,0,1]
	v_pk_fma_f32 v[30:31], v[30:31], v[174:175], v[140:141] op_sel_hi:[1,0,1]
	v_cvt_pk_bf16_f32 v26, v26, v27
	v_cvt_pk_bf16_f32 v27, v28, v29
	v_cvt_pk_bf16_f32 v28, v30, v31
	v_cvt_pk_bf16_f32 v29, v32, v33
	v_lshl_add_u64 v[30:31], v[34:35], 1, s[24:25]
	s_cbranch_vccz .Lmy_wt_g1_12
	global_store_dwordx4 v[30:31], v[26:29], off
.Lmy_wt_g1_12r:
	v_pk_fma_f32 v[20:21], v[20:21], v[174:175], v[138:139] op_sel_hi:[1,0,1]
	v_pk_fma_f32 v[18:19], v[18:19], v[174:175], v[136:137] op_sel_hi:[1,0,1]
	v_pk_fma_f32 v[26:27], v[12:13], v[174:175], v[134:135] op_sel_hi:[1,0,1]
	v_pk_fma_f32 v[12:13], v[10:11], v[174:175], v[132:133] op_sel_hi:[1,0,1]
	v_cvt_pk_bf16_f32 v10, v18, v19
	v_cvt_pk_bf16_f32 v11, v20, v21
	v_cvt_pk_bf16_f32 v12, v12, v13
	v_cvt_pk_bf16_f32 v13, v26, v27
	s_cbranch_vccz .Lmy_wt_g1_13
	global_store_dwordx4 v[30:31], v[10:13], off offset:256
.Lmy_wt_g1_13r:
	v_mad_i64_i32 v[18:19], s[0:1], v158, s29, v[156:157]
	s_nop 0
	v_pk_fma_f32 v[12:13], v[24:25], v[170:171], v[146:147] op_sel_hi:[1,0,1]
	v_pk_fma_f32 v[10:11], v[22:23], v[170:171], v[144:145] op_sel_hi:[1,0,1]
	v_pk_fma_f32 v[16:17], v[16:17], v[170:171], v[142:143] op_sel_hi:[1,0,1]
	v_pk_fma_f32 v[14:15], v[14:15], v[170:171], v[140:141] op_sel_hi:[1,0,1]
	v_cvt_pk_bf16_f32 v10, v10, v11
	v_cvt_pk_bf16_f32 v11, v12, v13
	v_cvt_pk_bf16_f32 v12, v14, v15
	v_cvt_pk_bf16_f32 v13, v16, v17
	v_lshl_add_u64 v[14:15], v[18:19], 1, s[24:25]
	s_cbranch_vccz .Lmy_wt_g1_14
	global_store_dwordx4 v[14:15], v[10:13], off
.Lmy_wt_g1_14r:
	v_pk_fma_f32 v[8:9], v[8:9], v[170:171], v[138:139] op_sel_hi:[1,0,1]
	v_pk_fma_f32 v[6:7], v[6:7], v[170:171], v[136:137] op_sel_hi:[1,0,1]
	v_pk_fma_f32 v[10:11], v[4:5], v[170:171], v[134:135] op_sel_hi:[1,0,1]
	v_pk_fma_f32 v[4:5], v[2:3], v[170:171], v[132:133] op_sel_hi:[1,0,1]
	v_cvt_pk_bf16_f32 v2, v6, v7
	v_cvt_pk_bf16_f32 v3, v8, v9
	v_cvt_pk_bf16_f32 v4, v4, v5
	v_cvt_pk_bf16_f32 v5, v10, v11
	s_mov_b64 s[0:1], -1
	s_cbranch_vccz .Lmy_wt_g1_15
	global_store_dwordx4 v[14:15], v[2:5], off offset:256
.Lmy_wt_g1_15r:
	s_cbranch_vccnz .LBB0_316
	s_andn2_b64 vcc, exec, s[20:21]
	s_cbranch_vccnz .LBB0_315
	s_barrier
	s_branch .LBB0_315
.Lmy_wt_g1_0:
	global_store_dwordx4 v[128:129], v[124:127], off sc1
	s_branch .Lmy_wt_g1_0r
.Lmy_wt_g1_1:
	global_store_dwordx4 v[128:129], v[108:111], off offset:256 sc1
	s_branch .Lmy_wt_g1_1r
.Lmy_wt_g1_2:
	global_store_dwordx4 v[112:113], v[108:111], off sc1
	s_branch .Lmy_wt_g1_2r
.Lmy_wt_g1_3:
	global_store_dwordx4 v[112:113], v[90:93], off offset:256 sc1
	s_branch .Lmy_wt_g1_3r
.Lmy_wt_g1_4:
	global_store_dwordx4 v[94:95], v[90:93], off sc1
	s_branch .Lmy_wt_g1_4r
.Lmy_wt_g1_5:
	global_store_dwordx4 v[94:95], v[74:77], off offset:256 sc1
	s_branch .Lmy_wt_g1_5r
.Lmy_wt_g1_6:
	global_store_dwordx4 v[78:79], v[74:77], off sc1
	s_branch .Lmy_wt_g1_6r
.Lmy_wt_g1_7:
	global_store_dwordx4 v[78:79], v[66:69], off offset:256 sc1
	s_branch .Lmy_wt_g1_7r
.Lmy_wt_g1_8:
	global_store_dwordx4 v[62:63], v[58:61], off sc1
	s_branch .Lmy_wt_g1_8r
.Lmy_wt_g1_9:
	global_store_dwordx4 v[62:63], v[42:45], off offset:256 sc1
	s_branch .Lmy_wt_g1_9r
.Lmy_wt_g1_10:
	global_store_dwordx4 v[46:47], v[42:45], off sc1
	s_branch .Lmy_wt_g1_10r
.Lmy_wt_g1_11:
	global_store_dwordx4 v[46:47], v[26:29], off offset:256 sc1
	s_branch .Lmy_wt_g1_11r
.Lmy_wt_g1_12:
	global_store_dwordx4 v[30:31], v[26:29], off sc1
	s_branch .Lmy_wt_g1_12r
.Lmy_wt_g1_13:
	global_store_dwordx4 v[30:31], v[10:13], off offset:256 sc1
	s_branch .Lmy_wt_g1_13r
.Lmy_wt_g1_14:
	global_store_dwordx4 v[14:15], v[10:13], off sc1
	s_branch .Lmy_wt_g1_14r
.Lmy_wt_g1_15:
	global_store_dwordx4 v[14:15], v[2:5], off offset:256 sc1
	s_branch .Lmy_wt_g1_15r

.LBB0_867:
	s_lshl_b32 s6, s94, 8
	s_add_i32 s5, s6, 0xffffc000
	s_lshr_b32 s5, s5, 12
	s_ashr_i32 s4, s94, 5
	s_add_i32 s5, s5, 2
	s_cmp_lt_i32 s94, 64
	s_cselect_b32 s4, s4, s5
	s_ashr_i32 s5, s4, 31
	s_lshl_b64 s[4:5], s[4:5], 14
	v_lshl_or_b32 v164, s18, 8, v240
	s_add_u32 s44, s79, s4
	s_addc_u32 s45, s88, s5
	v_ashrrev_i32_e32 v165, 31, v164
	v_add_u32_e32 v222, s6, v238
	s_add_u32 s4, s89, s4
	v_lshlrev_b64 v[210:211], 1, v[164:165]
	v_ashrrev_i32_e32 v223, 31, v222
	v_lshlrev_b64 v[90:91], 2, v[164:165]
	s_addc_u32 s5, s90, s5
	v_lshl_add_u64 v[164:165], s[82:83], 0, v[210:211]
	v_lshlrev_b64 v[226:227], 11, v[222:223]
	v_lshl_add_u64 v[92:93], s[44:45], 0, v[90:91]
	v_lshl_add_u64 v[94:95], s[4:5], 0, v[90:91]
	v_lshl_add_u64 v[166:167], v[164:165], 0, v[226:227]
	global_load_dwordx4 v[120:123], v[92:93], off offset:16
	global_load_dwordx4 v[128:131], v[92:93], off
	global_load_dwordx4 v[108:111], v[94:95], off offset:16
	global_load_dwordx4 v[112:115], v[94:95], off
	global_load_dwordx4 v[100:103], v[92:93], off offset:528
	global_load_dwordx4 v[104:107], v[92:93], off offset:512
	s_nop 0
	global_load_dwordx4 v[90:93], v[94:95], off offset:528
	s_nop 0
	global_load_dwordx4 v[94:97], v[94:95], off offset:512
	s_nop 0
	global_load_dwordx4 v[192:195], v[166:167], off
	global_load_dwordx4 v[188:191], v[166:167], off offset:256
	v_or_b32_e32 v220, 16, v222
	v_ashrrev_i32_e32 v221, 31, v220
	v_or_b32_e32 v216, 32, v222
	v_or_b32_e32 v212, 48, v222
	v_lshlrev_b64 v[224:225], 11, v[220:221]
	v_ashrrev_i32_e32 v217, 31, v216
	v_ashrrev_i32_e32 v213, 31, v212
	v_lshl_add_u64 v[166:167], v[164:165], 0, v[224:225]
	v_lshlrev_b64 v[218:219], 11, v[216:217]
	v_lshlrev_b64 v[214:215], 11, v[212:213]
	global_load_dwordx4 v[184:187], v[166:167], off
	global_load_dwordx4 v[180:183], v[166:167], off offset:256
	v_lshl_add_u64 v[166:167], v[164:165], 0, v[218:219]
	v_lshl_add_u64 v[164:165], v[164:165], 0, v[214:215]
	global_load_dwordx4 v[176:179], v[166:167], off
	global_load_dwordx4 v[172:175], v[166:167], off offset:256
	global_load_dwordx4 v[168:171], v[164:165], off
	s_nop 0
	global_load_dwordx4 v[164:167], v[164:165], off offset:256
	v_and_b32_e32 v201, 64, v229
	v_xor_b32_e32 v200, 16, v229
	v_add_u32_e32 v201, 64, v201
	v_cmp_lt_i32_e32 vcc, v200, v201
	s_lshl_b32 s68, s18, 2
	s_ashr_i32 s69, s68, 31
	v_cndmask_b32_e32 v200, v229, v200, vcc
	v_lshlrev_b32_e32 v242, 2, v200
	v_xor_b32_e32 v200, 32, v229
	v_cmp_lt_i32_e32 vcc, v200, v201
	s_waitcnt vmcnt(0)
	v_and_b32_e32 v201, 0xffff0000, v192
	v_cndmask_b32_e32 v200, v229, v200, vcc
	s_andn2_b64 vcc, exec, s[40:41]
	v_lshlrev_b32_e32 v243, 2, v200
	v_lshlrev_b32_e32 v200, 16, v192
	v_lshlrev_b32_e32 v192, 16, v193
	v_and_b32_e32 v193, 0xffff0000, v193
	v_lshlrev_b32_e32 v202, 16, v194
	v_and_b32_e32 v203, 0xffff0000, v194
	v_lshlrev_b32_e32 v194, 16, v195
	v_and_b32_e32 v195, 0xffff0000, v195
	v_pk_fma_f32 v[162:163], v[162:163], v[130:131], v[192:193]
	v_pk_fma_f32 v[192:193], v[158:159], v[122:123], v[194:195]
	v_pk_fma_f32 v[194:195], v[156:157], v[120:121], v[202:203]
	v_pk_fma_f32 v[160:161], v[160:161], v[128:129], v[200:201]
	v_pk_mul_f32 v[156:157], v[194:195], v[194:195]
	v_pk_mul_f32 v[158:159], v[192:193], v[192:193]
	v_pk_fma_f32 v[156:157], v[160:161], v[160:161], v[156:157]
	v_pk_fma_f32 v[158:159], v[162:163], v[162:163], v[158:159]
	v_add_f32_e32 v156, v156, v157
	v_add_f32_e32 v157, v158, v159
	v_lshl_add_u64 v[200:201], s[82:83], 0, v[226:227]
	v_add_f32_e32 v202, v156, v157
	v_cvt_pk_bf16_f32 v156, v160, v161
	v_cvt_pk_bf16_f32 v157, v162, v163
	v_cvt_pk_bf16_f32 v158, v194, v195
	v_cvt_pk_bf16_f32 v159, v192, v193
	v_lshl_add_u64 v[200:201], v[200:201], 0, v[210:211]
	s_cbranch_vccnz .Lmy_wt_g2a_0
	global_store_dwordx4 v[200:201], v[156:159], off
.Lmy_wt_g2a_0r:
	s_nop 1
	v_pk_mul_f32 v[158:159], v[114:115], v[162:163]
	v_pk_mul_f32 v[156:157], v[112:113], v[160:161]
	v_pk_mul_f32 v[160:161], v[110:111], v[192:193]
	v_pk_mul_f32 v[162:163], v[108:109], v[194:195]
	v_cvt_pk_bf16_f32 v156, v156, v157
	v_cvt_pk_bf16_f32 v157, v158, v159
	v_cvt_pk_bf16_f32 v159, v160, v161
	v_lshl_add_u64 v[160:161], s[22:23], 0, v[226:227]
	v_cvt_pk_bf16_f32 v158, v162, v163
	v_lshl_add_u64 v[160:161], v[160:161], 0, v[210:211]
	s_cbranch_vccnz .Lmy_wt_g2a_1
	global_store_dwordx4 v[160:161], v[156:159], off
.Lmy_wt_g2a_1r:
	v_lshlrev_b32_e32 v162, 16, v190
	v_and_b32_e32 v163, 0xffff0000, v190
	v_lshlrev_b32_e32 v156, 16, v188
	v_and_b32_e32 v157, 0xffff0000, v188
	v_lshlrev_b32_e32 v158, 16, v189
	v_and_b32_e32 v159, 0xffff0000, v189
	v_lshlrev_b32_e32 v188, 16, v191
	v_and_b32_e32 v189, 0xffff0000, v191
	v_pk_fma_f32 v[152:153], v[152:153], v[104:105], v[156:157]
	v_pk_fma_f32 v[154:155], v[154:155], v[106:107], v[158:159]
	v_pk_fma_f32 v[156:157], v[150:151], v[102:103], v[188:189]
	v_pk_fma_f32 v[158:159], v[148:149], v[100:101], v[162:163]
	v_pk_mul_f32 v[150:151], v[156:157], v[156:157]
	v_pk_mul_f32 v[148:149], v[158:159], v[158:159]
	v_pk_fma_f32 v[150:151], v[154:155], v[154:155], v[150:151]
	v_pk_fma_f32 v[148:149], v[152:153], v[152:153], v[148:149]
	s_nop 0
	v_add_f32_e32 v148, v148, v149
	v_add_f32_e32 v149, v150, v151
	v_add_f32_e32 v148, v148, v149
	v_add_f32_e32 v162, v202, v148
	v_cvt_pk_bf16_f32 v148, v152, v153
	v_cvt_pk_bf16_f32 v149, v154, v155
	v_cvt_pk_bf16_f32 v150, v158, v159
	v_cvt_pk_bf16_f32 v151, v156, v157
	s_cbranch_vccnz .Lmy_wt_g2a_2
	global_store_dwordx4 v[200:201], v[148:151], off offset:256
.Lmy_wt_g2a_2r:
	s_nop 1
	v_pk_mul_f32 v[150:151], v[96:97], v[154:155]
	v_pk_mul_f32 v[148:149], v[94:95], v[152:153]
	v_pk_mul_f32 v[152:153], v[92:93], v[156:157]
	v_pk_mul_f32 v[154:155], v[90:91], v[158:159]
	v_cvt_pk_bf16_f32 v148, v148, v149
	v_cvt_pk_bf16_f32 v149, v150, v151
	v_cvt_pk_bf16_f32 v150, v154, v155
	v_cvt_pk_bf16_f32 v151, v152, v153
	s_cbranch_vccnz .Lmy_wt_g2a_3
	global_store_dwordx4 v[160:161], v[148:151], off offset:256
.Lmy_wt_g2a_3r:
	ds_bpermute_b32 v148, v242, v162
	s_waitcnt lgkmcnt(0)
	v_add_f32_e32 v148, v162, v148
	ds_bpermute_b32 v149, v243, v148
	s_and_saveexec_b64 s[70:71], s[38:39]
	s_mov_b32 s96, s3
	s_movk_i32 s97, 0xff
	s_cbranch_execz .LBB0_869
	v_lshlrev_b64 v[150:151], 6, v[222:223]
	v_lshl_add_u64 v[150:151], s[58:59], 0, v[150:151]
	v_lshl_add_u64 v[150:151], s[68:69], 2, v[150:151]
	s_lshl_b32 s48, s92, 2
	v_lshl_add_u64 v[150:151], v[150:151], 0, s[48:49]
	s_waitcnt lgkmcnt(0)
	v_add_f32_e32 v148, v148, v149
	global_store_dword v[150:151], v148, off
.LBB0_869:
	s_or_b64 exec, exec, s[70:71]
	v_add_u32_e32 v156, 0x80, v222
	v_ashrrev_i32_e32 v157, 31, v156
	v_lshlrev_b64 v[160:161], 11, v[156:157]
	s_waitcnt lgkmcnt(0)
	v_lshl_add_u64 v[148:149], s[82:83], 0, v[160:161]
	v_lshl_add_u64 v[158:159], v[148:149], 0, v[210:211]
	global_load_dwordx4 v[152:155], v[158:159], off
	global_load_dwordx4 v[148:151], v[158:159], off offset:256
	v_lshlrev_b32_e32 v162, 16, v184
	v_and_b32_e32 v163, 0xffff0000, v184
	v_lshlrev_b32_e32 v184, 16, v185
	v_and_b32_e32 v185, 0xffff0000, v185
	v_lshlrev_b32_e32 v188, 16, v186
	v_and_b32_e32 v189, 0xffff0000, v186
	v_lshlrev_b32_e32 v186, 16, v187
	v_and_b32_e32 v187, 0xffff0000, v187
	v_pk_fma_f32 v[144:145], v[144:145], v[128:129], v[162:163]
	v_pk_fma_f32 v[146:147], v[146:147], v[130:131], v[184:185]
	v_pk_fma_f32 v[162:163], v[142:143], v[122:123], v[186:187]
	v_pk_fma_f32 v[184:185], v[140:141], v[120:121], v[188:189]
	v_pk_mul_f32 v[142:143], v[162:163], v[162:163]
	v_pk_mul_f32 v[140:141], v[184:185], v[184:185]
	v_pk_fma_f32 v[142:143], v[146:147], v[146:147], v[142:143]
	v_pk_fma_f32 v[140:141], v[144:145], v[144:145], v[140:141]
	v_lshl_add_u64 v[186:187], s[82:83], 0, v[224:225]
	v_add_f32_e32 v140, v140, v141
	v_add_f32_e32 v141, v142, v143
	v_add_f32_e32 v188, v140, v141
	v_cvt_pk_bf16_f32 v140, v144, v145
	v_cvt_pk_bf16_f32 v141, v146, v147
	v_cvt_pk_bf16_f32 v142, v184, v185
	v_cvt_pk_bf16_f32 v143, v162, v163
	v_lshl_add_u64 v[186:187], v[186:187], 0, v[210:211]
	s_cbranch_vccnz .Lmy_wt_g2a_4
	global_store_dwordx4 v[186:187], v[140:143], off
.Lmy_wt_g2a_4r:
	s_nop 1
	v_pk_mul_f32 v[142:143], v[114:115], v[146:147]
	v_pk_mul_f32 v[140:141], v[112:113], v[144:145]
	v_pk_mul_f32 v[144:145], v[110:111], v[162:163]
	v_pk_mul_f32 v[146:147], v[108:109], v[184:185]
	v_cvt_pk_bf16_f32 v140, v140, v141
	v_cvt_pk_bf16_f32 v141, v142, v143
	v_cvt_pk_bf16_f32 v143, v144, v145
	v_lshl_add_u64 v[144:145], s[22:23], 0, v[224:225]
	v_cvt_pk_bf16_f32 v142, v146, v147
	v_lshl_add_u64 v[144:145], v[144:145], 0, v[210:211]
	s_cbranch_vccnz .Lmy_wt_g2a_5
	global_store_dwordx4 v[144:145], v[140:143], off
.Lmy_wt_g2a_5r:
	v_lshlrev_b32_e32 v146, 16, v182
	v_and_b32_e32 v147, 0xffff0000, v182
	v_lshlrev_b32_e32 v140, 16, v180
	v_and_b32_e32 v141, 0xffff0000, v180
	v_lshlrev_b32_e32 v142, 16, v181
	v_and_b32_e32 v143, 0xffff0000, v181
	v_lshlrev_b32_e32 v162, 16, v183
	v_and_b32_e32 v163, 0xffff0000, v183
	v_pk_fma_f32 v[136:137], v[136:137], v[104:105], v[140:141]
	v_pk_fma_f32 v[138:139], v[138:139], v[106:107], v[142:143]
	v_pk_fma_f32 v[140:141], v[134:135], v[102:103], v[162:163]
	v_pk_fma_f32 v[142:143], v[132:133], v[100:101], v[146:147]
	v_pk_mul_f32 v[134:135], v[140:141], v[140:141]
	v_pk_mul_f32 v[132:133], v[142:143], v[142:143]
	v_pk_fma_f32 v[134:135], v[138:139], v[138:139], v[134:135]
	v_pk_fma_f32 v[132:133], v[136:137], v[136:137], v[132:133]
	s_nop 0
	v_add_f32_e32 v132, v132, v133
	v_add_f32_e32 v133, v134, v135
	v_add_f32_e32 v132, v132, v133
	v_add_f32_e32 v146, v188, v132
	v_cvt_pk_bf16_f32 v132, v136, v137
	v_cvt_pk_bf16_f32 v133, v138, v139
	v_cvt_pk_bf16_f32 v134, v142, v143
	v_cvt_pk_bf16_f32 v135, v140, v141
	s_cbranch_vccnz .Lmy_wt_g2a_6
	global_store_dwordx4 v[186:187], v[132:135], off offset:256
.Lmy_wt_g2a_6r:
	ds_bpermute_b32 v135, v242, v146
	v_pk_mul_f32 v[138:139], v[96:97], v[138:139]
	v_pk_mul_f32 v[132:133], v[94:95], v[136:137]
	v_pk_mul_f32 v[140:141], v[92:93], v[140:141]
	v_cvt_pk_bf16_f32 v134, v132, v133
	s_waitcnt lgkmcnt(0)
	v_add_f32_e32 v132, v146, v135
	ds_bpermute_b32 v133, v243, v132
	v_pk_mul_f32 v[136:137], v[90:91], v[142:143]
	v_cvt_pk_bf16_f32 v135, v138, v139
	v_cvt_pk_bf16_f32 v136, v136, v137
	v_cvt_pk_bf16_f32 v137, v140, v141
	s_cbranch_vccnz .Lmy_wt_g2a_7
	global_store_dwordx4 v[144:145], v[134:137], off offset:256
.Lmy_wt_g2a_7r:
	s_and_saveexec_b64 s[70:71], s[38:39]
	s_cbranch_execz .LBB0_871
	v_lshlrev_b64 v[134:135], 6, v[220:221]
	v_lshl_add_u64 v[134:135], s[58:59], 0, v[134:135]
	v_lshl_add_u64 v[134:135], s[68:69], 2, v[134:135]
	s_lshl_b32 s48, s92, 2
	v_lshl_add_u64 v[134:135], v[134:135], 0, s[48:49]
	s_waitcnt lgkmcnt(0)
	v_add_f32_e32 v132, v132, v133
	global_store_dword v[134:135], v132, off
.LBB0_871:
	s_or_b64 exec, exec, s[70:71]
	v_or_b32_e32 v140, 16, v156
	v_ashrrev_i32_e32 v141, 31, v140
	v_lshlrev_b64 v[144:145], 11, v[140:141]
	s_waitcnt lgkmcnt(0)
	v_lshl_add_u64 v[132:133], s[82:83], 0, v[144:145]
	v_lshl_add_u64 v[142:143], v[132:133], 0, v[210:211]
	global_load_dwordx4 v[136:139], v[142:143], off
	global_load_dwordx4 v[132:135], v[142:143], off offset:256
	v_lshlrev_b32_e32 v146, 16, v176
	v_and_b32_e32 v147, 0xffff0000, v176
	v_lshlrev_b32_e32 v162, 16, v177
	v_and_b32_e32 v163, 0xffff0000, v177
	v_lshlrev_b32_e32 v176, 16, v178
	v_and_b32_e32 v177, 0xffff0000, v178
	v_lshlrev_b32_e32 v178, 16, v179
	v_and_b32_e32 v179, 0xffff0000, v179
	v_pk_fma_f32 v[124:125], v[124:125], v[128:129], v[146:147]
	v_pk_fma_f32 v[126:127], v[126:127], v[130:131], v[162:163]
	v_pk_fma_f32 v[146:147], v[118:119], v[122:123], v[178:179]
	v_pk_fma_f32 v[162:163], v[116:117], v[120:121], v[176:177]
	v_pk_mul_f32 v[118:119], v[146:147], v[146:147]
	v_pk_mul_f32 v[116:117], v[162:163], v[162:163]
	v_pk_fma_f32 v[118:119], v[126:127], v[126:127], v[118:119]
	v_pk_fma_f32 v[116:117], v[124:125], v[124:125], v[116:117]
	v_lshl_add_u64 v[176:177], s[82:83], 0, v[218:219]
	v_add_f32_e32 v116, v116, v117
	v_add_f32_e32 v117, v118, v119
	v_add_f32_e32 v178, v116, v117
	v_cvt_pk_bf16_f32 v116, v124, v125
	v_cvt_pk_bf16_f32 v117, v126, v127
	v_cvt_pk_bf16_f32 v118, v162, v163
	v_cvt_pk_bf16_f32 v119, v146, v147
	v_lshl_add_u64 v[176:177], v[176:177], 0, v[210:211]
	s_cbranch_vccnz .Lmy_wt_g2a_8
	global_store_dwordx4 v[176:177], v[116:119], off
.Lmy_wt_g2a_8r:
	s_nop 1
	v_pk_mul_f32 v[118:119], v[114:115], v[126:127]
	v_pk_mul_f32 v[116:117], v[112:113], v[124:125]
	v_pk_mul_f32 v[124:125], v[110:111], v[146:147]
	v_pk_mul_f32 v[126:127], v[108:109], v[162:163]
	v_cvt_pk_bf16_f32 v116, v116, v117
	v_cvt_pk_bf16_f32 v117, v118, v119
	v_cvt_pk_bf16_f32 v119, v124, v125
	v_lshl_add_u64 v[124:125], s[22:23], 0, v[218:219]
	v_cvt_pk_bf16_f32 v118, v126, v127
	v_lshl_add_u64 v[124:125], v[124:125], 0, v[210:211]
	s_cbranch_vccnz .Lmy_wt_g2a_9
	global_store_dwordx4 v[124:125], v[116:119], off
.Lmy_wt_g2a_9r:
	v_lshlrev_b32_e32 v126, 16, v174
	v_and_b32_e32 v127, 0xffff0000, v174
	v_lshlrev_b32_e32 v116, 16, v172
	v_and_b32_e32 v117, 0xffff0000, v172
	v_lshlrev_b32_e32 v118, 16, v173
	v_and_b32_e32 v119, 0xffff0000, v173
	v_lshlrev_b32_e32 v146, 16, v175
	v_and_b32_e32 v147, 0xffff0000, v175
	v_pk_fma_f32 v[86:87], v[86:87], v[104:105], v[116:117]
	v_pk_fma_f32 v[88:89], v[88:89], v[106:107], v[118:119]
	v_pk_fma_f32 v[116:117], v[84:85], v[102:103], v[146:147]
	v_pk_fma_f32 v[118:119], v[82:83], v[100:101], v[126:127]
	v_pk_mul_f32 v[84:85], v[116:117], v[116:117]
	v_pk_mul_f32 v[82:83], v[118:119], v[118:119]
	v_pk_fma_f32 v[84:85], v[88:89], v[88:89], v[84:85]
	v_pk_fma_f32 v[82:83], v[86:87], v[86:87], v[82:83]
	s_nop 0
	v_add_f32_e32 v82, v82, v83
	v_add_f32_e32 v83, v84, v85
	v_add_f32_e32 v82, v82, v83
	v_add_f32_e32 v126, v178, v82
	v_cvt_pk_bf16_f32 v82, v86, v87
	v_cvt_pk_bf16_f32 v83, v88, v89
	v_cvt_pk_bf16_f32 v84, v118, v119
	v_cvt_pk_bf16_f32 v85, v116, v117
	s_cbranch_vccnz .Lmy_wt_g2a_10
	global_store_dwordx4 v[176:177], v[82:85], off offset:256
.Lmy_wt_g2a_10r:
	ds_bpermute_b32 v85, v242, v126
	v_pk_mul_f32 v[88:89], v[96:97], v[88:89]
	v_pk_mul_f32 v[82:83], v[94:95], v[86:87]
	v_pk_mul_f32 v[116:117], v[92:93], v[116:117]
	v_cvt_pk_bf16_f32 v84, v82, v83
	s_waitcnt lgkmcnt(0)
	v_add_f32_e32 v82, v126, v85
	ds_bpermute_b32 v83, v243, v82
	v_pk_mul_f32 v[86:87], v[90:91], v[118:119]
	v_cvt_pk_bf16_f32 v85, v88, v89
	v_cvt_pk_bf16_f32 v86, v86, v87
	v_cvt_pk_bf16_f32 v87, v116, v117
	s_cbranch_vccnz .Lmy_wt_g2a_11
	global_store_dwordx4 v[124:125], v[84:87], off offset:256
.Lmy_wt_g2a_11r:
	s_and_saveexec_b64 s[70:71], s[38:39]
	v_readlane_b32 s8, v255, 31
	v_readlane_b32 s74, v255, 33
	v_readlane_b32 s9, v255, 32
	v_readlane_b32 s75, v255, 34
	s_cbranch_execz .LBB0_873
	v_lshlrev_b64 v[84:85], 6, v[216:217]
	v_lshl_add_u64 v[84:85], s[58:59], 0, v[84:85]
	v_lshl_add_u64 v[84:85], s[68:69], 2, v[84:85]
	s_lshl_b32 s48, s92, 2
	v_lshl_add_u64 v[84:85], v[84:85], 0, s[48:49]
	s_waitcnt lgkmcnt(0)
	v_add_f32_e32 v82, v82, v83
	global_store_dword v[84:85], v82, off
.LBB0_873:
	s_or_b64 exec, exec, s[70:71]
	v_or_b32_e32 v116, 32, v156
	v_ashrrev_i32_e32 v117, 31, v116
	v_lshlrev_b64 v[124:125], 11, v[116:117]
	s_waitcnt lgkmcnt(0)
	v_lshl_add_u64 v[82:83], s[82:83], 0, v[124:125]
	v_lshl_add_u64 v[118:119], v[82:83], 0, v[210:211]
	global_load_dwordx4 v[86:89], v[118:119], off
	global_load_dwordx4 v[82:85], v[118:119], off offset:256
	v_lshlrev_b32_e32 v126, 16, v168
	v_and_b32_e32 v127, 0xffff0000, v168
	v_lshlrev_b32_e32 v146, 16, v169
	v_and_b32_e32 v147, 0xffff0000, v169
	v_lshlrev_b32_e32 v162, 16, v170
	v_and_b32_e32 v163, 0xffff0000, v170
	v_lshlrev_b32_e32 v168, 16, v171
	v_and_b32_e32 v169, 0xffff0000, v171
	v_pk_fma_f32 v[78:79], v[78:79], v[128:129], v[126:127]
	v_pk_fma_f32 v[80:81], v[80:81], v[130:131], v[146:147]
	v_pk_fma_f32 v[126:127], v[76:77], v[122:123], v[168:169]
	v_pk_fma_f32 v[146:147], v[74:75], v[120:121], v[162:163]
	v_pk_mul_f32 v[76:77], v[126:127], v[126:127]
	v_pk_mul_f32 v[74:75], v[146:147], v[146:147]
	v_pk_fma_f32 v[76:77], v[80:81], v[80:81], v[76:77]
	v_pk_fma_f32 v[74:75], v[78:79], v[78:79], v[74:75]
	v_lshl_add_u64 v[162:163], s[82:83], 0, v[214:215]
	v_add_f32_e32 v74, v74, v75
	v_add_f32_e32 v75, v76, v77
	v_add_f32_e32 v168, v74, v75
	v_cvt_pk_bf16_f32 v74, v78, v79
	v_cvt_pk_bf16_f32 v75, v80, v81
	v_cvt_pk_bf16_f32 v76, v146, v147
	v_cvt_pk_bf16_f32 v77, v126, v127
	v_lshl_add_u64 v[162:163], v[162:163], 0, v[210:211]
	s_cbranch_vccnz .Lmy_wt_g2a_12
	global_store_dwordx4 v[162:163], v[74:77], off
.Lmy_wt_g2a_12r:
	s_nop 1
	v_pk_mul_f32 v[76:77], v[114:115], v[80:81]
	v_pk_mul_f32 v[74:75], v[112:113], v[78:79]
	v_pk_mul_f32 v[78:79], v[110:111], v[126:127]
	v_pk_mul_f32 v[80:81], v[108:109], v[146:147]
	v_cvt_pk_bf16_f32 v74, v74, v75
	v_cvt_pk_bf16_f32 v75, v76, v77
	v_cvt_pk_bf16_f32 v77, v78, v79
	v_lshl_add_u64 v[78:79], s[22:23], 0, v[214:215]
	v_cvt_pk_bf16_f32 v76, v80, v81
	v_lshl_add_u64 v[78:79], v[78:79], 0, v[210:211]
	s_cbranch_vccnz .Lmy_wt_g2a_13
	global_store_dwordx4 v[78:79], v[74:77], off
.Lmy_wt_g2a_13r:
	v_lshlrev_b32_e32 v80, 16, v166
	v_and_b32_e32 v81, 0xffff0000, v166
	v_lshlrev_b32_e32 v74, 16, v164
	v_and_b32_e32 v75, 0xffff0000, v164
	v_lshlrev_b32_e32 v76, 16, v165
	v_and_b32_e32 v77, 0xffff0000, v165
	v_lshlrev_b32_e32 v126, 16, v167
	v_and_b32_e32 v127, 0xffff0000, v167
	v_pk_fma_f32 v[70:71], v[70:71], v[104:105], v[74:75]
	v_pk_fma_f32 v[72:73], v[72:73], v[106:107], v[76:77]
	v_pk_fma_f32 v[74:75], v[68:69], v[102:103], v[126:127]
	v_pk_fma_f32 v[76:77], v[66:67], v[100:101], v[80:81]
	v_pk_mul_f32 v[68:69], v[74:75], v[74:75]
	v_pk_mul_f32 v[66:67], v[76:77], v[76:77]
	v_pk_fma_f32 v[68:69], v[72:73], v[72:73], v[68:69]
	v_pk_fma_f32 v[66:67], v[70:71], v[70:71], v[66:67]
	s_nop 0
	v_add_f32_e32 v66, v66, v67
	v_add_f32_e32 v67, v68, v69
	v_add_f32_e32 v66, v66, v67
	v_add_f32_e32 v80, v168, v66
	v_cvt_pk_bf16_f32 v66, v70, v71
	v_cvt_pk_bf16_f32 v67, v72, v73
	v_cvt_pk_bf16_f32 v68, v76, v77
	v_cvt_pk_bf16_f32 v69, v74, v75
	s_cbranch_vccnz .Lmy_wt_g2a_14
	global_store_dwordx4 v[162:163], v[66:69], off offset:256
.Lmy_wt_g2a_14r:
	ds_bpermute_b32 v69, v242, v80
	v_pk_mul_f32 v[72:73], v[96:97], v[72:73]
	v_pk_mul_f32 v[66:67], v[94:95], v[70:71]
	v_pk_mul_f32 v[74:75], v[92:93], v[74:75]
	v_cvt_pk_bf16_f32 v68, v66, v67
	s_waitcnt lgkmcnt(0)
	v_add_f32_e32 v66, v80, v69
	ds_bpermute_b32 v67, v243, v66
	v_pk_mul_f32 v[70:71], v[90:91], v[76:77]
	v_cvt_pk_bf16_f32 v69, v72, v73
	v_cvt_pk_bf16_f32 v70, v70, v71
	v_cvt_pk_bf16_f32 v71, v74, v75
	s_cbranch_vccnz .Lmy_wt_g2a_15
	global_store_dwordx4 v[78:79], v[68:71], off offset:256
.Lmy_wt_g2a_15r:
	s_and_saveexec_b64 s[70:71], s[38:39]
	s_cbranch_execz .LBB0_875
	v_lshlrev_b64 v[68:69], 6, v[212:213]
	v_lshl_add_u64 v[68:69], s[58:59], 0, v[68:69]
	v_lshl_add_u64 v[68:69], s[68:69], 2, v[68:69]
	s_lshl_b32 s48, s92, 2
	v_lshl_add_u64 v[68:69], v[68:69], 0, s[48:49]
	s_waitcnt lgkmcnt(0)
	v_add_f32_e32 v66, v66, v67
	global_store_dword v[68:69], v66, off
.LBB0_875:
	s_or_b64 exec, exec, s[70:71]
	v_or_b32_e32 v74, 48, v156
	v_ashrrev_i32_e32 v75, 31, v74
	v_lshlrev_b64 v[78:79], 11, v[74:75]
	s_waitcnt lgkmcnt(0)
	v_lshl_add_u64 v[66:67], s[82:83], 0, v[78:79]
	v_lshl_add_u64 v[76:77], v[66:67], 0, v[210:211]
	global_load_dwordx4 v[70:73], v[76:77], off
	global_load_dwordx4 v[66:69], v[76:77], off offset:256
	s_waitcnt vmcnt(19)
	v_lshlrev_b32_e32 v80, 16, v152
	v_and_b32_e32 v81, 0xffff0000, v152
	v_lshlrev_b32_e32 v126, 16, v153
	v_and_b32_e32 v127, 0xffff0000, v153
	v_lshlrev_b32_e32 v146, 16, v154
	v_and_b32_e32 v147, 0xffff0000, v154
	v_lshlrev_b32_e32 v152, 16, v155
	v_and_b32_e32 v153, 0xffff0000, v155
	v_pk_fma_f32 v[62:63], v[62:63], v[128:129], v[80:81]
	v_pk_fma_f32 v[64:65], v[64:65], v[130:131], v[126:127]
	v_pk_fma_f32 v[80:81], v[60:61], v[122:123], v[152:153]
	v_pk_fma_f32 v[126:127], v[58:59], v[120:121], v[146:147]
	v_pk_mul_f32 v[60:61], v[80:81], v[80:81]
	v_pk_mul_f32 v[58:59], v[126:127], v[126:127]
	v_pk_fma_f32 v[60:61], v[64:65], v[64:65], v[60:61]
	v_pk_fma_f32 v[58:59], v[62:63], v[62:63], v[58:59]
	s_nop 0
	v_add_f32_e32 v58, v58, v59
	v_add_f32_e32 v59, v60, v61
	v_add_f32_e32 v146, v58, v59
	v_cvt_pk_bf16_f32 v58, v62, v63
	v_cvt_pk_bf16_f32 v59, v64, v65
	v_cvt_pk_bf16_f32 v60, v126, v127
	v_cvt_pk_bf16_f32 v61, v80, v81
	s_cbranch_vccnz .Lmy_wt_g2a_16
	global_store_dwordx4 v[158:159], v[58:61], off
.Lmy_wt_g2a_16r:
	s_nop 1
	v_pk_mul_f32 v[60:61], v[114:115], v[64:65]
	v_pk_mul_f32 v[58:59], v[112:113], v[62:63]
	v_pk_mul_f32 v[62:63], v[110:111], v[80:81]
	v_pk_mul_f32 v[64:65], v[108:109], v[126:127]
	v_cvt_pk_bf16_f32 v58, v58, v59
	v_cvt_pk_bf16_f32 v59, v60, v61
	v_cvt_pk_bf16_f32 v61, v62, v63
	v_lshl_add_u64 v[62:63], s[22:23], 0, v[160:161]
	v_cvt_pk_bf16_f32 v60, v64, v65
	v_lshl_add_u64 v[62:63], v[62:63], 0, v[210:211]
	s_cbranch_vccnz .Lmy_wt_g2a_17
	global_store_dwordx4 v[62:63], v[58:61], off
.Lmy_wt_g2a_17r:
	s_waitcnt vmcnt(20)
	v_lshlrev_b32_e32 v64, 16, v150
	v_and_b32_e32 v65, 0xffff0000, v150
	v_lshlrev_b32_e32 v58, 16, v148
	v_and_b32_e32 v59, 0xffff0000, v148
	v_lshlrev_b32_e32 v60, 16, v149
	v_and_b32_e32 v61, 0xffff0000, v149
	v_lshlrev_b32_e32 v80, 16, v151
	v_and_b32_e32 v81, 0xffff0000, v151
	v_pk_fma_f32 v[54:55], v[54:55], v[104:105], v[58:59]
	v_pk_fma_f32 v[56:57], v[56:57], v[106:107], v[60:61]
	v_pk_fma_f32 v[58:59], v[52:53], v[102:103], v[80:81]
	v_pk_fma_f32 v[60:61], v[50:51], v[100:101], v[64:65]
	v_pk_mul_f32 v[52:53], v[58:59], v[58:59]
	v_pk_mul_f32 v[50:51], v[60:61], v[60:61]
	v_pk_fma_f32 v[52:53], v[56:57], v[56:57], v[52:53]
	v_pk_fma_f32 v[50:51], v[54:55], v[54:55], v[50:51]
	s_nop 0
	v_add_f32_e32 v50, v50, v51
	v_add_f32_e32 v51, v52, v53
	v_add_f32_e32 v50, v50, v51
	v_add_f32_e32 v64, v146, v50
	v_cvt_pk_bf16_f32 v50, v54, v55
	v_cvt_pk_bf16_f32 v51, v56, v57
	v_cvt_pk_bf16_f32 v52, v60, v61
	v_cvt_pk_bf16_f32 v53, v58, v59
	s_cbranch_vccnz .Lmy_wt_g2a_18
	global_store_dwordx4 v[158:159], v[50:53], off offset:256
.Lmy_wt_g2a_18r:
	ds_bpermute_b32 v53, v242, v64
	v_pk_mul_f32 v[56:57], v[96:97], v[56:57]
	v_pk_mul_f32 v[50:51], v[94:95], v[54:55]
	v_pk_mul_f32 v[58:59], v[92:93], v[58:59]
	v_cvt_pk_bf16_f32 v52, v50, v51
	s_waitcnt lgkmcnt(0)
	v_add_f32_e32 v50, v64, v53
	ds_bpermute_b32 v51, v243, v50
	v_pk_mul_f32 v[54:55], v[90:91], v[60:61]
	v_cvt_pk_bf16_f32 v53, v56, v57
	v_cvt_pk_bf16_f32 v54, v54, v55
	v_cvt_pk_bf16_f32 v55, v58, v59
	s_cbranch_vccnz .Lmy_wt_g2a_19
	global_store_dwordx4 v[62:63], v[52:55], off offset:256
.Lmy_wt_g2a_19r:
	s_and_saveexec_b64 s[70:71], s[38:39]
	s_cbranch_execz .LBB0_877
	v_lshlrev_b64 v[52:53], 6, v[156:157]
	v_lshl_add_u64 v[52:53], s[58:59], 0, v[52:53]
	v_lshl_add_u64 v[52:53], s[68:69], 2, v[52:53]
	s_lshl_b32 s48, s92, 2
	v_lshl_add_u64 v[52:53], v[52:53], 0, s[48:49]
	s_waitcnt lgkmcnt(0)
	v_add_f32_e32 v50, v50, v51
	global_store_dword v[52:53], v50, off
.LBB0_877:
	s_or_b64 exec, exec, s[70:71]
	s_waitcnt vmcnt(17)
	v_lshlrev_b32_e32 v50, 16, v136
	s_waitcnt lgkmcnt(0)
	v_and_b32_e32 v51, 0xffff0000, v136
	v_lshlrev_b32_e32 v52, 16, v137
	v_and_b32_e32 v53, 0xffff0000, v137
	v_lshlrev_b32_e32 v54, 16, v138
	v_and_b32_e32 v55, 0xffff0000, v138
	v_lshlrev_b32_e32 v56, 16, v139
	v_and_b32_e32 v57, 0xffff0000, v139
	v_pk_fma_f32 v[46:47], v[46:47], v[128:129], v[50:51]
	v_pk_fma_f32 v[48:49], v[48:49], v[130:131], v[52:53]
	v_pk_fma_f32 v[50:51], v[44:45], v[122:123], v[56:57]
	v_pk_fma_f32 v[52:53], v[42:43], v[120:121], v[54:55]
	v_pk_mul_f32 v[44:45], v[50:51], v[50:51]
	v_pk_mul_f32 v[42:43], v[52:53], v[52:53]
	v_pk_fma_f32 v[44:45], v[48:49], v[48:49], v[44:45]
	v_pk_fma_f32 v[42:43], v[46:47], v[46:47], v[42:43]
	s_nop 0
	v_add_f32_e32 v42, v42, v43
	v_add_f32_e32 v43, v44, v45
	v_add_f32_e32 v54, v42, v43
	v_cvt_pk_bf16_f32 v42, v46, v47
	v_cvt_pk_bf16_f32 v43, v48, v49
	v_cvt_pk_bf16_f32 v44, v52, v53
	v_cvt_pk_bf16_f32 v45, v50, v51
	s_cbranch_vccnz .Lmy_wt_g2a_20
	global_store_dwordx4 v[142:143], v[42:45], off
.Lmy_wt_g2a_20r:
	s_nop 1
	v_pk_mul_f32 v[44:45], v[114:115], v[48:49]
	v_pk_mul_f32 v[42:43], v[112:113], v[46:47]
	v_pk_mul_f32 v[46:47], v[110:111], v[50:51]
	v_pk_mul_f32 v[48:49], v[108:109], v[52:53]
	v_cvt_pk_bf16_f32 v42, v42, v43
	v_cvt_pk_bf16_f32 v43, v44, v45
	v_cvt_pk_bf16_f32 v45, v46, v47
	v_lshl_add_u64 v[46:47], s[22:23], 0, v[144:145]
	v_cvt_pk_bf16_f32 v44, v48, v49
	v_lshl_add_u64 v[46:47], v[46:47], 0, v[210:211]
	s_cbranch_vccnz .Lmy_wt_g2a_21
	global_store_dwordx4 v[46:47], v[42:45], off
.Lmy_wt_g2a_21r:
	s_waitcnt vmcnt(18)
	v_lshlrev_b32_e32 v48, 16, v134
	v_and_b32_e32 v49, 0xffff0000, v134
	v_lshlrev_b32_e32 v42, 16, v132
	v_and_b32_e32 v43, 0xffff0000, v132
	v_lshlrev_b32_e32 v44, 16, v133
	v_and_b32_e32 v45, 0xffff0000, v133
	v_lshlrev_b32_e32 v50, 16, v135
	v_and_b32_e32 v51, 0xffff0000, v135
	v_pk_fma_f32 v[38:39], v[38:39], v[104:105], v[42:43]
	v_pk_fma_f32 v[40:41], v[40:41], v[106:107], v[44:45]
	v_pk_fma_f32 v[42:43], v[36:37], v[102:103], v[50:51]
	v_pk_fma_f32 v[44:45], v[34:35], v[100:101], v[48:49]
	v_pk_mul_f32 v[36:37], v[42:43], v[42:43]
	v_pk_mul_f32 v[34:35], v[44:45], v[44:45]
	v_pk_fma_f32 v[36:37], v[40:41], v[40:41], v[36:37]
	v_pk_fma_f32 v[34:35], v[38:39], v[38:39], v[34:35]
	s_nop 0
	v_add_f32_e32 v34, v34, v35
	v_add_f32_e32 v35, v36, v37
	v_add_f32_e32 v34, v34, v35
	v_add_f32_e32 v48, v54, v34
	v_cvt_pk_bf16_f32 v34, v38, v39
	v_cvt_pk_bf16_f32 v35, v40, v41
	v_cvt_pk_bf16_f32 v36, v44, v45
	v_cvt_pk_bf16_f32 v37, v42, v43
	s_cbranch_vccnz .Lmy_wt_g2a_22
	global_store_dwordx4 v[142:143], v[34:37], off offset:256
.Lmy_wt_g2a_22r:
	ds_bpermute_b32 v37, v242, v48
	v_pk_mul_f32 v[40:41], v[96:97], v[40:41]
	v_pk_mul_f32 v[34:35], v[94:95], v[38:39]
	v_pk_mul_f32 v[42:43], v[92:93], v[42:43]
	v_cvt_pk_bf16_f32 v36, v34, v35
	s_waitcnt lgkmcnt(0)
	v_add_f32_e32 v34, v48, v37
	ds_bpermute_b32 v35, v243, v34
	v_pk_mul_f32 v[38:39], v[90:91], v[44:45]
	v_cvt_pk_bf16_f32 v37, v40, v41
	v_cvt_pk_bf16_f32 v38, v38, v39
	v_cvt_pk_bf16_f32 v39, v42, v43
	s_cbranch_vccnz .Lmy_wt_g2a_23
	global_store_dwordx4 v[46:47], v[36:39], off offset:256
.Lmy_wt_g2a_23r:
	s_and_saveexec_b64 s[70:71], s[38:39]
	s_cbranch_execz .LBB0_879
	v_lshlrev_b64 v[36:37], 6, v[140:141]
	v_lshl_add_u64 v[36:37], s[58:59], 0, v[36:37]
	v_lshl_add_u64 v[36:37], s[68:69], 2, v[36:37]
	s_lshl_b32 s48, s92, 2
	v_lshl_add_u64 v[36:37], v[36:37], 0, s[48:49]
	s_waitcnt lgkmcnt(0)
	v_add_f32_e32 v34, v34, v35
	global_store_dword v[36:37], v34, off
.LBB0_879:
	s_or_b64 exec, exec, s[70:71]
	s_waitcnt vmcnt(15)
	v_lshlrev_b32_e32 v34, 16, v86
	s_waitcnt lgkmcnt(0)
	v_and_b32_e32 v35, 0xffff0000, v86
	v_lshlrev_b32_e32 v36, 16, v87
	v_and_b32_e32 v37, 0xffff0000, v87
	v_lshlrev_b32_e32 v38, 16, v88
	v_and_b32_e32 v39, 0xffff0000, v88
	v_lshlrev_b32_e32 v40, 16, v89
	v_and_b32_e32 v41, 0xffff0000, v89
	v_pk_fma_f32 v[30:31], v[30:31], v[128:129], v[34:35]
	v_pk_fma_f32 v[32:33], v[32:33], v[130:131], v[36:37]
	v_pk_fma_f32 v[34:35], v[28:29], v[122:123], v[40:41]
	v_pk_fma_f32 v[36:37], v[26:27], v[120:121], v[38:39]
	v_pk_mul_f32 v[28:29], v[34:35], v[34:35]
	v_pk_mul_f32 v[26:27], v[36:37], v[36:37]
	v_pk_fma_f32 v[28:29], v[32:33], v[32:33], v[28:29]
	v_pk_fma_f32 v[26:27], v[30:31], v[30:31], v[26:27]
	s_nop 0
	v_add_f32_e32 v26, v26, v27
	v_add_f32_e32 v27, v28, v29
	v_add_f32_e32 v38, v26, v27
	v_cvt_pk_bf16_f32 v26, v30, v31
	v_cvt_pk_bf16_f32 v27, v32, v33
	v_cvt_pk_bf16_f32 v28, v36, v37
	v_cvt_pk_bf16_f32 v29, v34, v35
	s_cbranch_vccnz .Lmy_wt_g2a_24
	global_store_dwordx4 v[118:119], v[26:29], off
.Lmy_wt_g2a_24r:
	s_nop 1
	v_pk_mul_f32 v[28:29], v[114:115], v[32:33]
	v_pk_mul_f32 v[26:27], v[112:113], v[30:31]
	v_pk_mul_f32 v[30:31], v[110:111], v[34:35]
	v_pk_mul_f32 v[32:33], v[108:109], v[36:37]
	v_cvt_pk_bf16_f32 v26, v26, v27
	v_cvt_pk_bf16_f32 v27, v28, v29
	v_cvt_pk_bf16_f32 v29, v30, v31
	v_lshl_add_u64 v[30:31], s[22:23], 0, v[124:125]
	v_cvt_pk_bf16_f32 v28, v32, v33
	v_lshl_add_u64 v[30:31], v[30:31], 0, v[210:211]
	s_cbranch_vccnz .Lmy_wt_g2a_25
	global_store_dwordx4 v[30:31], v[26:29], off
.Lmy_wt_g2a_25r:
	s_waitcnt vmcnt(16)
	v_lshlrev_b32_e32 v32, 16, v84
	v_and_b32_e32 v33, 0xffff0000, v84
	v_lshlrev_b32_e32 v26, 16, v82
	v_and_b32_e32 v27, 0xffff0000, v82
	v_lshlrev_b32_e32 v28, 16, v83
	v_and_b32_e32 v29, 0xffff0000, v83
	v_lshlrev_b32_e32 v34, 16, v85
	v_and_b32_e32 v35, 0xffff0000, v85
	v_pk_fma_f32 v[22:23], v[22:23], v[104:105], v[26:27]
	v_pk_fma_f32 v[24:25], v[24:25], v[106:107], v[28:29]
	v_pk_fma_f32 v[26:27], v[20:21], v[102:103], v[34:35]
	v_pk_fma_f32 v[28:29], v[18:19], v[100:101], v[32:33]
	v_pk_mul_f32 v[20:21], v[26:27], v[26:27]
	v_pk_mul_f32 v[18:19], v[28:29], v[28:29]
	v_pk_fma_f32 v[20:21], v[24:25], v[24:25], v[20:21]
	v_pk_fma_f32 v[18:19], v[22:23], v[22:23], v[18:19]
	s_nop 0
	v_add_f32_e32 v18, v18, v19
	v_add_f32_e32 v19, v20, v21
	v_add_f32_e32 v18, v18, v19
	v_add_f32_e32 v32, v38, v18
	v_cvt_pk_bf16_f32 v18, v22, v23
	v_cvt_pk_bf16_f32 v19, v24, v25
	v_cvt_pk_bf16_f32 v20, v28, v29
	v_cvt_pk_bf16_f32 v21, v26, v27
	s_cbranch_vccnz .Lmy_wt_g2a_26
	global_store_dwordx4 v[118:119], v[18:21], off offset:256
.Lmy_wt_g2a_26r:
	ds_bpermute_b32 v21, v242, v32
	v_pk_mul_f32 v[24:25], v[96:97], v[24:25]
	v_pk_mul_f32 v[18:19], v[94:95], v[22:23]
	v_pk_mul_f32 v[26:27], v[92:93], v[26:27]
	v_cvt_pk_bf16_f32 v20, v18, v19
	s_waitcnt lgkmcnt(0)
	v_add_f32_e32 v18, v32, v21
	ds_bpermute_b32 v19, v243, v18
	v_pk_mul_f32 v[22:23], v[90:91], v[28:29]
	v_cvt_pk_bf16_f32 v21, v24, v25
	v_cvt_pk_bf16_f32 v22, v22, v23
	v_cvt_pk_bf16_f32 v23, v26, v27
	s_cbranch_vccnz .Lmy_wt_g2a_27
	global_store_dwordx4 v[30:31], v[20:23], off offset:256
.Lmy_wt_g2a_27r:
	s_and_saveexec_b64 s[70:71], s[38:39]
	s_cbranch_execz .LBB0_881
	v_lshlrev_b64 v[20:21], 6, v[116:117]
	v_lshl_add_u64 v[20:21], s[58:59], 0, v[20:21]
	v_lshl_add_u64 v[20:21], s[68:69], 2, v[20:21]
	s_lshl_b32 s48, s92, 2
	v_lshl_add_u64 v[20:21], v[20:21], 0, s[48:49]
	s_waitcnt lgkmcnt(0)
	v_add_f32_e32 v18, v18, v19
	global_store_dword v[20:21], v18, off
.LBB0_881:
	s_or_b64 exec, exec, s[70:71]
	s_waitcnt vmcnt(13)
	v_lshlrev_b32_e32 v18, 16, v70
	s_waitcnt lgkmcnt(0)
	v_and_b32_e32 v19, 0xffff0000, v70
	v_lshlrev_b32_e32 v20, 16, v71
	v_and_b32_e32 v21, 0xffff0000, v71
	v_lshlrev_b32_e32 v22, 16, v72
	v_and_b32_e32 v23, 0xffff0000, v72
	v_lshlrev_b32_e32 v24, 16, v73
	v_and_b32_e32 v25, 0xffff0000, v73
	v_pk_fma_f32 v[14:15], v[14:15], v[128:129], v[18:19]
	v_pk_fma_f32 v[16:17], v[16:17], v[130:131], v[20:21]
	v_pk_fma_f32 v[18:19], v[12:13], v[122:123], v[24:25]
	v_pk_fma_f32 v[20:21], v[10:11], v[120:121], v[22:23]
	v_pk_mul_f32 v[12:13], v[18:19], v[18:19]
	v_pk_mul_f32 v[10:11], v[20:21], v[20:21]
	v_pk_fma_f32 v[12:13], v[16:17], v[16:17], v[12:13]
	v_pk_fma_f32 v[10:11], v[14:15], v[14:15], v[10:11]
	s_nop 0
	v_add_f32_e32 v10, v10, v11
	v_add_f32_e32 v11, v12, v13
	v_add_f32_e32 v22, v10, v11
	v_cvt_pk_bf16_f32 v10, v14, v15
	v_cvt_pk_bf16_f32 v11, v16, v17
	v_cvt_pk_bf16_f32 v12, v20, v21
	v_cvt_pk_bf16_f32 v13, v18, v19
	s_cbranch_vccnz .Lmy_wt_g2a_28
	global_store_dwordx4 v[76:77], v[10:13], off
.Lmy_wt_g2a_28r:
	s_nop 1
	v_pk_mul_f32 v[12:13], v[114:115], v[16:17]
	v_pk_mul_f32 v[10:11], v[112:113], v[14:15]
	v_pk_mul_f32 v[14:15], v[110:111], v[18:19]
	v_pk_mul_f32 v[16:17], v[108:109], v[20:21]
	v_cvt_pk_bf16_f32 v10, v10, v11
	v_cvt_pk_bf16_f32 v11, v12, v13
	v_cvt_pk_bf16_f32 v13, v14, v15
	v_lshl_add_u64 v[14:15], s[22:23], 0, v[78:79]
	v_cvt_pk_bf16_f32 v12, v16, v17
	v_lshl_add_u64 v[14:15], v[14:15], 0, v[210:211]
	s_cbranch_vccnz .Lmy_wt_g2a_29
	global_store_dwordx4 v[14:15], v[10:13], off
.Lmy_wt_g2a_29r:
	s_waitcnt vmcnt(14)
	v_lshlrev_b32_e32 v16, 16, v68
	v_and_b32_e32 v17, 0xffff0000, v68
	v_lshlrev_b32_e32 v10, 16, v66
	v_and_b32_e32 v11, 0xffff0000, v66
	v_lshlrev_b32_e32 v12, 16, v67
	v_and_b32_e32 v13, 0xffff0000, v67
	v_lshlrev_b32_e32 v18, 16, v69
	v_and_b32_e32 v19, 0xffff0000, v69
	v_pk_fma_f32 v[6:7], v[6:7], v[104:105], v[10:11]
	v_pk_fma_f32 v[8:9], v[8:9], v[106:107], v[12:13]
	v_pk_fma_f32 v[10:11], v[4:5], v[102:103], v[18:19]
	v_pk_fma_f32 v[12:13], v[2:3], v[100:101], v[16:17]
	v_pk_mul_f32 v[4:5], v[10:11], v[10:11]
	v_pk_mul_f32 v[2:3], v[12:13], v[12:13]
	v_pk_fma_f32 v[4:5], v[8:9], v[8:9], v[4:5]
	v_pk_fma_f32 v[2:3], v[6:7], v[6:7], v[2:3]
	s_nop 0
	v_add_f32_e32 v2, v2, v3
	v_add_f32_e32 v3, v4, v5
	v_add_f32_e32 v2, v2, v3
	v_add_f32_e32 v16, v22, v2
	v_cvt_pk_bf16_f32 v2, v6, v7
	v_cvt_pk_bf16_f32 v3, v8, v9
	v_cvt_pk_bf16_f32 v4, v12, v13
	v_cvt_pk_bf16_f32 v5, v10, v11
	s_cbranch_vccnz .Lmy_wt_g2a_30
	global_store_dwordx4 v[76:77], v[2:5], off offset:256
.Lmy_wt_g2a_30r:
	ds_bpermute_b32 v5, v242, v16
	v_pk_mul_f32 v[8:9], v[96:97], v[8:9]
	v_pk_mul_f32 v[2:3], v[94:95], v[6:7]
	v_pk_mul_f32 v[10:11], v[92:93], v[10:11]
	v_cvt_pk_bf16_f32 v4, v2, v3
	s_waitcnt lgkmcnt(0)
	v_add_f32_e32 v2, v16, v5
	ds_bpermute_b32 v3, v243, v2
	v_pk_mul_f32 v[6:7], v[90:91], v[12:13]
	v_cvt_pk_bf16_f32 v5, v8, v9
	v_cvt_pk_bf16_f32 v6, v6, v7
	v_cvt_pk_bf16_f32 v7, v10, v11
	s_cbranch_vccnz .Lmy_wt_g2a_31
	global_store_dwordx4 v[14:15], v[4:7], off offset:256
.Lmy_wt_g2a_31r:
	s_and_saveexec_b64 s[70:71], s[38:39]
	s_cbranch_execz .LBB0_883
	v_lshlrev_b64 v[4:5], 6, v[74:75]
	v_lshl_add_u64 v[4:5], s[58:59], 0, v[4:5]
	v_lshl_add_u64 v[4:5], s[68:69], 2, v[4:5]
	s_lshl_b32 s48, s92, 2
	v_lshl_add_u64 v[4:5], v[4:5], 0, s[48:49]
	s_waitcnt lgkmcnt(0)
	v_add_f32_e32 v2, v2, v3
	global_store_dword v[4:5], v2, off

.Lmy_wt_g2a_0:
	global_store_dwordx4 v[200:201], v[156:159], off sc1
	s_branch .Lmy_wt_g2a_0r
.Lmy_wt_g2a_1:
	global_store_dwordx4 v[160:161], v[156:159], off sc1
	s_branch .Lmy_wt_g2a_1r
.Lmy_wt_g2a_2:
	global_store_dwordx4 v[200:201], v[148:151], off offset:256 sc1
	s_branch .Lmy_wt_g2a_2r
.Lmy_wt_g2a_3:
	global_store_dwordx4 v[160:161], v[148:151], off offset:256 sc1
	s_branch .Lmy_wt_g2a_3r
.Lmy_wt_g2a_4:
	global_store_dwordx4 v[186:187], v[140:143], off sc1
	s_branch .Lmy_wt_g2a_4r
.Lmy_wt_g2a_5:
	global_store_dwordx4 v[144:145], v[140:143], off sc1
	s_branch .Lmy_wt_g2a_5r
.Lmy_wt_g2a_6:
	global_store_dwordx4 v[186:187], v[132:135], off offset:256 sc1
	s_branch .Lmy_wt_g2a_6r
.Lmy_wt_g2a_7:
	global_store_dwordx4 v[144:145], v[134:137], off offset:256 sc1
	s_branch .Lmy_wt_g2a_7r
.Lmy_wt_g2a_8:
	global_store_dwordx4 v[176:177], v[116:119], off sc1
	s_branch .Lmy_wt_g2a_8r
.Lmy_wt_g2a_9:
	global_store_dwordx4 v[124:125], v[116:119], off sc1
	s_branch .Lmy_wt_g2a_9r
.Lmy_wt_g2a_10:
	global_store_dwordx4 v[176:177], v[82:85], off offset:256 sc1
	s_branch .Lmy_wt_g2a_10r
.Lmy_wt_g2a_11:
	global_store_dwordx4 v[124:125], v[84:87], off offset:256 sc1
	s_branch .Lmy_wt_g2a_11r
.Lmy_wt_g2a_12:
	global_store_dwordx4 v[162:163], v[74:77], off sc1
	s_branch .Lmy_wt_g2a_12r

.Lmy_wt_g2a_14:
	global_store_dwordx4 v[162:163], v[66:69], off offset:256 sc1
	s_branch .Lmy_wt_g2a_14r
.Lmy_wt_g2a_15:
	global_store_dwordx4 v[78:79], v[68:71], off offset:256 sc1
	s_branch .Lmy_wt_g2a_15r
.Lmy_wt_g2a_16:
	global_store_dwordx4 v[158:159], v[58:61], off sc1
	s_branch .Lmy_wt_g2a_16r

.Lmy_wt_g2a_18:
	global_store_dwordx4 v[158:159], v[50:53], off offset:256 sc1
	s_branch .Lmy_wt_g2a_18r
.Lmy_wt_g2a_19:
	global_store_dwordx4 v[62:63], v[52:55], off offset:256 sc1
	s_branch .Lmy_wt_g2a_19r
.Lmy_wt_g2a_20:
	global_store_dwordx4 v[142:143], v[42:45], off sc1
	s_branch .Lmy_wt_g2a_20r

.Lmy_wt_g2a_22:
	global_store_dwordx4 v[142:143], v[34:37], off offset:256 sc1
	s_branch .Lmy_wt_g2a_22r
.Lmy_wt_g2a_23:
	global_store_dwordx4 v[46:47], v[36:39], off offset:256 sc1
	s_branch .Lmy_wt_g2a_23r
.Lmy_wt_g2a_24:
	global_store_dwordx4 v[118:119], v[26:29], off sc1
	s_branch .Lmy_wt_g2a_24r

.Lmy_wt_g2a_26:
	global_store_dwordx4 v[118:119], v[18:21], off offset:256 sc1
	s_branch .Lmy_wt_g2a_26r
.Lmy_wt_g2a_27:
	global_store_dwordx4 v[30:31], v[20:23], off offset:256 sc1
	s_branch .Lmy_wt_g2a_27r
.Lmy_wt_g2a_28:
	global_store_dwordx4 v[76:77], v[10:13], off sc1
	s_branch .Lmy_wt_g2a_28r

.Lmy_wt_g2a_30:
	global_store_dwordx4 v[76:77], v[2:5], off offset:256 sc1
	s_branch .Lmy_wt_g2a_30r
.Lmy_wt_g2a_31:
	global_store_dwordx4 v[14:15], v[4:7], off offset:256 sc1
	s_branch .Lmy_wt_g2a_31r

.LBB0_921:
	s_or_b64 exec, exec, s[68:69]
	v_readlane_b32 s4, v252, 3
	v_or_b32_e32 v132, 48, v180
	v_readlane_b32 s5, v252, 4
	v_readlane_b32 s7, v252, 6
	v_ashrrev_i32_e32 v133, 31, v132
	v_add_u32_e32 v50, 0xffffc0b0, v214
	v_cmp_gt_i32_e32 vcc, s21, v132
	v_readlane_b32 s6, v252, 5
	v_mov_b32_e32 v52, s7
	v_mov_b32_e32 v53, s5
	s_waitcnt lgkmcnt(0)
	v_cndmask_b32_e32 v51, 0, v133, vcc
	v_cndmask_b32_e32 v50, v50, v132, vcc
	v_cndmask_b32_e32 v53, v52, v53, vcc
	v_mov_b32_e32 v52, s6
	v_mov_b32_e32 v54, s4
	v_cndmask_b32_e32 v52, v52, v54, vcc
	s_andn2_b64 vcc, exec, s[38:39]
	v_lshlrev_b64 v[50:51], 12, v[50:51]
	v_lshl_add_u64 v[50:51], v[52:53], 0, v[50:51]
	v_lshl_add_u64 v[54:55], v[212:213], 2, v[50:51]
	global_load_dwordx4 v[58:61], v[54:55], off offset:16
	global_load_dwordx4 v[62:65], v[54:55], off
	global_load_dwordx4 v[50:53], v[54:55], off offset:528
	s_nop 0
	global_load_dwordx4 v[54:57], v[54:55], off offset:512
	v_or_b32_e32 v134, 16, v180
	s_waitcnt vmcnt(19)
	v_pk_fma_f32 v[122:123], v[44:45], v[118:119], v[122:123]
	v_pk_fma_f32 v[120:121], v[42:43], v[116:117], v[120:121]
	v_ashrrev_i32_e32 v135, 31, v134
	s_waitcnt vmcnt(18)
	v_pk_fma_f32 v[48:49], v[48:49], v[126:127], v[130:131]
	v_pk_fma_f32 v[46:47], v[46:47], v[124:125], v[128:129]
	v_pk_mul_f32 v[42:43], v[122:123], v[122:123]
	v_pk_mul_f32 v[44:45], v[120:121], v[120:121]
	v_pk_fma_f32 v[42:43], v[48:49], v[48:49], v[42:43]
	v_pk_fma_f32 v[44:45], v[46:47], v[46:47], v[44:45]
	v_lshlrev_b64 v[128:129], 11, v[134:135]
	v_add_f32_e32 v44, v44, v45
	v_add_f32_e32 v42, v42, v43
	v_lshl_add_u64 v[130:131], s[82:83], 0, v[128:129]
	v_add_f32_e32 v136, v44, v42
	v_cvt_pk_bf16_f32 v42, v46, v47
	v_cvt_pk_bf16_f32 v43, v48, v49
	v_cvt_pk_bf16_f32 v44, v120, v121
	v_cvt_pk_bf16_f32 v45, v122, v123
	v_lshl_add_u64 v[130:131], v[130:131], 0, v[210:211]
	s_cbranch_vccnz .Lmy_wt_g2b_0
	global_store_dwordx4 v[130:131], v[42:45], off
.Lmy_wt_g2b_0r:
	s_waitcnt vmcnt(17)
	v_pk_fma_f32 v[40:41], v[40:41], v[106:107], v[96:97]
	v_pk_fma_f32 v[38:39], v[38:39], v[104:105], v[94:95]
	v_pk_mul_f32 v[44:45], v[114:115], v[48:49]
	v_pk_mul_f32 v[42:43], v[112:113], v[46:47]
	v_pk_mul_f32 v[46:47], v[110:111], v[122:123]
	v_pk_mul_f32 v[48:49], v[108:109], v[120:121]
	v_cvt_pk_bf16_f32 v42, v42, v43
	v_cvt_pk_bf16_f32 v43, v44, v45
	v_cvt_pk_bf16_f32 v45, v46, v47
	v_lshl_add_u64 v[46:47], s[22:23], 0, v[128:129]
	v_cvt_pk_bf16_f32 v44, v48, v49
	v_lshl_add_u64 v[46:47], v[46:47], 0, v[210:211]
	s_cbranch_vccnz .Lmy_wt_g2b_1
	global_store_dwordx4 v[46:47], v[42:45], off
.Lmy_wt_g2b_1r:
	v_readlane_b32 s8, v252, 7
	v_readlane_b32 s9, v252, 8
	v_pk_fma_f32 v[42:43], v[36:37], v[102:103], v[84:85]
	v_pk_fma_f32 v[44:45], v[34:35], v[100:101], v[82:83]
	v_pk_mul_f32 v[34:35], v[42:43], v[42:43]
	v_pk_mul_f32 v[36:37], v[44:45], v[44:45]
	v_pk_fma_f32 v[34:35], v[40:41], v[40:41], v[34:35]
	v_pk_fma_f32 v[36:37], v[38:39], v[38:39], v[36:37]
	v_add_f32_e32 v34, v34, v35
	v_add_f32_e32 v36, v36, v37
	v_add_f32_e32 v34, v36, v34
	v_add_f32_e32 v48, v136, v34
	v_cvt_pk_bf16_f32 v34, v38, v39
	v_cvt_pk_bf16_f32 v35, v40, v41
	v_cvt_pk_bf16_f32 v36, v44, v45
	v_cvt_pk_bf16_f32 v37, v42, v43
	s_cbranch_vccnz .Lmy_wt_g2b_2
	global_store_dwordx4 v[130:131], v[34:37], off offset:256
.Lmy_wt_g2b_2r:
	ds_bpermute_b32 v37, v227, v48
	v_pk_mul_f32 v[40:41], v[92:93], v[40:41]
	v_pk_mul_f32 v[34:35], v[90:91], v[38:39]
	v_pk_mul_f32 v[42:43], v[88:89], v[42:43]
	v_cvt_pk_bf16_f32 v36, v34, v35
	s_waitcnt lgkmcnt(0)
	v_add_f32_e32 v34, v48, v37
	ds_bpermute_b32 v35, v226, v34
	v_pk_mul_f32 v[38:39], v[86:87], v[44:45]
	v_cvt_pk_bf16_f32 v37, v40, v41
	v_cvt_pk_bf16_f32 v38, v38, v39
	v_cvt_pk_bf16_f32 v39, v42, v43
	v_readlane_b32 s10, v252, 9
	v_readlane_b32 s11, v252, 10
	v_readlane_b32 s12, v252, 11
	v_readlane_b32 s13, v252, 12
	v_readlane_b32 s14, v252, 13
	v_readlane_b32 s15, v252, 14
	v_readlane_b32 s16, v252, 15
	v_readlane_b32 s17, v252, 16
	v_readlane_b32 s18, v252, 17
	v_readlane_b32 s19, v252, 18
	s_cbranch_vccnz .Lmy_wt_g2b_3
	global_store_dwordx4 v[46:47], v[36:39], off offset:256
.Lmy_wt_g2b_3r:
	s_and_saveexec_b64 s[68:69], s[36:37]
	s_cbranch_execz .LBB0_923
	v_lshlrev_b64 v[36:37], 6, v[134:135]
	v_lshl_add_u64 v[36:37], s[58:59], 0, v[36:37]
	v_lshl_add_u64 v[36:37], s[56:57], 2, v[36:37]
	s_lshl_b32 s48, s75, 2
	v_lshl_add_u64 v[36:37], v[36:37], 0, s[48:49]
	s_waitcnt lgkmcnt(0)
	v_add_f32_e32 v34, v34, v35
	global_store_dword v[36:37], v34, off
.LBB0_923:
	s_or_b64 exec, exec, s[68:69]
	s_waitcnt vmcnt(15) lgkmcnt(0)
	v_pk_fma_f32 v[34:35], v[28:29], v[118:119], v[76:77]
	v_pk_fma_f32 v[36:37], v[26:27], v[116:117], v[74:75]
	s_waitcnt vmcnt(14)
	v_pk_fma_f32 v[32:33], v[32:33], v[126:127], v[80:81]
	v_pk_fma_f32 v[30:31], v[30:31], v[124:125], v[78:79]
	v_pk_mul_f32 v[26:27], v[34:35], v[34:35]
	v_pk_mul_f32 v[28:29], v[36:37], v[36:37]
	v_pk_fma_f32 v[26:27], v[32:33], v[32:33], v[26:27]
	v_pk_fma_f32 v[28:29], v[30:31], v[30:31], v[28:29]
	v_lshlrev_b64 v[38:39], 11, v[148:149]
	v_add_f32_e32 v28, v28, v29
	v_add_f32_e32 v26, v26, v27
	v_lshl_add_u64 v[40:41], s[82:83], 0, v[38:39]
	v_add_f32_e32 v42, v28, v26
	v_cvt_pk_bf16_f32 v26, v30, v31
	v_cvt_pk_bf16_f32 v27, v32, v33
	v_cvt_pk_bf16_f32 v28, v36, v37
	v_cvt_pk_bf16_f32 v29, v34, v35
	v_lshl_add_u64 v[40:41], v[40:41], 0, v[210:211]
	s_cbranch_vccnz .Lmy_wt_g2b_4
	global_store_dwordx4 v[40:41], v[26:29], off
.Lmy_wt_g2b_4r:
	s_waitcnt vmcnt(13)
	v_pk_fma_f32 v[24:25], v[24:25], v[106:107], v[72:73]
	v_pk_fma_f32 v[22:23], v[22:23], v[104:105], v[70:71]
	v_pk_mul_f32 v[28:29], v[114:115], v[32:33]
	v_pk_mul_f32 v[26:27], v[112:113], v[30:31]
	v_pk_mul_f32 v[30:31], v[110:111], v[34:35]
	v_pk_mul_f32 v[32:33], v[108:109], v[36:37]
	v_cvt_pk_bf16_f32 v26, v26, v27
	v_cvt_pk_bf16_f32 v27, v28, v29
	v_cvt_pk_bf16_f32 v29, v30, v31
	v_lshl_add_u64 v[30:31], s[22:23], 0, v[38:39]
	v_cvt_pk_bf16_f32 v28, v32, v33
	v_lshl_add_u64 v[30:31], v[30:31], 0, v[210:211]
	s_cbranch_vccnz .Lmy_wt_g2b_5
	global_store_dwordx4 v[30:31], v[26:29], off
.Lmy_wt_g2b_5r:
	s_nop 1
	v_pk_fma_f32 v[26:27], v[20:21], v[102:103], v[68:69]
	v_pk_fma_f32 v[28:29], v[18:19], v[100:101], v[66:67]
	v_pk_mul_f32 v[18:19], v[26:27], v[26:27]
	v_pk_mul_f32 v[20:21], v[28:29], v[28:29]
	v_pk_fma_f32 v[18:19], v[24:25], v[24:25], v[18:19]
	v_pk_fma_f32 v[20:21], v[22:23], v[22:23], v[20:21]
	v_add_f32_e32 v18, v18, v19
	v_add_f32_e32 v20, v20, v21
	v_add_f32_e32 v18, v20, v18
	v_add_f32_e32 v32, v42, v18
	v_cvt_pk_bf16_f32 v18, v22, v23
	v_cvt_pk_bf16_f32 v19, v24, v25
	v_cvt_pk_bf16_f32 v20, v28, v29
	v_cvt_pk_bf16_f32 v21, v26, v27
	s_cbranch_vccnz .Lmy_wt_g2b_6
	global_store_dwordx4 v[40:41], v[18:21], off offset:256
.Lmy_wt_g2b_6r:
	ds_bpermute_b32 v21, v227, v32
	v_pk_mul_f32 v[24:25], v[92:93], v[24:25]
	v_pk_mul_f32 v[18:19], v[90:91], v[22:23]
	v_pk_mul_f32 v[26:27], v[88:89], v[26:27]
	v_cvt_pk_bf16_f32 v20, v18, v19
	s_waitcnt lgkmcnt(0)
	v_add_f32_e32 v18, v32, v21
	ds_bpermute_b32 v19, v226, v18
	v_pk_mul_f32 v[22:23], v[86:87], v[28:29]
	v_cvt_pk_bf16_f32 v21, v24, v25
	v_cvt_pk_bf16_f32 v22, v22, v23
	v_cvt_pk_bf16_f32 v23, v26, v27
	s_cbranch_vccnz .Lmy_wt_g2b_7
	global_store_dwordx4 v[30:31], v[20:23], off offset:256
.Lmy_wt_g2b_7r:
	s_and_saveexec_b64 s[68:69], s[36:37]
	s_cbranch_execz .LBB0_925
	v_lshlrev_b64 v[20:21], 6, v[148:149]
	v_lshl_add_u64 v[20:21], s[58:59], 0, v[20:21]
	v_lshl_add_u64 v[20:21], s[56:57], 2, v[20:21]
	s_lshl_b32 s48, s75, 2
	v_lshl_add_u64 v[20:21], v[20:21], 0, s[48:49]
	s_waitcnt lgkmcnt(0)
	v_add_f32_e32 v18, v18, v19
	global_store_dword v[20:21], v18, off
.LBB0_925:
	s_or_b64 exec, exec, s[68:69]
	s_waitcnt vmcnt(11) lgkmcnt(0)
	v_pk_fma_f32 v[18:19], v[12:13], v[118:119], v[60:61]
	v_pk_fma_f32 v[20:21], v[10:11], v[116:117], v[58:59]
	s_waitcnt vmcnt(10)
	v_pk_fma_f32 v[16:17], v[16:17], v[126:127], v[64:65]
	v_pk_fma_f32 v[14:15], v[14:15], v[124:125], v[62:63]
	v_pk_mul_f32 v[10:11], v[18:19], v[18:19]
	v_pk_mul_f32 v[12:13], v[20:21], v[20:21]
	v_pk_fma_f32 v[10:11], v[16:17], v[16:17], v[10:11]
	v_pk_fma_f32 v[12:13], v[14:15], v[14:15], v[12:13]
	v_lshlrev_b64 v[22:23], 11, v[132:133]
	v_add_f32_e32 v12, v12, v13
	v_add_f32_e32 v10, v10, v11
	v_lshl_add_u64 v[24:25], s[82:83], 0, v[22:23]
	v_add_f32_e32 v26, v12, v10
	v_cvt_pk_bf16_f32 v10, v14, v15
	v_cvt_pk_bf16_f32 v11, v16, v17
	v_cvt_pk_bf16_f32 v12, v20, v21
	v_cvt_pk_bf16_f32 v13, v18, v19
	v_lshl_add_u64 v[24:25], v[24:25], 0, v[210:211]
	s_cbranch_vccnz .Lmy_wt_g2b_8
	global_store_dwordx4 v[24:25], v[10:13], off
.Lmy_wt_g2b_8r:
	s_waitcnt vmcnt(9)
	v_pk_fma_f32 v[8:9], v[8:9], v[106:107], v[56:57]
	v_pk_fma_f32 v[6:7], v[6:7], v[104:105], v[54:55]
	v_pk_mul_f32 v[12:13], v[114:115], v[16:17]
	v_pk_mul_f32 v[10:11], v[112:113], v[14:15]
	v_pk_mul_f32 v[14:15], v[110:111], v[18:19]
	v_pk_mul_f32 v[16:17], v[108:109], v[20:21]
	v_cvt_pk_bf16_f32 v10, v10, v11
	v_cvt_pk_bf16_f32 v11, v12, v13
	v_cvt_pk_bf16_f32 v13, v14, v15
	v_lshl_add_u64 v[14:15], s[22:23], 0, v[22:23]
	v_cvt_pk_bf16_f32 v12, v16, v17
	v_lshl_add_u64 v[14:15], v[14:15], 0, v[210:211]
	s_cbranch_vccnz .Lmy_wt_g2b_9
	global_store_dwordx4 v[14:15], v[10:13], off
.Lmy_wt_g2b_9r:
	s_nop 1
	v_pk_fma_f32 v[10:11], v[4:5], v[102:103], v[52:53]
	v_pk_fma_f32 v[12:13], v[2:3], v[100:101], v[50:51]
	v_pk_mul_f32 v[2:3], v[10:11], v[10:11]
	v_pk_mul_f32 v[4:5], v[12:13], v[12:13]
	v_pk_fma_f32 v[2:3], v[8:9], v[8:9], v[2:3]
	v_pk_fma_f32 v[4:5], v[6:7], v[6:7], v[4:5]
	v_add_f32_e32 v2, v2, v3
	v_add_f32_e32 v4, v4, v5
	v_add_f32_e32 v2, v4, v2
	v_add_f32_e32 v16, v26, v2
	v_cvt_pk_bf16_f32 v2, v6, v7
	v_cvt_pk_bf16_f32 v3, v8, v9
	v_cvt_pk_bf16_f32 v4, v12, v13
	v_cvt_pk_bf16_f32 v5, v10, v11
	s_cbranch_vccnz .Lmy_wt_g2b_10
	global_store_dwordx4 v[24:25], v[2:5], off offset:256
.Lmy_wt_g2b_10r:
	ds_bpermute_b32 v5, v227, v16
	v_pk_mul_f32 v[8:9], v[92:93], v[8:9]
	v_pk_mul_f32 v[2:3], v[90:91], v[6:7]
	v_pk_mul_f32 v[10:11], v[88:89], v[10:11]
	v_cvt_pk_bf16_f32 v4, v2, v3
	s_waitcnt lgkmcnt(0)
	v_add_f32_e32 v2, v16, v5
	ds_bpermute_b32 v3, v226, v2
	v_pk_mul_f32 v[6:7], v[86:87], v[12:13]
	v_cvt_pk_bf16_f32 v5, v8, v9
	v_cvt_pk_bf16_f32 v6, v6, v7
	v_cvt_pk_bf16_f32 v7, v10, v11
	s_cbranch_vccnz .Lmy_wt_g2b_11
	global_store_dwordx4 v[14:15], v[4:7], off offset:256
.Lmy_wt_g2b_11r:
	s_and_saveexec_b64 s[68:69], s[36:37]
	s_cbranch_execz .LBB0_927
	v_lshlrev_b64 v[4:5], 6, v[132:133]
	v_lshl_add_u64 v[4:5], s[58:59], 0, v[4:5]
	v_lshl_add_u64 v[4:5], s[56:57], 2, v[4:5]
	s_lshl_b32 s48, s75, 2
	v_lshl_add_u64 v[4:5], v[4:5], 0, s[48:49]
	s_waitcnt lgkmcnt(0)
	v_add_f32_e32 v2, v2, v3
	global_store_dword v[4:5], v2, off

.Lmy_wt_g2b_0:
	global_store_dwordx4 v[130:131], v[42:45], off sc1
	s_branch .Lmy_wt_g2b_0r

.Lmy_wt_g2b_2:
	global_store_dwordx4 v[130:131], v[34:37], off offset:256 sc1
	s_branch .Lmy_wt_g2b_2r

.Lmy_wt_g2b_4:
	global_store_dwordx4 v[40:41], v[26:29], off sc1
	s_branch .Lmy_wt_g2b_4r

.Lmy_wt_g2b_6:
	global_store_dwordx4 v[40:41], v[18:21], off offset:256 sc1
	s_branch .Lmy_wt_g2b_6r

.Lmy_wt_g2b_8:
	global_store_dwordx4 v[24:25], v[10:13], off sc1
	s_branch .Lmy_wt_g2b_8r

.Lmy_wt_g2b_10:
	global_store_dwordx4 v[24:25], v[2:5], off offset:256 sc1
	s_branch .Lmy_wt_g2b_10r

.LBB0_1014:
	s_lshl_b32 s4, s77, 8
	v_add_u32_e32 v162, s4, v188
	v_ashrrev_i32_e32 v163, 31, v162
	v_or_b32_e32 v180, 16, v162
	v_lshlrev_b64 v[132:133], 6, v[162:163]
	v_ashrrev_i32_e32 v181, 31, v180
	v_or_b32_e32 v176, 32, v162
	v_lshl_add_u64 v[132:133], v[154:155], 0, v[132:133]
	v_lshlrev_b64 v[134:135], 6, v[180:181]
	v_ashrrev_i32_e32 v177, 31, v176
	v_lshl_add_u64 v[134:135], v[154:155], 0, v[134:135]
	global_load_dwordx4 v[192:195], v[132:133], off
	global_load_dwordx4 v[200:203], v[134:135], off
	v_lshlrev_b64 v[132:133], 6, v[176:177]
	v_lshl_add_u64 v[132:133], v[154:155], 0, v[132:133]
	global_load_dwordx4 v[204:207], v[132:133], off
	v_or_b32_e32 v170, 48, v162
	v_ashrrev_i32_e32 v171, 31, v170
	v_lshlrev_b64 v[132:133], 6, v[170:171]
	v_lshl_add_u64 v[132:133], v[154:155], 0, v[132:133]
	global_load_dwordx4 v[208:211], v[132:133], off
	v_add_u32_e32 v166, 0x80, v162
	v_ashrrev_i32_e32 v167, 31, v166
	v_lshlrev_b64 v[132:133], 6, v[166:167]
	v_lshl_add_u64 v[132:133], v[154:155], 0, v[132:133]
	global_load_dwordx4 v[212:215], v[132:133], off
	v_add_u32_e32 v164, 0x90, v162
	v_and_b32_e32 v132, 64, v229
	v_ashrrev_i32_e32 v165, 31, v164
	v_add_u32_e32 v136, 64, v132
	v_lshlrev_b64 v[132:133], 6, v[164:165]
	v_lshl_add_u64 v[132:133], v[154:155], 0, v[132:133]
	global_load_dwordx4 v[216:219], v[132:133], off
	v_add_u32_e32 v158, 0xa0, v162
	v_ashrrev_i32_e32 v159, 31, v158
	v_add_u32_e32 v156, 0xb0, v162
	v_lshlrev_b64 v[132:133], 6, v[158:159]
	v_ashrrev_i32_e32 v157, 31, v156
	v_lshl_add_u64 v[132:133], v[154:155], 0, v[132:133]
	global_load_dwordx4 v[220:223], v[132:133], off
	v_lshlrev_b64 v[132:133], 6, v[156:157]
	v_lshl_add_u64 v[132:133], v[154:155], 0, v[132:133]
	global_load_dwordx4 v[224:227], v[132:133], off
	s_addk_i32 s4, 0xc000
	s_lshr_b32 s4, s4, 12
	s_ashr_i32 s5, s77, 5
	s_add_i32 s4, s4, 2
	s_cmp_lt_i32 s77, 64
	s_cselect_b32 s4, s5, s4
	s_ashr_i32 s5, s4, 31
	v_xor_b32_e32 v134, 16, v229
	s_lshl_b64 s[4:5], s[4:5], 14
	v_lshl_or_b32 v238, s79, 8, v190
	v_xor_b32_e32 v135, 32, v229
	v_cmp_lt_i32_e32 vcc, v134, v136
	s_add_u32 s4, s71, s4
	v_ashrrev_i32_e32 v239, 31, v238
	v_cndmask_b32_e32 v134, v229, v134, vcc
	v_cmp_lt_i32_e32 vcc, v135, v136
	s_addc_u32 s5, s74, s5
	v_lshl_add_u64 v[136:137], v[238:239], 2, s[4:5]
	v_cndmask_b32_e32 v135, v229, v135, vcc
	v_lshlrev_b32_e32 v160, 2, v134
	v_lshlrev_b32_e32 v168, 2, v135
	global_load_dwordx4 v[140:143], v[136:137], off offset:16
	global_load_dwordx4 v[144:147], v[136:137], off
	global_load_dwordx4 v[132:135], v[136:137], off offset:528
	s_nop 0
	global_load_dwordx4 v[136:139], v[136:137], off offset:512
	s_andn2_b64 vcc, exec, s[36:37]
	s_mov_b64 s[36:37], -1
	s_waitcnt vmcnt(0)
	v_mov_b32_e32 v240, v193
	v_mov_b32_e32 v241, v194
	v_mov_b32_e32 v193, v195
	v_pk_add_f32 v[192:193], v[240:241], v[192:193]
	v_mov_b32_e32 v194, v201
	v_mov_b32_e32 v195, v202
	v_mov_b32_e32 v201, v203
	v_add_f32_e32 v172, v192, v193
	v_pk_add_f32 v[192:193], v[194:195], v[200:201]
	v_mov_b32_e32 v202, v205
	v_mov_b32_e32 v203, v206
	v_mov_b32_e32 v205, v207
	ds_bpermute_b32 v174, v160, v172
	v_add_f32_e32 v178, v192, v193
	v_pk_add_f32 v[194:195], v[202:203], v[204:205]
	ds_bpermute_b32 v192, v160, v178
	v_add_f32_e32 v182, v194, v195
	ds_bpermute_b32 v194, v160, v182
	s_waitcnt lgkmcnt(2)
	v_add_f32_e32 v172, v172, v174
	ds_bpermute_b32 v174, v168, v172
	s_waitcnt lgkmcnt(2)
	v_add_f32_e32 v178, v178, v192
	v_mov_b32_e32 v206, v209
	v_mov_b32_e32 v207, v210
	v_mov_b32_e32 v209, v211
	ds_bpermute_b32 v192, v168, v178
	v_pk_add_f32 v[200:201], v[206:207], v[208:209]
	s_waitcnt lgkmcnt(2)
	v_add_f32_e32 v182, v182, v194
	v_add_f32_e32 v193, v200, v201
	ds_bpermute_b32 v200, v168, v182
	ds_bpermute_b32 v195, v160, v193
	s_waitcnt lgkmcnt(3)
	v_add_f32_e32 v172, v172, v174
	v_fmamk_f32 v172, v172, 0x3a800000, v1
	s_waitcnt lgkmcnt(2)
	v_add_f32_e32 v174, v178, v192
	v_rsq_f32_e32 v192, v172
	v_fmamk_f32 v172, v174, 0x3a800000, v1
	v_rsq_f32_e32 v194, v172
	s_waitcnt lgkmcnt(1)
	v_add_f32_e32 v172, v182, v200
	v_mov_b32_e32 v200, v213
	v_mov_b32_e32 v201, v214
	v_mov_b32_e32 v213, v215
	v_pk_add_f32 v[200:201], v[200:201], v[212:213]
	s_waitcnt lgkmcnt(0)
	v_add_f32_e32 v174, v193, v195
	v_add_f32_e32 v193, v200, v201
	ds_bpermute_b32 v178, v168, v174
	ds_bpermute_b32 v195, v160, v193
	v_fmamk_f32 v172, v172, 0x3a800000, v1
	v_rsq_f32_e32 v182, v172
	v_mov_b32_e32 v200, v217
	s_waitcnt lgkmcnt(1)
	v_add_f32_e32 v172, v174, v178
	s_waitcnt lgkmcnt(0)
	v_add_f32_e32 v174, v193, v195
	v_mov_b32_e32 v201, v218
	v_mov_b32_e32 v217, v219
	ds_bpermute_b32 v193, v168, v174
	v_pk_add_f32 v[200:201], v[200:201], v[216:217]
	v_fmamk_f32 v172, v172, 0x3a800000, v1
	v_add_f32_e32 v195, v200, v201
	ds_bpermute_b32 v200, v160, v195
	v_rsq_f32_e32 v178, v172
	s_waitcnt lgkmcnt(1)
	v_add_f32_e32 v172, v174, v193
	v_fmamk_f32 v172, v172, 0x3a800000, v1
	v_rsq_f32_e32 v174, v172
	s_waitcnt lgkmcnt(0)
	v_add_f32_e32 v172, v195, v200
	v_mov_b32_e32 v200, v221
	v_mov_b32_e32 v201, v222
	v_mov_b32_e32 v221, v223
	v_pk_add_f32 v[200:201], v[200:201], v[220:221]
	ds_bpermute_b32 v193, v168, v172
	v_add_f32_e32 v195, v200, v201
	v_mov_b32_e32 v200, v225
	v_mov_b32_e32 v201, v226
	v_mov_b32_e32 v225, v227
	v_pk_add_f32 v[200:201], v[200:201], v[224:225]
	ds_bpermute_b32 v202, v160, v195
	v_add_f32_e32 v200, v200, v201
	ds_bpermute_b32 v160, v160, v200
	s_waitcnt lgkmcnt(2)
	v_add_f32_e32 v172, v172, v193
	v_pk_fma_f32 v[94:95], v[94:95], v[182:183], v[144:145] op_sel_hi:[1,0,1]
	s_waitcnt lgkmcnt(1)
	v_add_f32_e32 v193, v195, v202
	ds_bpermute_b32 v195, v168, v193
	s_waitcnt lgkmcnt(1)
	v_add_f32_e32 v160, v200, v160
	ds_bpermute_b32 v200, v168, v160
	v_pk_fma_f32 v[128:129], v[128:129], v[192:193], v[144:145] op_sel_hi:[1,0,1]
	v_pk_fma_f32 v[130:131], v[130:131], v[192:193], v[146:147] op_sel_hi:[1,0,1]
	v_pk_fma_f32 v[126:127], v[126:127], v[192:193], v[142:143] op_sel_hi:[1,0,1]
	v_pk_fma_f32 v[124:125], v[124:125], v[192:193], v[140:141] op_sel_hi:[1,0,1]
	v_max_f32_e32 v128, 0, v128
	v_max_f32_e32 v129, 0, v129
	s_waitcnt lgkmcnt(0)
	v_add_f32_e32 v160, v160, v200
	v_lshlrev_b64 v[200:201], 13, v[162:163]
	v_max_f32_e32 v124, 0, v124
	v_max_f32_e32 v125, 0, v125
	v_max_f32_e32 v130, 0, v130
	v_max_f32_e32 v126, 0, v126
	v_max_f32_e32 v131, 0, v131
	v_max_f32_e32 v127, 0, v127
	v_pk_mul_f32 v[128:129], v[128:129], v[128:129]
	v_lshlrev_b64 v[162:163], 1, v[238:239]
	v_pk_mul_f32 v[130:131], v[130:131], v[130:131]
	v_pk_mul_f32 v[202:203], v[126:127], v[126:127]
	v_pk_mul_f32 v[126:127], v[124:125], v[124:125]
	v_cvt_pk_bf16_f32 v124, v128, v129
	v_lshl_add_u64 v[128:129], s[24:25], 0, v[200:201]
	v_pk_fma_f32 v[122:123], v[122:123], v[192:193], v[138:139] op_sel_hi:[1,0,1]
	v_pk_fma_f32 v[120:121], v[120:121], v[192:193], v[136:137] op_sel_hi:[1,0,1]
	v_pk_fma_f32 v[118:119], v[118:119], v[192:193], v[134:135] op_sel_hi:[1,0,1]
	v_pk_fma_f32 v[116:117], v[116:117], v[192:193], v[132:133] op_sel_hi:[1,0,1]
	v_cvt_pk_bf16_f32 v125, v130, v131
	v_cvt_pk_bf16_f32 v126, v126, v127
	v_cvt_pk_bf16_f32 v127, v202, v203
	v_lshl_add_u64 v[128:129], v[128:129], 0, v[162:163]
	v_max_f32_e32 v120, 0, v120
	v_max_f32_e32 v116, 0, v116
	v_max_f32_e32 v121, 0, v121
	v_max_f32_e32 v117, 0, v117
	v_max_f32_e32 v122, 0, v122
	v_max_f32_e32 v118, 0, v118
	v_max_f32_e32 v123, 0, v123
	v_max_f32_e32 v119, 0, v119
	s_cbranch_vccnz .Lmy_wt_g3_0
	global_store_dwordx4 v[128:129], v[124:127], off
.Lmy_wt_g3_0r:
	v_pk_mul_f32 v[122:123], v[122:123], v[122:123]
	v_pk_mul_f32 v[120:121], v[120:121], v[120:121]
	v_pk_mul_f32 v[124:125], v[118:119], v[118:119]
	v_pk_mul_f32 v[118:119], v[116:117], v[116:117]
	v_pk_fma_f32 v[112:113], v[112:113], v[194:195], v[144:145] op_sel_hi:[1,0,1]
	v_cvt_pk_bf16_f32 v116, v120, v121
	v_cvt_pk_bf16_f32 v117, v122, v123
	v_cvt_pk_bf16_f32 v118, v118, v119
	v_cvt_pk_bf16_f32 v119, v124, v125
	v_pk_fma_f32 v[114:115], v[114:115], v[194:195], v[146:147] op_sel_hi:[1,0,1]
	v_pk_fma_f32 v[110:111], v[110:111], v[194:195], v[142:143] op_sel_hi:[1,0,1]
	v_pk_fma_f32 v[108:109], v[108:109], v[194:195], v[140:141] op_sel_hi:[1,0,1]
	v_max_f32_e32 v112, 0, v112
	v_max_f32_e32 v113, 0, v113
	s_cbranch_vccnz .Lmy_wt_g3_1
	global_store_dwordx4 v[128:129], v[116:119], off offset:256
.Lmy_wt_g3_1r:
	v_max_f32_e32 v108, 0, v108
	v_max_f32_e32 v109, 0, v109
	v_lshlrev_b64 v[116:117], 13, v[180:181]
	v_max_f32_e32 v114, 0, v114
	v_max_f32_e32 v110, 0, v110
	v_max_f32_e32 v115, 0, v115
	v_max_f32_e32 v111, 0, v111
	v_pk_mul_f32 v[112:113], v[112:113], v[112:113]
	v_pk_mul_f32 v[114:115], v[114:115], v[114:115]
	v_pk_mul_f32 v[118:119], v[110:111], v[110:111]
	v_pk_mul_f32 v[110:111], v[108:109], v[108:109]
	v_cvt_pk_bf16_f32 v108, v112, v113
	v_lshl_add_u64 v[112:113], s[24:25], 0, v[116:117]
	v_pk_fma_f32 v[106:107], v[106:107], v[194:195], v[138:139] op_sel_hi:[1,0,1]
	v_pk_fma_f32 v[104:105], v[104:105], v[194:195], v[136:137] op_sel_hi:[1,0,1]
	v_pk_fma_f32 v[102:103], v[102:103], v[194:195], v[134:135] op_sel_hi:[1,0,1]
	v_pk_fma_f32 v[100:101], v[100:101], v[194:195], v[132:133] op_sel_hi:[1,0,1]
	v_cvt_pk_bf16_f32 v109, v114, v115
	v_cvt_pk_bf16_f32 v110, v110, v111
	v_cvt_pk_bf16_f32 v111, v118, v119
	v_lshl_add_u64 v[112:113], v[112:113], 0, v[162:163]
	v_max_f32_e32 v104, 0, v104
	v_max_f32_e32 v100, 0, v100
	v_max_f32_e32 v105, 0, v105
	v_max_f32_e32 v101, 0, v101
	v_max_f32_e32 v106, 0, v106
	v_max_f32_e32 v102, 0, v102
	v_max_f32_e32 v107, 0, v107
	v_max_f32_e32 v103, 0, v103
	s_cbranch_vccnz .Lmy_wt_g3_2
	global_store_dwordx4 v[112:113], v[108:111], off
.Lmy_wt_g3_2r:
	v_pk_mul_f32 v[106:107], v[106:107], v[106:107]
	v_pk_mul_f32 v[104:105], v[104:105], v[104:105]
	v_pk_mul_f32 v[108:109], v[102:103], v[102:103]
	v_pk_mul_f32 v[102:103], v[100:101], v[100:101]
	v_cvt_pk_bf16_f32 v100, v104, v105
	v_cvt_pk_bf16_f32 v101, v106, v107
	v_cvt_pk_bf16_f32 v102, v102, v103
	v_cvt_pk_bf16_f32 v103, v108, v109
	v_pk_fma_f32 v[96:97], v[96:97], v[182:183], v[146:147] op_sel_hi:[1,0,1]
	v_pk_fma_f32 v[92:93], v[92:93], v[182:183], v[142:143] op_sel_hi:[1,0,1]
	v_pk_fma_f32 v[90:91], v[90:91], v[182:183], v[140:141] op_sel_hi:[1,0,1]
	v_max_f32_e32 v94, 0, v94
	v_max_f32_e32 v95, 0, v95
	s_cbranch_vccnz .Lmy_wt_g3_3
	global_store_dwordx4 v[112:113], v[100:103], off offset:256
.Lmy_wt_g3_3r:
	v_max_f32_e32 v90, 0, v90
	v_max_f32_e32 v91, 0, v91
	v_lshlrev_b64 v[100:101], 13, v[176:177]
	v_max_f32_e32 v96, 0, v96
	v_max_f32_e32 v92, 0, v92
	v_max_f32_e32 v97, 0, v97
	v_max_f32_e32 v93, 0, v93
	v_pk_mul_f32 v[94:95], v[94:95], v[94:95]
	v_pk_mul_f32 v[96:97], v[96:97], v[96:97]
	v_pk_mul_f32 v[102:103], v[92:93], v[92:93]
	v_pk_mul_f32 v[92:93], v[90:91], v[90:91]
	v_cvt_pk_bf16_f32 v90, v94, v95
	v_lshl_add_u64 v[94:95], s[24:25], 0, v[100:101]
	v_pk_fma_f32 v[88:89], v[88:89], v[182:183], v[138:139] op_sel_hi:[1,0,1]
	v_pk_fma_f32 v[86:87], v[86:87], v[182:183], v[136:137] op_sel_hi:[1,0,1]
	v_pk_fma_f32 v[84:85], v[84:85], v[182:183], v[134:135] op_sel_hi:[1,0,1]
	v_pk_fma_f32 v[82:83], v[82:83], v[182:183], v[132:133] op_sel_hi:[1,0,1]
	v_cvt_pk_bf16_f32 v91, v96, v97
	v_cvt_pk_bf16_f32 v92, v92, v93
	v_cvt_pk_bf16_f32 v93, v102, v103
	v_lshl_add_u64 v[94:95], v[94:95], 0, v[162:163]
	v_max_f32_e32 v86, 0, v86
	v_max_f32_e32 v82, 0, v82
	v_max_f32_e32 v87, 0, v87
	v_max_f32_e32 v83, 0, v83
	v_max_f32_e32 v88, 0, v88
	v_max_f32_e32 v84, 0, v84
	v_max_f32_e32 v89, 0, v89
	v_max_f32_e32 v85, 0, v85
	s_cbranch_vccnz .Lmy_wt_g3_4
	global_store_dwordx4 v[94:95], v[90:93], off
.Lmy_wt_g3_4r:
	v_pk_mul_f32 v[88:89], v[88:89], v[88:89]
	v_pk_mul_f32 v[86:87], v[86:87], v[86:87]
	v_pk_mul_f32 v[90:91], v[84:85], v[84:85]
	v_pk_mul_f32 v[84:85], v[82:83], v[82:83]
	v_pk_fma_f32 v[78:79], v[78:79], v[178:179], v[144:145] op_sel_hi:[1,0,1]
	v_cvt_pk_bf16_f32 v82, v86, v87
	v_cvt_pk_bf16_f32 v83, v88, v89
	v_cvt_pk_bf16_f32 v84, v84, v85
	v_cvt_pk_bf16_f32 v85, v90, v91
	v_pk_fma_f32 v[80:81], v[80:81], v[178:179], v[146:147] op_sel_hi:[1,0,1]
	v_pk_fma_f32 v[76:77], v[76:77], v[178:179], v[142:143] op_sel_hi:[1,0,1]
	v_pk_fma_f32 v[74:75], v[74:75], v[178:179], v[140:141] op_sel_hi:[1,0,1]
	v_max_f32_e32 v78, 0, v78
	v_max_f32_e32 v79, 0, v79
	s_cbranch_vccnz .Lmy_wt_g3_5
	global_store_dwordx4 v[94:95], v[82:85], off offset:256
.Lmy_wt_g3_5r:
	v_max_f32_e32 v74, 0, v74
	v_max_f32_e32 v75, 0, v75
	v_lshlrev_b64 v[82:83], 13, v[170:171]
	v_max_f32_e32 v80, 0, v80
	v_max_f32_e32 v76, 0, v76
	v_max_f32_e32 v81, 0, v81
	v_max_f32_e32 v77, 0, v77
	v_pk_mul_f32 v[78:79], v[78:79], v[78:79]
	v_pk_mul_f32 v[80:81], v[80:81], v[80:81]
	v_pk_mul_f32 v[84:85], v[76:77], v[76:77]
	v_pk_mul_f32 v[76:77], v[74:75], v[74:75]
	v_cvt_pk_bf16_f32 v74, v78, v79
	v_lshl_add_u64 v[78:79], s[24:25], 0, v[82:83]
	v_pk_fma_f32 v[72:73], v[72:73], v[178:179], v[138:139] op_sel_hi:[1,0,1]
	v_pk_fma_f32 v[70:71], v[70:71], v[178:179], v[136:137] op_sel_hi:[1,0,1]
	v_pk_fma_f32 v[68:69], v[68:69], v[178:179], v[134:135] op_sel_hi:[1,0,1]
	v_pk_fma_f32 v[66:67], v[66:67], v[178:179], v[132:133] op_sel_hi:[1,0,1]
	v_cvt_pk_bf16_f32 v75, v80, v81
	v_cvt_pk_bf16_f32 v76, v76, v77
	v_cvt_pk_bf16_f32 v77, v84, v85
	v_lshl_add_u64 v[78:79], v[78:79], 0, v[162:163]
	v_max_f32_e32 v70, 0, v70
	v_max_f32_e32 v66, 0, v66
	v_max_f32_e32 v71, 0, v71
	v_max_f32_e32 v67, 0, v67
	v_max_f32_e32 v72, 0, v72
	v_max_f32_e32 v68, 0, v68
	v_max_f32_e32 v73, 0, v73
	v_max_f32_e32 v69, 0, v69
	v_fmamk_f32 v172, v172, 0x3a800000, v1
	s_cbranch_vccnz .Lmy_wt_g3_6
	global_store_dwordx4 v[78:79], v[74:77], off
.Lmy_wt_g3_6r:
	v_pk_mul_f32 v[72:73], v[72:73], v[72:73]
	v_pk_mul_f32 v[70:71], v[70:71], v[70:71]
	v_pk_mul_f32 v[74:75], v[68:69], v[68:69]
	v_pk_mul_f32 v[68:69], v[66:67], v[66:67]
	v_pk_fma_f32 v[62:63], v[62:63], v[174:175], v[144:145] op_sel_hi:[1,0,1]
	v_rsq_f32_e32 v172, v172
	v_cvt_pk_bf16_f32 v66, v70, v71
	v_cvt_pk_bf16_f32 v67, v72, v73
	v_cvt_pk_bf16_f32 v68, v68, v69
	v_cvt_pk_bf16_f32 v69, v74, v75
	v_pk_fma_f32 v[64:65], v[64:65], v[174:175], v[146:147] op_sel_hi:[1,0,1]
	v_pk_fma_f32 v[60:61], v[60:61], v[174:175], v[142:143] op_sel_hi:[1,0,1]
	v_pk_fma_f32 v[58:59], v[58:59], v[174:175], v[140:141] op_sel_hi:[1,0,1]
	v_max_f32_e32 v62, 0, v62
	v_max_f32_e32 v63, 0, v63
	s_cbranch_vccnz .Lmy_wt_g3_7
	global_store_dwordx4 v[78:79], v[66:69], off offset:256
.Lmy_wt_g3_7r:
	v_max_f32_e32 v58, 0, v58
	v_max_f32_e32 v59, 0, v59
	v_lshlrev_b64 v[66:67], 13, v[166:167]
	v_max_f32_e32 v64, 0, v64
	v_max_f32_e32 v60, 0, v60
	v_max_f32_e32 v65, 0, v65
	v_max_f32_e32 v61, 0, v61
	v_pk_mul_f32 v[62:63], v[62:63], v[62:63]
	v_pk_mul_f32 v[64:65], v[64:65], v[64:65]
	v_pk_mul_f32 v[68:69], v[60:61], v[60:61]
	v_pk_mul_f32 v[60:61], v[58:59], v[58:59]
	v_cvt_pk_bf16_f32 v58, v62, v63
	v_lshl_add_u64 v[62:63], s[24:25], 0, v[66:67]
	v_pk_fma_f32 v[56:57], v[56:57], v[174:175], v[138:139] op_sel_hi:[1,0,1]
	v_pk_fma_f32 v[54:55], v[54:55], v[174:175], v[136:137] op_sel_hi:[1,0,1]
	v_pk_fma_f32 v[52:53], v[52:53], v[174:175], v[134:135] op_sel_hi:[1,0,1]
	v_pk_fma_f32 v[50:51], v[50:51], v[174:175], v[132:133] op_sel_hi:[1,0,1]
	v_add_f32_e32 v168, v193, v195
	v_cvt_pk_bf16_f32 v59, v64, v65
	v_cvt_pk_bf16_f32 v60, v60, v61
	v_cvt_pk_bf16_f32 v61, v68, v69
	v_lshl_add_u64 v[62:63], v[62:63], 0, v[162:163]
	v_max_f32_e32 v54, 0, v54
	v_max_f32_e32 v50, 0, v50
	v_max_f32_e32 v55, 0, v55
	v_max_f32_e32 v51, 0, v51
	v_max_f32_e32 v56, 0, v56
	v_max_f32_e32 v52, 0, v52
	v_max_f32_e32 v57, 0, v57
	v_max_f32_e32 v53, 0, v53
	v_fmamk_f32 v168, v168, 0x3a800000, v1
	s_cbranch_vccnz .Lmy_wt_g3_8
	global_store_dwordx4 v[62:63], v[58:61], off
.Lmy_wt_g3_8r:
	v_pk_mul_f32 v[56:57], v[56:57], v[56:57]
	v_pk_mul_f32 v[54:55], v[54:55], v[54:55]
	v_pk_mul_f32 v[58:59], v[52:53], v[52:53]
	v_pk_mul_f32 v[52:53], v[50:51], v[50:51]
	v_pk_fma_f32 v[46:47], v[46:47], v[172:173], v[144:145] op_sel_hi:[1,0,1]
	v_rsq_f32_e32 v168, v168
	v_cvt_pk_bf16_f32 v50, v54, v55
	v_cvt_pk_bf16_f32 v51, v56, v57
	v_cvt_pk_bf16_f32 v52, v52, v53
	v_cvt_pk_bf16_f32 v53, v58, v59
	v_pk_fma_f32 v[48:49], v[48:49], v[172:173], v[146:147] op_sel_hi:[1,0,1]
	v_pk_fma_f32 v[44:45], v[44:45], v[172:173], v[142:143] op_sel_hi:[1,0,1]
	v_pk_fma_f32 v[42:43], v[42:43], v[172:173], v[140:141] op_sel_hi:[1,0,1]
	v_max_f32_e32 v46, 0, v46
	v_max_f32_e32 v47, 0, v47
	s_cbranch_vccnz .Lmy_wt_g3_9
	global_store_dwordx4 v[62:63], v[50:53], off offset:256
.Lmy_wt_g3_9r:
	v_max_f32_e32 v42, 0, v42
	v_max_f32_e32 v43, 0, v43
	v_lshlrev_b64 v[50:51], 13, v[164:165]
	v_max_f32_e32 v48, 0, v48
	v_max_f32_e32 v44, 0, v44
	v_max_f32_e32 v49, 0, v49
	v_max_f32_e32 v45, 0, v45
	v_pk_mul_f32 v[46:47], v[46:47], v[46:47]
	v_pk_mul_f32 v[48:49], v[48:49], v[48:49]
	v_pk_mul_f32 v[52:53], v[44:45], v[44:45]
	v_pk_mul_f32 v[44:45], v[42:43], v[42:43]
	v_cvt_pk_bf16_f32 v42, v46, v47
	v_lshl_add_u64 v[46:47], s[24:25], 0, v[50:51]
	v_pk_fma_f32 v[40:41], v[40:41], v[172:173], v[138:139] op_sel_hi:[1,0,1]
	v_pk_fma_f32 v[38:39], v[38:39], v[172:173], v[136:137] op_sel_hi:[1,0,1]
	v_pk_fma_f32 v[36:37], v[36:37], v[172:173], v[134:135] op_sel_hi:[1,0,1]
	v_pk_fma_f32 v[34:35], v[34:35], v[172:173], v[132:133] op_sel_hi:[1,0,1]
	v_cvt_pk_bf16_f32 v43, v48, v49
	v_cvt_pk_bf16_f32 v44, v44, v45
	v_cvt_pk_bf16_f32 v45, v52, v53
	v_lshl_add_u64 v[46:47], v[46:47], 0, v[162:163]
	v_max_f32_e32 v38, 0, v38
	v_max_f32_e32 v34, 0, v34
	v_max_f32_e32 v39, 0, v39
	v_max_f32_e32 v35, 0, v35
	v_max_f32_e32 v40, 0, v40
	v_max_f32_e32 v36, 0, v36
	v_max_f32_e32 v41, 0, v41
	v_max_f32_e32 v37, 0, v37
	v_fmamk_f32 v160, v160, 0x3a800000, v1
	s_cbranch_vccnz .Lmy_wt_g3_10
	global_store_dwordx4 v[46:47], v[42:45], off
.Lmy_wt_g3_10r:
	v_pk_mul_f32 v[40:41], v[40:41], v[40:41]
	v_pk_mul_f32 v[38:39], v[38:39], v[38:39]
	v_pk_mul_f32 v[42:43], v[36:37], v[36:37]
	v_pk_mul_f32 v[36:37], v[34:35], v[34:35]
	v_pk_fma_f32 v[30:31], v[30:31], v[168:169], v[144:145] op_sel_hi:[1,0,1]
	v_rsq_f32_e32 v160, v160
	v_cvt_pk_bf16_f32 v34, v38, v39
	v_cvt_pk_bf16_f32 v35, v40, v41
	v_cvt_pk_bf16_f32 v36, v36, v37
	v_cvt_pk_bf16_f32 v37, v42, v43
	v_pk_fma_f32 v[32:33], v[32:33], v[168:169], v[146:147] op_sel_hi:[1,0,1]
	v_pk_fma_f32 v[28:29], v[28:29], v[168:169], v[142:143] op_sel_hi:[1,0,1]
	v_pk_fma_f32 v[26:27], v[26:27], v[168:169], v[140:141] op_sel_hi:[1,0,1]
	v_max_f32_e32 v30, 0, v30
	v_max_f32_e32 v31, 0, v31
	s_cbranch_vccnz .Lmy_wt_g3_11
	global_store_dwordx4 v[46:47], v[34:37], off offset:256
.Lmy_wt_g3_11r:
	v_max_f32_e32 v26, 0, v26
	v_max_f32_e32 v27, 0, v27
	v_lshlrev_b64 v[34:35], 13, v[158:159]
	v_max_f32_e32 v32, 0, v32
	v_max_f32_e32 v28, 0, v28
	v_max_f32_e32 v33, 0, v33
	v_max_f32_e32 v29, 0, v29
	v_pk_mul_f32 v[30:31], v[30:31], v[30:31]
	v_pk_mul_f32 v[32:33], v[32:33], v[32:33]
	v_pk_mul_f32 v[36:37], v[28:29], v[28:29]
	v_pk_mul_f32 v[28:29], v[26:27], v[26:27]
	v_cvt_pk_bf16_f32 v26, v30, v31
	v_lshl_add_u64 v[30:31], s[24:25], 0, v[34:35]
	v_pk_fma_f32 v[24:25], v[24:25], v[168:169], v[138:139] op_sel_hi:[1,0,1]
	v_pk_fma_f32 v[22:23], v[22:23], v[168:169], v[136:137] op_sel_hi:[1,0,1]
	v_pk_fma_f32 v[20:21], v[20:21], v[168:169], v[134:135] op_sel_hi:[1,0,1]
	v_pk_fma_f32 v[18:19], v[18:19], v[168:169], v[132:133] op_sel_hi:[1,0,1]
	v_cvt_pk_bf16_f32 v27, v32, v33
	v_cvt_pk_bf16_f32 v28, v28, v29
	v_cvt_pk_bf16_f32 v29, v36, v37
	v_lshl_add_u64 v[30:31], v[30:31], 0, v[162:163]
	v_max_f32_e32 v22, 0, v22
	v_max_f32_e32 v18, 0, v18
	v_max_f32_e32 v23, 0, v23
	v_max_f32_e32 v19, 0, v19
	v_max_f32_e32 v24, 0, v24
	v_max_f32_e32 v20, 0, v20
	v_max_f32_e32 v25, 0, v25
	v_max_f32_e32 v21, 0, v21
	s_cbranch_vccnz .Lmy_wt_g3_12
	global_store_dwordx4 v[30:31], v[26:29], off
.Lmy_wt_g3_12r:
	v_pk_mul_f32 v[24:25], v[24:25], v[24:25]
	v_pk_mul_f32 v[22:23], v[22:23], v[22:23]
	v_pk_mul_f32 v[26:27], v[20:21], v[20:21]
	v_pk_mul_f32 v[20:21], v[18:19], v[18:19]
	v_pk_fma_f32 v[14:15], v[14:15], v[160:161], v[144:145] op_sel_hi:[1,0,1]
	v_cvt_pk_bf16_f32 v18, v22, v23
	v_cvt_pk_bf16_f32 v19, v24, v25
	v_cvt_pk_bf16_f32 v20, v20, v21
	v_cvt_pk_bf16_f32 v21, v26, v27
	v_pk_fma_f32 v[16:17], v[16:17], v[160:161], v[146:147] op_sel_hi:[1,0,1]
	v_pk_fma_f32 v[12:13], v[12:13], v[160:161], v[142:143] op_sel_hi:[1,0,1]
	v_pk_fma_f32 v[10:11], v[10:11], v[160:161], v[140:141] op_sel_hi:[1,0,1]
	v_max_f32_e32 v14, 0, v14
	v_max_f32_e32 v15, 0, v15
	s_cbranch_vccnz .Lmy_wt_g3_13
	global_store_dwordx4 v[30:31], v[18:21], off offset:256
.Lmy_wt_g3_13r:
	v_max_f32_e32 v10, 0, v10
	v_max_f32_e32 v11, 0, v11
	v_lshlrev_b64 v[18:19], 13, v[156:157]
	v_max_f32_e32 v16, 0, v16
	v_max_f32_e32 v12, 0, v12
	v_max_f32_e32 v17, 0, v17
	v_max_f32_e32 v13, 0, v13
	v_pk_mul_f32 v[14:15], v[14:15], v[14:15]
	v_pk_mul_f32 v[16:17], v[16:17], v[16:17]
	v_pk_mul_f32 v[20:21], v[12:13], v[12:13]
	v_pk_mul_f32 v[12:13], v[10:11], v[10:11]
	v_cvt_pk_bf16_f32 v10, v14, v15
	v_lshl_add_u64 v[14:15], s[24:25], 0, v[18:19]
	v_pk_fma_f32 v[8:9], v[8:9], v[160:161], v[138:139] op_sel_hi:[1,0,1]
	v_pk_fma_f32 v[6:7], v[6:7], v[160:161], v[136:137] op_sel_hi:[1,0,1]
	v_pk_fma_f32 v[4:5], v[4:5], v[160:161], v[134:135] op_sel_hi:[1,0,1]
	v_pk_fma_f32 v[2:3], v[2:3], v[160:161], v[132:133] op_sel_hi:[1,0,1]
	v_cvt_pk_bf16_f32 v11, v16, v17
	v_cvt_pk_bf16_f32 v12, v12, v13
	v_cvt_pk_bf16_f32 v13, v20, v21
	v_lshl_add_u64 v[14:15], v[14:15], 0, v[162:163]
	v_max_f32_e32 v6, 0, v6
	v_max_f32_e32 v2, 0, v2
	v_max_f32_e32 v7, 0, v7
	v_max_f32_e32 v3, 0, v3
	v_max_f32_e32 v8, 0, v8
	v_max_f32_e32 v4, 0, v4
	v_max_f32_e32 v9, 0, v9
	v_max_f32_e32 v5, 0, v5
	s_cbranch_vccnz .Lmy_wt_g3_14
	global_store_dwordx4 v[14:15], v[10:13], off
.Lmy_wt_g3_14r:
	v_pk_mul_f32 v[8:9], v[8:9], v[8:9]
	v_pk_mul_f32 v[6:7], v[6:7], v[6:7]
	v_pk_mul_f32 v[10:11], v[4:5], v[4:5]
	v_pk_mul_f32 v[4:5], v[2:3], v[2:3]
	v_cvt_pk_bf16_f32 v2, v6, v7
	v_cvt_pk_bf16_f32 v3, v8, v9
	v_cvt_pk_bf16_f32 v4, v4, v5
	v_cvt_pk_bf16_f32 v5, v10, v11
	s_cbranch_vccnz .Lmy_wt_g3_15
	global_store_dwordx4 v[14:15], v[2:5], off offset:256
.Lmy_wt_g3_15r:
	s_cbranch_vccnz .LBB0_1003
	s_andn2_b64 vcc, exec, s[10:11]
	s_cbranch_vccnz .LBB0_1002
	s_barrier
	s_branch .LBB0_1002

.Lmy_wt_g3_1:
	global_store_dwordx4 v[128:129], v[116:119], off offset:256 sc1
	s_branch .Lmy_wt_g3_1r

.Lmy_wt_g3_3:
	global_store_dwordx4 v[112:113], v[100:103], off offset:256 sc1
	s_branch .Lmy_wt_g3_3r

.Lmy_wt_g3_5:
	global_store_dwordx4 v[94:95], v[82:85], off offset:256 sc1
	s_branch .Lmy_wt_g3_5r

.Lmy_wt_g3_9:
	global_store_dwordx4 v[62:63], v[50:53], off offset:256 sc1
	s_branch .Lmy_wt_g3_9r

.Lmy_wt_g3_11:
	global_store_dwordx4 v[46:47], v[34:37], off offset:256 sc1
	s_branch .Lmy_wt_g3_11r

.Lmy_wt_g3_13:
	global_store_dwordx4 v[30:31], v[18:21], off offset:256 sc1
	s_branch .Lmy_wt_g3_13r

.LBB0_1119:
	s_lshl_b32 s4, s70, 8
	v_add_u32_e32 v194, s4, v204
	s_addk_i32 s4, 0xc000
	s_lshr_b32 s4, s4, 12
	s_ashr_i32 s5, s70, 5
	s_add_i32 s4, s4, 2
	s_cmp_lt_i32 s70, 64
	v_lshl_or_b32 v178, s20, 8, v206
	s_cselect_b32 s4, s5, s4
	v_ashrrev_i32_e32 v179, 31, v178
	s_ashr_i32 s5, s4, 31
	v_lshlrev_b64 v[180:181], 1, v[178:179]
	v_ashrrev_i32_e32 v195, 31, v194
	s_lshl_b64 s[4:5], s[4:5], 14
	v_lshl_add_u64 v[148:149], s[82:83], 0, v[180:181]
	v_lshlrev_b64 v[214:215], 11, v[194:195]
	s_add_u32 s4, s89, s4
	v_lshl_add_u64 v[112:113], v[148:149], 0, v[214:215]
	s_addc_u32 s5, s90, s5
	global_load_dwordx4 v[200:203], v[112:113], off
	global_load_dwordx4 v[210:213], v[112:113], off offset:256
	v_lshl_add_u64 v[112:113], v[178:179], 2, s[4:5]
	global_load_dwordx4 v[128:131], v[112:113], off
	global_load_dwordx4 v[124:127], v[112:113], off offset:16
	global_load_dwordx4 v[116:119], v[112:113], off offset:512
	s_nop 0
	global_load_dwordx4 v[112:115], v[112:113], off offset:528
	v_or_b32_e32 v190, 16, v194
	v_or_b32_e32 v186, 32, v194
	v_or_b32_e32 v182, 48, v194
	v_ashrrev_i32_e32 v191, 31, v190
	v_ashrrev_i32_e32 v187, 31, v186
	v_ashrrev_i32_e32 v183, 31, v182
	v_lshlrev_b64 v[192:193], 11, v[190:191]
	v_lshlrev_b64 v[188:189], 11, v[186:187]
	v_lshlrev_b64 v[184:185], 11, v[182:183]
	v_lshl_add_u64 v[150:151], v[148:149], 0, v[192:193]
	v_lshl_add_u64 v[152:153], v[148:149], 0, v[188:189]
	v_lshl_add_u64 v[148:149], v[148:149], 0, v[184:185]
	global_load_dwordx4 v[168:171], v[150:151], off
	global_load_dwordx4 v[164:167], v[150:151], off offset:256
	global_load_dwordx4 v[160:163], v[152:153], off
	global_load_dwordx4 v[156:159], v[152:153], off offset:256
	s_nop 0
	global_load_dwordx4 v[152:155], v[148:149], off
	s_nop 0
	global_load_dwordx4 v[148:151], v[148:149], off offset:256
	v_and_b32_e32 v209, 64, v229
	v_xor_b32_e32 v208, 16, v229
	v_add_u32_e32 v209, 64, v209
	v_xor_b32_e32 v216, 32, v229
	v_cmp_lt_i32_e32 vcc, v208, v209
	s_lshl_b32 s20, s20, 2
	s_ashr_i32 s21, s20, 31
	v_cndmask_b32_e32 v208, v229, v208, vcc
	v_cmp_lt_i32_e32 vcc, v216, v209
	v_lshlrev_b32_e32 v209, 2, v208
	s_waitcnt vmcnt(0)
	v_and_b32_e32 v217, 0xffff0000, v200
	v_cndmask_b32_e32 v216, v229, v216, vcc
	s_andn2_b64 vcc, exec, s[30:31]
	v_lshlrev_b32_e32 v208, 2, v216
	v_lshlrev_b32_e32 v216, 16, v200
	v_lshlrev_b32_e32 v200, 16, v201
	v_and_b32_e32 v201, 0xffff0000, v201
	v_lshlrev_b32_e32 v218, 16, v202
	v_and_b32_e32 v219, 0xffff0000, v202
	v_lshlrev_b32_e32 v202, 16, v203
	v_and_b32_e32 v203, 0xffff0000, v203
	v_lshlrev_b32_e32 v222, 16, v212
	v_and_b32_e32 v223, 0xffff0000, v212
	v_lshlrev_b32_e32 v212, 16, v213
	v_and_b32_e32 v213, 0xffff0000, v213
	v_lshlrev_b32_e32 v220, 16, v210
	v_and_b32_e32 v221, 0xffff0000, v210
	v_lshlrev_b32_e32 v210, 16, v211
	v_and_b32_e32 v211, 0xffff0000, v211
	v_pk_fma_f32 v[146:147], v[146:147], v[130:131], v[200:201]
	v_pk_fma_f32 v[142:143], v[142:143], v[126:127], v[202:203]
	v_pk_fma_f32 v[140:141], v[140:141], v[124:125], v[218:219]
	v_pk_fma_f32 v[200:201], v[134:135], v[114:115], v[212:213]
	v_pk_fma_f32 v[202:203], v[132:133], v[112:113], v[222:223]
	v_pk_fma_f32 v[144:145], v[144:145], v[128:129], v[216:217]
	v_pk_fma_f32 v[136:137], v[136:137], v[116:117], v[220:221]
	v_pk_fma_f32 v[138:139], v[138:139], v[118:119], v[210:211]
	v_pk_mul_f32 v[210:211], v[140:141], v[140:141]
	v_pk_mul_f32 v[212:213], v[142:143], v[142:143]
	v_cvt_pk_bf16_f32 v134, v140, v141
	v_cvt_pk_bf16_f32 v135, v142, v143
	v_pk_mul_f32 v[140:141], v[202:203], v[202:203]
	v_pk_mul_f32 v[142:143], v[200:201], v[200:201]
	v_cvt_pk_bf16_f32 v132, v144, v145
	v_cvt_pk_bf16_f32 v133, v146, v147
	v_pk_fma_f32 v[146:147], v[146:147], v[146:147], v[212:213]
	v_pk_fma_f32 v[144:145], v[144:145], v[144:145], v[210:211]
	v_pk_fma_f32 v[142:143], v[138:139], v[138:139], v[142:143]
	v_pk_fma_f32 v[140:141], v[136:137], v[136:137], v[140:141]
	v_add_f32_e32 v144, v144, v145
	v_add_f32_e32 v145, v146, v147
	v_add_f32_e32 v140, v140, v141
	v_add_f32_e32 v142, v142, v143
	v_add_f32_e32 v141, v144, v145
	v_add_f32_e32 v140, v140, v142
	v_add_f32_e32 v142, v141, v140
	ds_bpermute_b32 v143, v209, v142
	v_lshl_add_u64 v[140:141], s[22:23], 0, v[214:215]
	v_lshl_add_u64 v[140:141], v[140:141], 0, v[180:181]
	s_cbranch_vccnz .Lmy_wt_g4a_0
	global_store_dwordx4 v[140:141], v[132:135], off
.Lmy_wt_g4a_0r:
	s_waitcnt lgkmcnt(0)
	s_nop 0
	v_add_f32_e32 v132, v142, v143
	ds_bpermute_b32 v133, v208, v132
	v_cvt_pk_bf16_f32 v134, v136, v137
	v_cvt_pk_bf16_f32 v135, v138, v139
	v_cvt_pk_bf16_f32 v136, v202, v203
	v_cvt_pk_bf16_f32 v137, v200, v201
	s_cbranch_vccnz .Lmy_wt_g4a_1
	global_store_dwordx4 v[140:141], v[134:137], off offset:256
.Lmy_wt_g4a_1r:
	s_and_saveexec_b64 s[70:71], s[38:39]
	s_cbranch_execz .LBB0_1121
	v_lshlrev_b64 v[134:135], 6, v[194:195]
	v_lshl_add_u64 v[134:135], s[58:59], 0, v[134:135]
	v_lshl_add_u64 v[134:135], s[20:21], 2, v[134:135]
	s_lshl_b32 s48, s92, 2
	v_lshl_add_u64 v[134:135], v[134:135], 0, s[48:49]
	s_waitcnt lgkmcnt(0)
	v_add_f32_e32 v132, v132, v133
	global_store_dword v[134:135], v132, off
.LBB0_1121:
	s_or_b64 exec, exec, s[70:71]
	v_add_u32_e32 v140, 0x80, v194
	v_ashrrev_i32_e32 v141, 31, v140
	v_lshlrev_b64 v[142:143], 11, v[140:141]
	s_waitcnt lgkmcnt(0)
	v_lshl_add_u64 v[132:133], s[82:83], 0, v[142:143]
	v_lshl_add_u64 v[132:133], v[132:133], 0, v[180:181]
	global_load_dwordx4 v[136:139], v[132:133], off
	s_nop 0
	global_load_dwordx4 v[132:135], v[132:133], off offset:256
	v_lshlrev_b32_e32 v144, 16, v168
	v_and_b32_e32 v145, 0xffff0000, v168
	v_lshlrev_b32_e32 v146, 16, v169
	v_and_b32_e32 v147, 0xffff0000, v169
	v_lshlrev_b32_e32 v168, 16, v170
	v_and_b32_e32 v169, 0xffff0000, v170
	v_lshlrev_b32_e32 v170, 16, v171
	v_and_b32_e32 v171, 0xffff0000, v171
	v_pk_fma_f32 v[120:121], v[120:121], v[128:129], v[144:145]
	v_pk_fma_f32 v[144:145], v[110:111], v[126:127], v[170:171]
	v_pk_fma_f32 v[110:111], v[108:109], v[124:125], v[168:169]
	v_pk_fma_f32 v[122:123], v[122:123], v[130:131], v[146:147]
	v_pk_mul_f32 v[108:109], v[110:111], v[110:111]
	v_pk_mul_f32 v[146:147], v[144:145], v[144:145]
	v_pk_fma_f32 v[108:109], v[120:121], v[120:121], v[108:109]
	v_pk_fma_f32 v[146:147], v[122:123], v[122:123], v[146:147]
	v_add_f32_e32 v108, v108, v109
	v_add_f32_e32 v109, v146, v147
	v_add_f32_e32 v168, v108, v109
	v_cvt_pk_bf16_f32 v108, v120, v121
	v_cvt_pk_bf16_f32 v109, v122, v123
	v_cvt_pk_bf16_f32 v110, v110, v111
	v_cvt_pk_bf16_f32 v111, v144, v145
	v_lshlrev_b32_e32 v120, 16, v164
	v_and_b32_e32 v121, 0xffff0000, v164
	v_lshlrev_b32_e32 v122, 16, v165
	v_and_b32_e32 v123, 0xffff0000, v165
	v_lshlrev_b32_e32 v144, 16, v166
	v_and_b32_e32 v145, 0xffff0000, v166
	v_lshlrev_b32_e32 v146, 16, v167
	v_and_b32_e32 v147, 0xffff0000, v167
	v_pk_fma_f32 v[104:105], v[104:105], v[116:117], v[120:121]
	v_pk_fma_f32 v[106:107], v[106:107], v[118:119], v[122:123]
	v_pk_fma_f32 v[120:121], v[102:103], v[114:115], v[146:147]
	v_pk_fma_f32 v[122:123], v[100:101], v[112:113], v[144:145]
	v_pk_mul_f32 v[102:103], v[120:121], v[120:121]
	v_pk_mul_f32 v[100:101], v[122:123], v[122:123]
	v_pk_fma_f32 v[102:103], v[106:107], v[106:107], v[102:103]
	v_pk_fma_f32 v[100:101], v[104:105], v[104:105], v[100:101]
	s_nop 0
	v_add_f32_e32 v100, v100, v101
	v_add_f32_e32 v101, v102, v103
	v_add_f32_e32 v100, v100, v101
	v_add_f32_e32 v103, v168, v100
	ds_bpermute_b32 v146, v209, v103
	v_lshl_add_u64 v[100:101], s[22:23], 0, v[192:193]
	v_lshl_add_u64 v[144:145], v[100:101], 0, v[180:181]
	v_cvt_pk_bf16_f32 v102, v104, v105
	v_cvt_pk_bf16_f32 v104, v122, v123
	s_waitcnt lgkmcnt(0)
	v_add_f32_e32 v100, v103, v146
	ds_bpermute_b32 v101, v208, v100
	v_cvt_pk_bf16_f32 v103, v106, v107
	v_cvt_pk_bf16_f32 v105, v120, v121
	s_cbranch_vccnz .Lmy_wt_g4a_2
	global_store_dwordx4 v[144:145], v[108:111], off
.Lmy_wt_g4a_2r:
	s_cbranch_vccnz .Lmy_wt_g4a_3
	global_store_dwordx4 v[144:145], v[102:105], off offset:256
.Lmy_wt_g4a_3r:
	s_and_saveexec_b64 s[70:71], s[38:39]
	s_cbranch_execz .LBB0_1123
	v_lshlrev_b64 v[102:103], 6, v[190:191]
	v_lshl_add_u64 v[102:103], s[58:59], 0, v[102:103]
	v_lshl_add_u64 v[102:103], s[20:21], 2, v[102:103]
	s_lshl_b32 s48, s92, 2
	v_lshl_add_u64 v[102:103], v[102:103], 0, s[48:49]
	s_waitcnt lgkmcnt(0)
	v_add_f32_e32 v100, v100, v101
	global_store_dword v[102:103], v100, off
.LBB0_1123:
	s_or_b64 exec, exec, s[70:71]
	v_or_b32_e32 v108, 16, v140
	v_ashrrev_i32_e32 v109, 31, v108
	v_lshlrev_b64 v[110:111], 11, v[108:109]
	s_waitcnt lgkmcnt(0)
	v_lshl_add_u64 v[100:101], s[82:83], 0, v[110:111]
	v_lshl_add_u64 v[100:101], v[100:101], 0, v[180:181]
	global_load_dwordx4 v[104:107], v[100:101], off
	s_nop 0
	global_load_dwordx4 v[100:103], v[100:101], off offset:256
	v_lshlrev_b32_e32 v120, 16, v160
	v_and_b32_e32 v121, 0xffff0000, v160
	v_lshlrev_b32_e32 v144, 16, v162
	v_and_b32_e32 v145, 0xffff0000, v162
	v_lshlrev_b32_e32 v146, 16, v163
	v_and_b32_e32 v147, 0xffff0000, v163
	v_lshlrev_b32_e32 v122, 16, v161
	v_and_b32_e32 v123, 0xffff0000, v161
	v_pk_fma_f32 v[94:95], v[94:95], v[128:129], v[120:121]
	v_pk_fma_f32 v[120:121], v[92:93], v[126:127], v[146:147]
	v_pk_fma_f32 v[92:93], v[90:91], v[124:125], v[144:145]
	v_pk_fma_f32 v[96:97], v[96:97], v[130:131], v[122:123]
	v_pk_mul_f32 v[90:91], v[92:93], v[92:93]
	v_pk_mul_f32 v[122:123], v[120:121], v[120:121]
	v_pk_fma_f32 v[90:91], v[94:95], v[94:95], v[90:91]
	v_pk_fma_f32 v[122:123], v[96:97], v[96:97], v[122:123]
	v_add_f32_e32 v90, v90, v91
	v_add_f32_e32 v91, v122, v123
	v_add_f32_e32 v144, v90, v91
	v_cvt_pk_bf16_f32 v90, v94, v95
	v_cvt_pk_bf16_f32 v91, v96, v97
	v_cvt_pk_bf16_f32 v92, v92, v93
	v_cvt_pk_bf16_f32 v93, v120, v121
	v_lshlrev_b32_e32 v94, 16, v156
	v_and_b32_e32 v95, 0xffff0000, v156
	v_lshlrev_b32_e32 v96, 16, v157
	v_and_b32_e32 v97, 0xffff0000, v157
	v_lshlrev_b32_e32 v120, 16, v158
	v_and_b32_e32 v121, 0xffff0000, v158
	v_lshlrev_b32_e32 v122, 16, v159
	v_and_b32_e32 v123, 0xffff0000, v159
	v_pk_fma_f32 v[86:87], v[86:87], v[116:117], v[94:95]
	v_pk_fma_f32 v[88:89], v[88:89], v[118:119], v[96:97]
	v_pk_fma_f32 v[94:95], v[84:85], v[114:115], v[122:123]
	v_pk_fma_f32 v[96:97], v[82:83], v[112:113], v[120:121]
	v_pk_mul_f32 v[84:85], v[94:95], v[94:95]
	v_pk_mul_f32 v[82:83], v[96:97], v[96:97]
	v_pk_fma_f32 v[84:85], v[88:89], v[88:89], v[84:85]
	v_pk_fma_f32 v[82:83], v[86:87], v[86:87], v[82:83]
	s_nop 0
	v_add_f32_e32 v82, v82, v83
	v_add_f32_e32 v83, v84, v85
	v_add_f32_e32 v82, v82, v83
	v_add_f32_e32 v85, v144, v82
	ds_bpermute_b32 v122, v209, v85
	v_lshl_add_u64 v[82:83], s[22:23], 0, v[188:189]
	v_lshl_add_u64 v[120:121], v[82:83], 0, v[180:181]
	v_cvt_pk_bf16_f32 v84, v86, v87
	v_cvt_pk_bf16_f32 v86, v96, v97
	s_waitcnt lgkmcnt(0)
	v_add_f32_e32 v82, v85, v122
	ds_bpermute_b32 v83, v208, v82
	v_cvt_pk_bf16_f32 v85, v88, v89
	v_cvt_pk_bf16_f32 v87, v94, v95
	s_cbranch_vccnz .Lmy_wt_g4a_4
	global_store_dwordx4 v[120:121], v[90:93], off
.Lmy_wt_g4a_4r:
	s_cbranch_vccnz .Lmy_wt_g4a_5
	global_store_dwordx4 v[120:121], v[84:87], off offset:256
.Lmy_wt_g4a_5r:
	s_and_saveexec_b64 s[70:71], s[38:39]
	s_cbranch_execz .LBB0_1125
	v_lshlrev_b64 v[84:85], 6, v[186:187]
	v_lshl_add_u64 v[84:85], s[58:59], 0, v[84:85]
	v_lshl_add_u64 v[84:85], s[20:21], 2, v[84:85]
	s_lshl_b32 s48, s92, 2
	v_lshl_add_u64 v[84:85], v[84:85], 0, s[48:49]
	s_waitcnt lgkmcnt(0)
	v_add_f32_e32 v82, v82, v83
	global_store_dword v[84:85], v82, off
.LBB0_1125:
	s_or_b64 exec, exec, s[70:71]
	v_or_b32_e32 v90, 32, v140
	v_ashrrev_i32_e32 v91, 31, v90
	v_lshlrev_b64 v[92:93], 11, v[90:91]
	s_waitcnt lgkmcnt(0)
	v_lshl_add_u64 v[82:83], s[82:83], 0, v[92:93]
	v_lshl_add_u64 v[82:83], v[82:83], 0, v[180:181]
	global_load_dwordx4 v[86:89], v[82:83], off
	s_nop 0
	global_load_dwordx4 v[82:85], v[82:83], off offset:256
	v_lshlrev_b32_e32 v94, 16, v152
	v_and_b32_e32 v95, 0xffff0000, v152
	v_lshlrev_b32_e32 v120, 16, v154
	v_and_b32_e32 v121, 0xffff0000, v154
	v_lshlrev_b32_e32 v122, 16, v155
	v_and_b32_e32 v123, 0xffff0000, v155
	v_lshlrev_b32_e32 v96, 16, v153
	v_and_b32_e32 v97, 0xffff0000, v153
	v_pk_fma_f32 v[78:79], v[78:79], v[128:129], v[94:95]
	v_pk_fma_f32 v[94:95], v[76:77], v[126:127], v[122:123]
	v_pk_fma_f32 v[76:77], v[74:75], v[124:125], v[120:121]
	v_pk_fma_f32 v[80:81], v[80:81], v[130:131], v[96:97]
	v_pk_mul_f32 v[74:75], v[76:77], v[76:77]
	v_pk_mul_f32 v[96:97], v[94:95], v[94:95]
	v_pk_fma_f32 v[74:75], v[78:79], v[78:79], v[74:75]
	v_pk_fma_f32 v[96:97], v[80:81], v[80:81], v[96:97]
	v_add_f32_e32 v74, v74, v75
	v_add_f32_e32 v75, v96, v97
	v_add_f32_e32 v120, v74, v75
	v_cvt_pk_bf16_f32 v74, v78, v79
	v_cvt_pk_bf16_f32 v75, v80, v81
	v_cvt_pk_bf16_f32 v76, v76, v77
	v_cvt_pk_bf16_f32 v77, v94, v95
	v_lshlrev_b32_e32 v78, 16, v148
	v_and_b32_e32 v79, 0xffff0000, v148
	v_lshlrev_b32_e32 v80, 16, v149
	v_and_b32_e32 v81, 0xffff0000, v149
	v_lshlrev_b32_e32 v94, 16, v150
	v_and_b32_e32 v95, 0xffff0000, v150
	v_lshlrev_b32_e32 v96, 16, v151
	v_and_b32_e32 v97, 0xffff0000, v151
	v_pk_fma_f32 v[70:71], v[70:71], v[116:117], v[78:79]
	v_pk_fma_f32 v[72:73], v[72:73], v[118:119], v[80:81]
	v_pk_fma_f32 v[78:79], v[68:69], v[114:115], v[96:97]
	v_pk_fma_f32 v[80:81], v[66:67], v[112:113], v[94:95]
	v_pk_mul_f32 v[68:69], v[78:79], v[78:79]
	v_pk_mul_f32 v[66:67], v[80:81], v[80:81]
	v_pk_fma_f32 v[68:69], v[72:73], v[72:73], v[68:69]
	v_pk_fma_f32 v[66:67], v[70:71], v[70:71], v[66:67]
	s_nop 0
	v_add_f32_e32 v66, v66, v67
	v_add_f32_e32 v67, v68, v69
	v_add_f32_e32 v66, v66, v67
	v_add_f32_e32 v69, v120, v66
	ds_bpermute_b32 v96, v209, v69
	v_lshl_add_u64 v[66:67], s[22:23], 0, v[184:185]
	v_lshl_add_u64 v[94:95], v[66:67], 0, v[180:181]
	v_cvt_pk_bf16_f32 v68, v70, v71
	v_cvt_pk_bf16_f32 v70, v80, v81
	s_waitcnt lgkmcnt(0)
	v_add_f32_e32 v66, v69, v96
	ds_bpermute_b32 v67, v208, v66
	v_cvt_pk_bf16_f32 v69, v72, v73
	v_cvt_pk_bf16_f32 v71, v78, v79
	s_cbranch_vccnz .Lmy_wt_g4a_6
	global_store_dwordx4 v[94:95], v[74:77], off
.Lmy_wt_g4a_6r:
	s_cbranch_vccnz .Lmy_wt_g4a_7
	global_store_dwordx4 v[94:95], v[68:71], off offset:256
.Lmy_wt_g4a_7r:
	s_and_saveexec_b64 s[70:71], s[38:39]
	s_cbranch_execz .LBB0_1127
	v_lshlrev_b64 v[68:69], 6, v[182:183]
	v_lshl_add_u64 v[68:69], s[58:59], 0, v[68:69]
	v_lshl_add_u64 v[68:69], s[20:21], 2, v[68:69]
	s_lshl_b32 s48, s92, 2
	v_lshl_add_u64 v[68:69], v[68:69], 0, s[48:49]
	s_waitcnt lgkmcnt(0)
	v_add_f32_e32 v66, v66, v67
	global_store_dword v[68:69], v66, off
.LBB0_1127:
	s_or_b64 exec, exec, s[70:71]
	v_or_b32_e32 v74, 48, v140
	v_ashrrev_i32_e32 v75, 31, v74
	v_lshlrev_b64 v[76:77], 11, v[74:75]
	s_waitcnt lgkmcnt(0)
	v_lshl_add_u64 v[66:67], s[82:83], 0, v[76:77]
	v_lshl_add_u64 v[66:67], v[66:67], 0, v[180:181]
	global_load_dwordx4 v[70:73], v[66:67], off
	s_nop 0
	global_load_dwordx4 v[66:69], v[66:67], off offset:256
	s_waitcnt vmcnt(13)
	v_lshlrev_b32_e32 v78, 16, v136
	v_and_b32_e32 v79, 0xffff0000, v136
	v_lshlrev_b32_e32 v94, 16, v138
	v_and_b32_e32 v95, 0xffff0000, v138
	v_lshlrev_b32_e32 v96, 16, v139
	v_and_b32_e32 v97, 0xffff0000, v139
	v_lshlrev_b32_e32 v80, 16, v137
	v_and_b32_e32 v81, 0xffff0000, v137
	v_pk_fma_f32 v[62:63], v[62:63], v[128:129], v[78:79]
	v_pk_fma_f32 v[78:79], v[60:61], v[126:127], v[96:97]
	v_pk_fma_f32 v[60:61], v[58:59], v[124:125], v[94:95]
	v_pk_fma_f32 v[64:65], v[64:65], v[130:131], v[80:81]
	v_pk_mul_f32 v[58:59], v[60:61], v[60:61]
	v_pk_mul_f32 v[80:81], v[78:79], v[78:79]
	v_pk_fma_f32 v[58:59], v[62:63], v[62:63], v[58:59]
	v_pk_fma_f32 v[80:81], v[64:65], v[64:65], v[80:81]
	v_add_f32_e32 v58, v58, v59
	v_add_f32_e32 v59, v80, v81
	v_add_f32_e32 v94, v58, v59
	v_cvt_pk_bf16_f32 v58, v62, v63
	v_cvt_pk_bf16_f32 v59, v64, v65
	v_cvt_pk_bf16_f32 v60, v60, v61
	v_cvt_pk_bf16_f32 v61, v78, v79
	s_waitcnt vmcnt(12)
	v_lshlrev_b32_e32 v62, 16, v132
	v_and_b32_e32 v63, 0xffff0000, v132
	v_lshlrev_b32_e32 v64, 16, v133
	v_and_b32_e32 v65, 0xffff0000, v133
	v_lshlrev_b32_e32 v78, 16, v134
	v_and_b32_e32 v79, 0xffff0000, v134
	v_lshlrev_b32_e32 v80, 16, v135
	v_and_b32_e32 v81, 0xffff0000, v135
	v_pk_fma_f32 v[54:55], v[54:55], v[116:117], v[62:63]
	v_pk_fma_f32 v[56:57], v[56:57], v[118:119], v[64:65]
	v_pk_fma_f32 v[62:63], v[52:53], v[114:115], v[80:81]
	v_pk_fma_f32 v[64:65], v[50:51], v[112:113], v[78:79]
	v_pk_mul_f32 v[52:53], v[62:63], v[62:63]
	v_pk_mul_f32 v[50:51], v[64:65], v[64:65]
	v_pk_fma_f32 v[52:53], v[56:57], v[56:57], v[52:53]
	v_pk_fma_f32 v[50:51], v[54:55], v[54:55], v[50:51]
	s_nop 0
	v_add_f32_e32 v50, v50, v51
	v_add_f32_e32 v51, v52, v53
	v_add_f32_e32 v50, v50, v51
	v_add_f32_e32 v53, v94, v50
	ds_bpermute_b32 v80, v209, v53
	v_lshl_add_u64 v[50:51], s[22:23], 0, v[142:143]
	v_lshl_add_u64 v[78:79], v[50:51], 0, v[180:181]
	v_cvt_pk_bf16_f32 v52, v54, v55
	v_cvt_pk_bf16_f32 v54, v64, v65
	s_waitcnt lgkmcnt(0)
	v_add_f32_e32 v50, v53, v80
	ds_bpermute_b32 v51, v208, v50
	v_cvt_pk_bf16_f32 v53, v56, v57
	v_cvt_pk_bf16_f32 v55, v62, v63
	s_cbranch_vccnz .Lmy_wt_g4a_8
	global_store_dwordx4 v[78:79], v[58:61], off
.Lmy_wt_g4a_8r:
	s_cbranch_vccnz .Lmy_wt_g4a_9
	global_store_dwordx4 v[78:79], v[52:55], off offset:256
.Lmy_wt_g4a_9r:
	s_and_saveexec_b64 s[70:71], s[38:39]
	s_cbranch_execz .LBB0_1129
	v_lshlrev_b64 v[52:53], 6, v[140:141]
	v_lshl_add_u64 v[52:53], s[58:59], 0, v[52:53]
	v_lshl_add_u64 v[52:53], s[20:21], 2, v[52:53]
	s_lshl_b32 s48, s92, 2
	v_lshl_add_u64 v[52:53], v[52:53], 0, s[48:49]
	s_waitcnt lgkmcnt(0)
	v_add_f32_e32 v50, v50, v51
	global_store_dword v[52:53], v50, off
.LBB0_1129:
	s_or_b64 exec, exec, s[70:71]
	s_waitcnt vmcnt(11)
	v_lshlrev_b32_e32 v50, 16, v104
	s_waitcnt lgkmcnt(0)
	v_and_b32_e32 v51, 0xffff0000, v104
	v_lshlrev_b32_e32 v54, 16, v106
	v_and_b32_e32 v55, 0xffff0000, v106
	v_lshlrev_b32_e32 v56, 16, v107
	v_and_b32_e32 v57, 0xffff0000, v107
	v_lshlrev_b32_e32 v52, 16, v105
	v_and_b32_e32 v53, 0xffff0000, v105
	v_pk_fma_f32 v[46:47], v[46:47], v[128:129], v[50:51]
	v_pk_fma_f32 v[50:51], v[44:45], v[126:127], v[56:57]
	v_pk_fma_f32 v[44:45], v[42:43], v[124:125], v[54:55]
	v_pk_fma_f32 v[48:49], v[48:49], v[130:131], v[52:53]
	v_pk_mul_f32 v[42:43], v[44:45], v[44:45]
	v_pk_mul_f32 v[52:53], v[50:51], v[50:51]
	v_pk_fma_f32 v[42:43], v[46:47], v[46:47], v[42:43]
	v_pk_fma_f32 v[52:53], v[48:49], v[48:49], v[52:53]
	v_add_f32_e32 v42, v42, v43
	v_add_f32_e32 v43, v52, v53
	v_add_f32_e32 v54, v42, v43
	v_cvt_pk_bf16_f32 v42, v46, v47
	v_cvt_pk_bf16_f32 v43, v48, v49
	v_cvt_pk_bf16_f32 v44, v44, v45
	v_cvt_pk_bf16_f32 v45, v50, v51
	s_waitcnt vmcnt(10)
	v_lshlrev_b32_e32 v46, 16, v100
	v_and_b32_e32 v47, 0xffff0000, v100
	v_lshlrev_b32_e32 v48, 16, v101
	v_and_b32_e32 v49, 0xffff0000, v101
	v_lshlrev_b32_e32 v50, 16, v102
	v_and_b32_e32 v51, 0xffff0000, v102
	v_lshlrev_b32_e32 v52, 16, v103
	v_and_b32_e32 v53, 0xffff0000, v103
	v_pk_fma_f32 v[38:39], v[38:39], v[116:117], v[46:47]
	v_pk_fma_f32 v[40:41], v[40:41], v[118:119], v[48:49]
	v_pk_fma_f32 v[46:47], v[36:37], v[114:115], v[52:53]
	v_pk_fma_f32 v[48:49], v[34:35], v[112:113], v[50:51]
	v_pk_mul_f32 v[36:37], v[46:47], v[46:47]
	v_pk_mul_f32 v[34:35], v[48:49], v[48:49]
	v_pk_fma_f32 v[36:37], v[40:41], v[40:41], v[36:37]
	v_pk_fma_f32 v[34:35], v[38:39], v[38:39], v[34:35]
	s_nop 0
	v_add_f32_e32 v34, v34, v35
	v_add_f32_e32 v35, v36, v37
	v_add_f32_e32 v34, v34, v35
	v_add_f32_e32 v37, v54, v34
	ds_bpermute_b32 v52, v209, v37
	v_lshl_add_u64 v[34:35], s[22:23], 0, v[110:111]
	v_lshl_add_u64 v[50:51], v[178:179], 1, v[34:35]
	v_cvt_pk_bf16_f32 v36, v38, v39
	v_cvt_pk_bf16_f32 v38, v48, v49
	s_waitcnt lgkmcnt(0)
	v_add_f32_e32 v34, v37, v52
	ds_bpermute_b32 v35, v208, v34
	v_cvt_pk_bf16_f32 v37, v40, v41
	v_cvt_pk_bf16_f32 v39, v46, v47
	s_cbranch_vccnz .Lmy_wt_g4a_10
	global_store_dwordx4 v[50:51], v[42:45], off
.Lmy_wt_g4a_10r:
	s_cbranch_vccnz .Lmy_wt_g4a_11
	global_store_dwordx4 v[50:51], v[36:39], off offset:256
.Lmy_wt_g4a_11r:
	s_and_saveexec_b64 s[70:71], s[38:39]
	s_cbranch_execz .LBB0_1131
	v_lshlrev_b64 v[36:37], 6, v[108:109]
	v_lshl_add_u64 v[36:37], s[58:59], 0, v[36:37]
	v_lshl_add_u64 v[36:37], s[20:21], 2, v[36:37]
	s_lshl_b32 s48, s92, 2
	v_lshl_add_u64 v[36:37], v[36:37], 0, s[48:49]
	s_waitcnt lgkmcnt(0)
	v_add_f32_e32 v34, v34, v35
	global_store_dword v[36:37], v34, off
.LBB0_1131:
	s_or_b64 exec, exec, s[70:71]
	s_waitcnt vmcnt(9)
	v_lshlrev_b32_e32 v34, 16, v86
	s_waitcnt lgkmcnt(0)
	v_and_b32_e32 v35, 0xffff0000, v86
	v_lshlrev_b32_e32 v38, 16, v88
	v_and_b32_e32 v39, 0xffff0000, v88
	v_lshlrev_b32_e32 v40, 16, v89
	v_and_b32_e32 v41, 0xffff0000, v89
	v_lshlrev_b32_e32 v36, 16, v87
	v_and_b32_e32 v37, 0xffff0000, v87
	v_pk_fma_f32 v[30:31], v[30:31], v[128:129], v[34:35]
	v_pk_fma_f32 v[34:35], v[28:29], v[126:127], v[40:41]
	v_pk_fma_f32 v[28:29], v[26:27], v[124:125], v[38:39]
	v_pk_fma_f32 v[32:33], v[32:33], v[130:131], v[36:37]
	v_pk_mul_f32 v[26:27], v[28:29], v[28:29]
	v_pk_mul_f32 v[36:37], v[34:35], v[34:35]
	v_pk_fma_f32 v[26:27], v[30:31], v[30:31], v[26:27]
	v_pk_fma_f32 v[36:37], v[32:33], v[32:33], v[36:37]
	v_add_f32_e32 v26, v26, v27
	v_add_f32_e32 v27, v36, v37
	v_add_f32_e32 v38, v26, v27
	v_cvt_pk_bf16_f32 v26, v30, v31
	v_cvt_pk_bf16_f32 v27, v32, v33
	v_cvt_pk_bf16_f32 v28, v28, v29
	v_cvt_pk_bf16_f32 v29, v34, v35
	s_waitcnt vmcnt(8)
	v_lshlrev_b32_e32 v30, 16, v82
	v_and_b32_e32 v31, 0xffff0000, v82
	v_lshlrev_b32_e32 v32, 16, v83
	v_and_b32_e32 v33, 0xffff0000, v83
	v_lshlrev_b32_e32 v34, 16, v84
	v_and_b32_e32 v35, 0xffff0000, v84
	v_lshlrev_b32_e32 v36, 16, v85
	v_and_b32_e32 v37, 0xffff0000, v85
	v_pk_fma_f32 v[22:23], v[22:23], v[116:117], v[30:31]
	v_pk_fma_f32 v[24:25], v[24:25], v[118:119], v[32:33]
	v_pk_fma_f32 v[30:31], v[20:21], v[114:115], v[36:37]
	v_pk_fma_f32 v[32:33], v[18:19], v[112:113], v[34:35]
	v_pk_mul_f32 v[20:21], v[30:31], v[30:31]
	v_pk_mul_f32 v[18:19], v[32:33], v[32:33]
	v_pk_fma_f32 v[20:21], v[24:25], v[24:25], v[20:21]
	v_pk_fma_f32 v[18:19], v[22:23], v[22:23], v[18:19]
	s_nop 0
	v_add_f32_e32 v18, v18, v19
	v_add_f32_e32 v19, v20, v21
	v_add_f32_e32 v18, v18, v19
	v_add_f32_e32 v21, v38, v18
	ds_bpermute_b32 v36, v209, v21
	v_lshl_add_u64 v[18:19], s[22:23], 0, v[92:93]
	v_lshl_add_u64 v[34:35], v[178:179], 1, v[18:19]
	v_cvt_pk_bf16_f32 v20, v22, v23
	v_cvt_pk_bf16_f32 v22, v32, v33
	s_waitcnt lgkmcnt(0)
	v_add_f32_e32 v18, v21, v36
	ds_bpermute_b32 v19, v208, v18
	v_cvt_pk_bf16_f32 v21, v24, v25
	v_cvt_pk_bf16_f32 v23, v30, v31
	s_cbranch_vccnz .Lmy_wt_g4a_12
	global_store_dwordx4 v[34:35], v[26:29], off
.Lmy_wt_g4a_12r:
	s_cbranch_vccnz .Lmy_wt_g4a_13
	global_store_dwordx4 v[34:35], v[20:23], off offset:256
.Lmy_wt_g4a_13r:
	s_and_saveexec_b64 s[70:71], s[38:39]
	s_cbranch_execz .LBB0_1133
	v_lshlrev_b64 v[20:21], 6, v[90:91]
	v_lshl_add_u64 v[20:21], s[58:59], 0, v[20:21]
	v_lshl_add_u64 v[20:21], s[20:21], 2, v[20:21]
	s_lshl_b32 s48, s92, 2
	v_lshl_add_u64 v[20:21], v[20:21], 0, s[48:49]
	s_waitcnt lgkmcnt(0)
	v_add_f32_e32 v18, v18, v19
	global_store_dword v[20:21], v18, off
.LBB0_1133:
	s_or_b64 exec, exec, s[70:71]
	s_waitcnt vmcnt(7)
	v_lshlrev_b32_e32 v18, 16, v70
	s_waitcnt lgkmcnt(0)
	v_and_b32_e32 v19, 0xffff0000, v70
	v_lshlrev_b32_e32 v22, 16, v72
	v_and_b32_e32 v23, 0xffff0000, v72
	v_lshlrev_b32_e32 v24, 16, v73
	v_and_b32_e32 v25, 0xffff0000, v73
	v_lshlrev_b32_e32 v20, 16, v71
	v_and_b32_e32 v21, 0xffff0000, v71
	v_pk_fma_f32 v[14:15], v[14:15], v[128:129], v[18:19]
	v_pk_fma_f32 v[18:19], v[12:13], v[126:127], v[24:25]
	v_pk_fma_f32 v[12:13], v[10:11], v[124:125], v[22:23]
	v_pk_fma_f32 v[16:17], v[16:17], v[130:131], v[20:21]
	v_pk_mul_f32 v[10:11], v[12:13], v[12:13]
	v_pk_mul_f32 v[20:21], v[18:19], v[18:19]
	v_pk_fma_f32 v[10:11], v[14:15], v[14:15], v[10:11]
	v_pk_fma_f32 v[20:21], v[16:17], v[16:17], v[20:21]
	v_add_f32_e32 v10, v10, v11
	v_add_f32_e32 v11, v20, v21
	v_add_f32_e32 v22, v10, v11
	v_cvt_pk_bf16_f32 v10, v14, v15
	v_cvt_pk_bf16_f32 v11, v16, v17
	v_cvt_pk_bf16_f32 v12, v12, v13
	v_cvt_pk_bf16_f32 v13, v18, v19
	s_waitcnt vmcnt(6)
	v_lshlrev_b32_e32 v14, 16, v66
	v_and_b32_e32 v15, 0xffff0000, v66
	v_lshlrev_b32_e32 v16, 16, v67
	v_and_b32_e32 v17, 0xffff0000, v67
	v_lshlrev_b32_e32 v18, 16, v68
	v_and_b32_e32 v19, 0xffff0000, v68
	v_lshlrev_b32_e32 v20, 16, v69
	v_and_b32_e32 v21, 0xffff0000, v69
	v_pk_fma_f32 v[6:7], v[6:7], v[116:117], v[14:15]
	v_pk_fma_f32 v[8:9], v[8:9], v[118:119], v[16:17]
	v_pk_fma_f32 v[14:15], v[4:5], v[114:115], v[20:21]
	v_pk_fma_f32 v[16:17], v[2:3], v[112:113], v[18:19]
	v_pk_mul_f32 v[4:5], v[14:15], v[14:15]
	v_pk_mul_f32 v[2:3], v[16:17], v[16:17]
	v_pk_fma_f32 v[4:5], v[8:9], v[8:9], v[4:5]
	v_pk_fma_f32 v[2:3], v[6:7], v[6:7], v[2:3]
	s_nop 0
	v_add_f32_e32 v2, v2, v3
	v_add_f32_e32 v3, v4, v5
	v_add_f32_e32 v2, v2, v3
	v_add_f32_e32 v5, v22, v2
	ds_bpermute_b32 v20, v209, v5
	v_lshl_add_u64 v[2:3], s[22:23], 0, v[76:77]
	v_lshl_add_u64 v[18:19], v[178:179], 1, v[2:3]
	v_cvt_pk_bf16_f32 v4, v6, v7
	v_cvt_pk_bf16_f32 v6, v16, v17
	s_waitcnt lgkmcnt(0)
	v_add_f32_e32 v2, v5, v20
	ds_bpermute_b32 v3, v208, v2
	v_cvt_pk_bf16_f32 v5, v8, v9
	v_cvt_pk_bf16_f32 v7, v14, v15
	s_cbranch_vccnz .Lmy_wt_g4a_14
	global_store_dwordx4 v[18:19], v[10:13], off
.Lmy_wt_g4a_14r:
	s_cbranch_vccnz .Lmy_wt_g4a_15
	global_store_dwordx4 v[18:19], v[4:7], off offset:256
.Lmy_wt_g4a_15r:
	s_and_saveexec_b64 s[70:71], s[38:39]
	s_cbranch_execz .LBB0_1135
	v_lshlrev_b64 v[4:5], 6, v[74:75]
	v_lshl_add_u64 v[4:5], s[58:59], 0, v[4:5]
	v_lshl_add_u64 v[4:5], s[20:21], 2, v[4:5]
	s_lshl_b32 s48, s92, 2
	v_lshl_add_u64 v[4:5], v[4:5], 0, s[48:49]
	s_waitcnt lgkmcnt(0)
	v_add_f32_e32 v2, v2, v3
	global_store_dword v[4:5], v2, off

.Lmy_wt_g4a_0:
	global_store_dwordx4 v[140:141], v[132:135], off sc1
	s_branch .Lmy_wt_g4a_0r
.Lmy_wt_g4a_1:
	global_store_dwordx4 v[140:141], v[134:137], off offset:256 sc1
	s_branch .Lmy_wt_g4a_1r
.Lmy_wt_g4a_2:
	global_store_dwordx4 v[144:145], v[108:111], off sc1
	s_branch .Lmy_wt_g4a_2r
.Lmy_wt_g4a_3:
	global_store_dwordx4 v[144:145], v[102:105], off offset:256 sc1
	s_branch .Lmy_wt_g4a_3r
.Lmy_wt_g4a_4:
	global_store_dwordx4 v[120:121], v[90:93], off sc1
	s_branch .Lmy_wt_g4a_4r
.Lmy_wt_g4a_5:
	global_store_dwordx4 v[120:121], v[84:87], off offset:256 sc1
	s_branch .Lmy_wt_g4a_5r
.Lmy_wt_g4a_6:
	global_store_dwordx4 v[94:95], v[74:77], off sc1
	s_branch .Lmy_wt_g4a_6r
.Lmy_wt_g4a_7:
	global_store_dwordx4 v[94:95], v[68:71], off offset:256 sc1
	s_branch .Lmy_wt_g4a_7r
.Lmy_wt_g4a_8:
	global_store_dwordx4 v[78:79], v[58:61], off sc1
	s_branch .Lmy_wt_g4a_8r
.Lmy_wt_g4a_9:
	global_store_dwordx4 v[78:79], v[52:55], off offset:256 sc1
	s_branch .Lmy_wt_g4a_9r
.Lmy_wt_g4a_10:
	global_store_dwordx4 v[50:51], v[42:45], off sc1
	s_branch .Lmy_wt_g4a_10r
.Lmy_wt_g4a_11:
	global_store_dwordx4 v[50:51], v[36:39], off offset:256 sc1
	s_branch .Lmy_wt_g4a_11r
.Lmy_wt_g4a_12:
	global_store_dwordx4 v[34:35], v[26:29], off sc1
	s_branch .Lmy_wt_g4a_12r
.Lmy_wt_g4a_13:
	global_store_dwordx4 v[34:35], v[20:23], off offset:256 sc1
	s_branch .Lmy_wt_g4a_13r
.Lmy_wt_g4a_14:
	global_store_dwordx4 v[18:19], v[10:13], off sc1
	s_branch .Lmy_wt_g4a_14r
.Lmy_wt_g4a_15:
	global_store_dwordx4 v[18:19], v[4:7], off offset:256 sc1
	s_branch .Lmy_wt_g4a_15r

.LBB0_1175:
	s_lshl_b32 s6, s68, 8
	s_add_i32 s5, s6, 0xffffc000
	s_lshr_b32 s5, s5, 12
	s_ashr_i32 s4, s68, 5
	s_add_i32 s5, s5, 2
	s_cmp_lt_i32 s68, 64
	s_cselect_b32 s4, s4, s5
	s_ashr_i32 s5, s4, 31
	s_lshl_b64 s[4:5], s[4:5], 14
	v_lshl_or_b32 v164, s56, 8, v240
	s_add_u32 s44, s89, s4
	s_addc_u32 s45, s90, s5
	v_ashrrev_i32_e32 v165, 31, v164
	v_add_u32_e32 v222, s6, v238
	s_add_u32 s4, s8, s4
	v_lshlrev_b64 v[210:211], 1, v[164:165]
	v_ashrrev_i32_e32 v223, 31, v222
	v_lshlrev_b64 v[90:91], 2, v[164:165]
	s_addc_u32 s5, s9, s5
	v_lshl_add_u64 v[164:165], s[82:83], 0, v[210:211]
	v_lshlrev_b64 v[226:227], 11, v[222:223]
	v_lshl_add_u64 v[92:93], s[44:45], 0, v[90:91]
	v_lshl_add_u64 v[94:95], s[4:5], 0, v[90:91]
	v_lshl_add_u64 v[166:167], v[164:165], 0, v[226:227]
	global_load_dwordx4 v[120:123], v[92:93], off offset:16
	global_load_dwordx4 v[128:131], v[92:93], off
	global_load_dwordx4 v[108:111], v[94:95], off offset:16
	global_load_dwordx4 v[112:115], v[94:95], off
	global_load_dwordx4 v[100:103], v[92:93], off offset:528
	global_load_dwordx4 v[104:107], v[92:93], off offset:512
	s_nop 0
	global_load_dwordx4 v[90:93], v[94:95], off offset:528
	s_nop 0
	global_load_dwordx4 v[94:97], v[94:95], off offset:512
	s_nop 0
	global_load_dwordx4 v[192:195], v[166:167], off
	global_load_dwordx4 v[188:191], v[166:167], off offset:256
	v_or_b32_e32 v220, 16, v222
	v_ashrrev_i32_e32 v221, 31, v220
	v_or_b32_e32 v216, 32, v222
	v_or_b32_e32 v212, 48, v222
	v_lshlrev_b64 v[224:225], 11, v[220:221]
	v_ashrrev_i32_e32 v217, 31, v216
	v_ashrrev_i32_e32 v213, 31, v212
	v_lshl_add_u64 v[166:167], v[164:165], 0, v[224:225]
	v_lshlrev_b64 v[218:219], 11, v[216:217]
	v_lshlrev_b64 v[214:215], 11, v[212:213]
	global_load_dwordx4 v[184:187], v[166:167], off
	global_load_dwordx4 v[180:183], v[166:167], off offset:256
	v_lshl_add_u64 v[166:167], v[164:165], 0, v[218:219]
	v_lshl_add_u64 v[164:165], v[164:165], 0, v[214:215]
	global_load_dwordx4 v[176:179], v[166:167], off
	global_load_dwordx4 v[172:175], v[166:167], off offset:256
	global_load_dwordx4 v[168:171], v[164:165], off
	s_nop 0
	global_load_dwordx4 v[164:167], v[164:165], off offset:256
	v_and_b32_e32 v201, 64, v229
	v_xor_b32_e32 v200, 16, v229
	v_add_u32_e32 v201, 64, v201
	v_cmp_lt_i32_e32 vcc, v200, v201
	s_lshl_b32 s56, s56, 2
	s_ashr_i32 s57, s56, 31
	v_cndmask_b32_e32 v200, v229, v200, vcc
	v_lshlrev_b32_e32 v242, 2, v200
	v_xor_b32_e32 v200, 32, v229
	v_cmp_lt_i32_e32 vcc, v200, v201
	s_waitcnt vmcnt(0)
	v_and_b32_e32 v201, 0xffff0000, v192
	v_cndmask_b32_e32 v200, v229, v200, vcc
	s_andn2_b64 vcc, exec, s[30:31]
	v_lshlrev_b32_e32 v243, 2, v200
	v_lshlrev_b32_e32 v200, 16, v192
	v_lshlrev_b32_e32 v192, 16, v193
	v_and_b32_e32 v193, 0xffff0000, v193
	v_lshlrev_b32_e32 v202, 16, v194
	v_and_b32_e32 v203, 0xffff0000, v194
	v_lshlrev_b32_e32 v194, 16, v195
	v_and_b32_e32 v195, 0xffff0000, v195
	v_pk_fma_f32 v[162:163], v[162:163], v[130:131], v[192:193]
	v_pk_fma_f32 v[192:193], v[158:159], v[122:123], v[194:195]
	v_pk_fma_f32 v[194:195], v[156:157], v[120:121], v[202:203]
	v_pk_fma_f32 v[160:161], v[160:161], v[128:129], v[200:201]
	v_pk_mul_f32 v[156:157], v[194:195], v[194:195]
	v_pk_mul_f32 v[158:159], v[192:193], v[192:193]
	v_pk_fma_f32 v[156:157], v[160:161], v[160:161], v[156:157]
	v_pk_fma_f32 v[158:159], v[162:163], v[162:163], v[158:159]
	v_add_f32_e32 v156, v156, v157
	v_add_f32_e32 v157, v158, v159
	v_lshl_add_u64 v[200:201], s[82:83], 0, v[226:227]
	v_add_f32_e32 v202, v156, v157
	v_cvt_pk_bf16_f32 v156, v160, v161
	v_cvt_pk_bf16_f32 v157, v162, v163
	v_cvt_pk_bf16_f32 v158, v194, v195
	v_cvt_pk_bf16_f32 v159, v192, v193
	v_lshl_add_u64 v[200:201], v[200:201], 0, v[210:211]
	s_cbranch_vccnz .Lmy_wt_g4b_0
	global_store_dwordx4 v[200:201], v[156:159], off

.Lmy_wt_g4b_3r:
	ds_bpermute_b32 v148, v242, v162
	s_waitcnt lgkmcnt(0)
	v_add_f32_e32 v148, v162, v148
	ds_bpermute_b32 v149, v243, v148
	s_and_saveexec_b64 s[68:69], s[38:39]
	s_cbranch_execz .LBB0_1177
	v_lshlrev_b64 v[150:151], 6, v[222:223]
	v_lshl_add_u64 v[150:151], s[58:59], 0, v[150:151]
	v_lshl_add_u64 v[150:151], s[56:57], 2, v[150:151]
	s_lshl_b32 s48, s92, 2
	v_lshl_add_u64 v[150:151], v[150:151], 0, s[48:49]
	s_waitcnt lgkmcnt(0)
	v_add_f32_e32 v148, v148, v149
	global_store_dword v[150:151], v148, off
.LBB0_1177:
	s_or_b64 exec, exec, s[68:69]
	v_add_u32_e32 v156, 0x80, v222
	v_ashrrev_i32_e32 v157, 31, v156
	v_lshlrev_b64 v[160:161], 11, v[156:157]
	s_waitcnt lgkmcnt(0)
	v_lshl_add_u64 v[148:149], s[82:83], 0, v[160:161]
	v_lshl_add_u64 v[158:159], v[148:149], 0, v[210:211]
	global_load_dwordx4 v[152:155], v[158:159], off
	global_load_dwordx4 v[148:151], v[158:159], off offset:256
	v_lshlrev_b32_e32 v162, 16, v184
	v_and_b32_e32 v163, 0xffff0000, v184
	v_lshlrev_b32_e32 v184, 16, v185
	v_and_b32_e32 v185, 0xffff0000, v185
	v_lshlrev_b32_e32 v188, 16, v186
	v_and_b32_e32 v189, 0xffff0000, v186
	v_lshlrev_b32_e32 v186, 16, v187
	v_and_b32_e32 v187, 0xffff0000, v187
	v_pk_fma_f32 v[144:145], v[144:145], v[128:129], v[162:163]
	v_pk_fma_f32 v[146:147], v[146:147], v[130:131], v[184:185]
	v_pk_fma_f32 v[162:163], v[142:143], v[122:123], v[186:187]
	v_pk_fma_f32 v[184:185], v[140:141], v[120:121], v[188:189]
	v_pk_mul_f32 v[142:143], v[162:163], v[162:163]
	v_pk_mul_f32 v[140:141], v[184:185], v[184:185]
	v_pk_fma_f32 v[142:143], v[146:147], v[146:147], v[142:143]
	v_pk_fma_f32 v[140:141], v[144:145], v[144:145], v[140:141]
	v_lshl_add_u64 v[186:187], s[82:83], 0, v[224:225]
	v_add_f32_e32 v140, v140, v141
	v_add_f32_e32 v141, v142, v143
	v_add_f32_e32 v188, v140, v141
	v_cvt_pk_bf16_f32 v140, v144, v145
	v_cvt_pk_bf16_f32 v141, v146, v147
	v_cvt_pk_bf16_f32 v142, v184, v185
	v_cvt_pk_bf16_f32 v143, v162, v163
	v_lshl_add_u64 v[186:187], v[186:187], 0, v[210:211]
	s_cbranch_vccnz .Lmy_wt_g4b_4
	global_store_dwordx4 v[186:187], v[140:143], off

.Lmy_wt_g4b_7r:
	s_and_saveexec_b64 s[68:69], s[38:39]
	s_cbranch_execz .LBB0_1179
	v_lshlrev_b64 v[134:135], 6, v[220:221]
	v_lshl_add_u64 v[134:135], s[58:59], 0, v[134:135]
	v_lshl_add_u64 v[134:135], s[56:57], 2, v[134:135]
	s_lshl_b32 s48, s92, 2
	v_lshl_add_u64 v[134:135], v[134:135], 0, s[48:49]
	s_waitcnt lgkmcnt(0)
	v_add_f32_e32 v132, v132, v133
	global_store_dword v[134:135], v132, off
.LBB0_1179:
	s_or_b64 exec, exec, s[68:69]
	v_or_b32_e32 v140, 16, v156
	v_ashrrev_i32_e32 v141, 31, v140
	v_lshlrev_b64 v[144:145], 11, v[140:141]
	s_waitcnt lgkmcnt(0)
	v_lshl_add_u64 v[132:133], s[82:83], 0, v[144:145]
	v_lshl_add_u64 v[142:143], v[132:133], 0, v[210:211]
	global_load_dwordx4 v[136:139], v[142:143], off
	global_load_dwordx4 v[132:135], v[142:143], off offset:256
	v_lshlrev_b32_e32 v146, 16, v176
	v_and_b32_e32 v147, 0xffff0000, v176
	v_lshlrev_b32_e32 v162, 16, v177
	v_and_b32_e32 v163, 0xffff0000, v177
	v_lshlrev_b32_e32 v176, 16, v178
	v_and_b32_e32 v177, 0xffff0000, v178
	v_lshlrev_b32_e32 v178, 16, v179
	v_and_b32_e32 v179, 0xffff0000, v179
	v_pk_fma_f32 v[124:125], v[124:125], v[128:129], v[146:147]
	v_pk_fma_f32 v[126:127], v[126:127], v[130:131], v[162:163]
	v_pk_fma_f32 v[146:147], v[118:119], v[122:123], v[178:179]
	v_pk_fma_f32 v[162:163], v[116:117], v[120:121], v[176:177]
	v_pk_mul_f32 v[118:119], v[146:147], v[146:147]
	v_pk_mul_f32 v[116:117], v[162:163], v[162:163]
	v_pk_fma_f32 v[118:119], v[126:127], v[126:127], v[118:119]
	v_pk_fma_f32 v[116:117], v[124:125], v[124:125], v[116:117]
	v_lshl_add_u64 v[176:177], s[82:83], 0, v[218:219]
	v_add_f32_e32 v116, v116, v117
	v_add_f32_e32 v117, v118, v119
	v_add_f32_e32 v178, v116, v117
	v_cvt_pk_bf16_f32 v116, v124, v125
	v_cvt_pk_bf16_f32 v117, v126, v127
	v_cvt_pk_bf16_f32 v118, v162, v163
	v_cvt_pk_bf16_f32 v119, v146, v147
	v_lshl_add_u64 v[176:177], v[176:177], 0, v[210:211]
	s_cbranch_vccnz .Lmy_wt_g4b_8
	global_store_dwordx4 v[176:177], v[116:119], off

.Lmy_wt_g4b_11r:
	s_and_saveexec_b64 s[68:69], s[38:39]
	s_mov_b64 s[78:79], 0x10000
	s_cbranch_execz .LBB0_1181
	v_lshlrev_b64 v[84:85], 6, v[216:217]
	v_lshl_add_u64 v[84:85], s[58:59], 0, v[84:85]
	v_lshl_add_u64 v[84:85], s[56:57], 2, v[84:85]
	s_lshl_b32 s48, s92, 2
	v_lshl_add_u64 v[84:85], v[84:85], 0, s[48:49]
	s_waitcnt lgkmcnt(0)
	v_add_f32_e32 v82, v82, v83
	global_store_dword v[84:85], v82, off
.LBB0_1181:
	s_or_b64 exec, exec, s[68:69]
	v_or_b32_e32 v116, 32, v156
	v_ashrrev_i32_e32 v117, 31, v116
	v_lshlrev_b64 v[124:125], 11, v[116:117]
	s_waitcnt lgkmcnt(0)
	v_lshl_add_u64 v[82:83], s[82:83], 0, v[124:125]
	v_lshl_add_u64 v[118:119], v[82:83], 0, v[210:211]
	global_load_dwordx4 v[86:89], v[118:119], off
	global_load_dwordx4 v[82:85], v[118:119], off offset:256
	v_lshlrev_b32_e32 v126, 16, v168
	v_and_b32_e32 v127, 0xffff0000, v168
	v_lshlrev_b32_e32 v146, 16, v169
	v_and_b32_e32 v147, 0xffff0000, v169
	v_lshlrev_b32_e32 v162, 16, v170
	v_and_b32_e32 v163, 0xffff0000, v170
	v_lshlrev_b32_e32 v168, 16, v171
	v_and_b32_e32 v169, 0xffff0000, v171
	v_pk_fma_f32 v[78:79], v[78:79], v[128:129], v[126:127]
	v_pk_fma_f32 v[80:81], v[80:81], v[130:131], v[146:147]
	v_pk_fma_f32 v[126:127], v[76:77], v[122:123], v[168:169]
	v_pk_fma_f32 v[146:147], v[74:75], v[120:121], v[162:163]
	v_pk_mul_f32 v[76:77], v[126:127], v[126:127]
	v_pk_mul_f32 v[74:75], v[146:147], v[146:147]
	v_pk_fma_f32 v[76:77], v[80:81], v[80:81], v[76:77]
	v_pk_fma_f32 v[74:75], v[78:79], v[78:79], v[74:75]
	v_lshl_add_u64 v[162:163], s[82:83], 0, v[214:215]
	v_add_f32_e32 v74, v74, v75
	v_add_f32_e32 v75, v76, v77
	v_add_f32_e32 v168, v74, v75
	v_cvt_pk_bf16_f32 v74, v78, v79
	v_cvt_pk_bf16_f32 v75, v80, v81
	v_cvt_pk_bf16_f32 v76, v146, v147
	v_cvt_pk_bf16_f32 v77, v126, v127
	v_lshl_add_u64 v[162:163], v[162:163], 0, v[210:211]
	s_cbranch_vccnz .Lmy_wt_g4b_12
	global_store_dwordx4 v[162:163], v[74:77], off

.Lmy_wt_g4b_15r:
	s_and_saveexec_b64 s[68:69], s[38:39]
	s_cbranch_execz .LBB0_1183
	v_lshlrev_b64 v[68:69], 6, v[212:213]
	v_lshl_add_u64 v[68:69], s[58:59], 0, v[68:69]
	v_lshl_add_u64 v[68:69], s[56:57], 2, v[68:69]
	s_lshl_b32 s48, s92, 2
	v_lshl_add_u64 v[68:69], v[68:69], 0, s[48:49]
	s_waitcnt lgkmcnt(0)
	v_add_f32_e32 v66, v66, v67
	global_store_dword v[68:69], v66, off
.LBB0_1183:
	s_or_b64 exec, exec, s[68:69]
	v_or_b32_e32 v74, 48, v156
	v_ashrrev_i32_e32 v75, 31, v74
	v_lshlrev_b64 v[78:79], 11, v[74:75]
	s_waitcnt lgkmcnt(0)
	v_lshl_add_u64 v[66:67], s[82:83], 0, v[78:79]
	v_lshl_add_u64 v[76:77], v[66:67], 0, v[210:211]
	global_load_dwordx4 v[70:73], v[76:77], off
	global_load_dwordx4 v[66:69], v[76:77], off offset:256
	s_waitcnt vmcnt(19)
	v_lshlrev_b32_e32 v80, 16, v152
	v_and_b32_e32 v81, 0xffff0000, v152
	v_lshlrev_b32_e32 v126, 16, v153
	v_and_b32_e32 v127, 0xffff0000, v153
	v_lshlrev_b32_e32 v146, 16, v154
	v_and_b32_e32 v147, 0xffff0000, v154
	v_lshlrev_b32_e32 v152, 16, v155
	v_and_b32_e32 v153, 0xffff0000, v155
	v_pk_fma_f32 v[62:63], v[62:63], v[128:129], v[80:81]
	v_pk_fma_f32 v[64:65], v[64:65], v[130:131], v[126:127]
	v_pk_fma_f32 v[80:81], v[60:61], v[122:123], v[152:153]
	v_pk_fma_f32 v[126:127], v[58:59], v[120:121], v[146:147]
	v_pk_mul_f32 v[60:61], v[80:81], v[80:81]
	v_pk_mul_f32 v[58:59], v[126:127], v[126:127]
	v_pk_fma_f32 v[60:61], v[64:65], v[64:65], v[60:61]
	v_pk_fma_f32 v[58:59], v[62:63], v[62:63], v[58:59]
	s_nop 0
	v_add_f32_e32 v58, v58, v59
	v_add_f32_e32 v59, v60, v61
	v_add_f32_e32 v146, v58, v59
	v_cvt_pk_bf16_f32 v58, v62, v63
	v_cvt_pk_bf16_f32 v59, v64, v65
	v_cvt_pk_bf16_f32 v60, v126, v127
	v_cvt_pk_bf16_f32 v61, v80, v81
	s_cbranch_vccnz .Lmy_wt_g4b_16
	global_store_dwordx4 v[158:159], v[58:61], off

.Lmy_wt_g4b_19r:
	s_and_saveexec_b64 s[68:69], s[38:39]
	s_cbranch_execz .LBB0_1185
	v_lshlrev_b64 v[52:53], 6, v[156:157]
	v_lshl_add_u64 v[52:53], s[58:59], 0, v[52:53]
	v_lshl_add_u64 v[52:53], s[56:57], 2, v[52:53]
	s_lshl_b32 s48, s92, 2
	v_lshl_add_u64 v[52:53], v[52:53], 0, s[48:49]
	s_waitcnt lgkmcnt(0)
	v_add_f32_e32 v50, v50, v51
	global_store_dword v[52:53], v50, off
.LBB0_1185:
	s_or_b64 exec, exec, s[68:69]
	s_waitcnt vmcnt(17)
	v_lshlrev_b32_e32 v50, 16, v136
	s_waitcnt lgkmcnt(0)
	v_and_b32_e32 v51, 0xffff0000, v136
	v_lshlrev_b32_e32 v52, 16, v137
	v_and_b32_e32 v53, 0xffff0000, v137
	v_lshlrev_b32_e32 v54, 16, v138
	v_and_b32_e32 v55, 0xffff0000, v138
	v_lshlrev_b32_e32 v56, 16, v139
	v_and_b32_e32 v57, 0xffff0000, v139
	v_pk_fma_f32 v[46:47], v[46:47], v[128:129], v[50:51]
	v_pk_fma_f32 v[48:49], v[48:49], v[130:131], v[52:53]
	v_pk_fma_f32 v[50:51], v[44:45], v[122:123], v[56:57]
	v_pk_fma_f32 v[52:53], v[42:43], v[120:121], v[54:55]
	v_pk_mul_f32 v[44:45], v[50:51], v[50:51]
	v_pk_mul_f32 v[42:43], v[52:53], v[52:53]
	v_pk_fma_f32 v[44:45], v[48:49], v[48:49], v[44:45]
	v_pk_fma_f32 v[42:43], v[46:47], v[46:47], v[42:43]
	s_nop 0
	v_add_f32_e32 v42, v42, v43
	v_add_f32_e32 v43, v44, v45
	v_add_f32_e32 v54, v42, v43
	v_cvt_pk_bf16_f32 v42, v46, v47
	v_cvt_pk_bf16_f32 v43, v48, v49
	v_cvt_pk_bf16_f32 v44, v52, v53
	v_cvt_pk_bf16_f32 v45, v50, v51
	s_cbranch_vccnz .Lmy_wt_g4b_20
	global_store_dwordx4 v[142:143], v[42:45], off

.Lmy_wt_g4b_23r:
	s_and_saveexec_b64 s[68:69], s[38:39]
	s_cbranch_execz .LBB0_1187
	v_lshlrev_b64 v[36:37], 6, v[140:141]
	v_lshl_add_u64 v[36:37], s[58:59], 0, v[36:37]
	v_lshl_add_u64 v[36:37], s[56:57], 2, v[36:37]
	s_lshl_b32 s48, s92, 2
	v_lshl_add_u64 v[36:37], v[36:37], 0, s[48:49]
	s_waitcnt lgkmcnt(0)
	v_add_f32_e32 v34, v34, v35
	global_store_dword v[36:37], v34, off
.LBB0_1187:
	s_or_b64 exec, exec, s[68:69]
	s_waitcnt vmcnt(15)
	v_lshlrev_b32_e32 v34, 16, v86
	s_waitcnt lgkmcnt(0)
	v_and_b32_e32 v35, 0xffff0000, v86
	v_lshlrev_b32_e32 v36, 16, v87
	v_and_b32_e32 v37, 0xffff0000, v87
	v_lshlrev_b32_e32 v38, 16, v88
	v_and_b32_e32 v39, 0xffff0000, v88
	v_lshlrev_b32_e32 v40, 16, v89
	v_and_b32_e32 v41, 0xffff0000, v89
	v_pk_fma_f32 v[30:31], v[30:31], v[128:129], v[34:35]
	v_pk_fma_f32 v[32:33], v[32:33], v[130:131], v[36:37]
	v_pk_fma_f32 v[34:35], v[28:29], v[122:123], v[40:41]
	v_pk_fma_f32 v[36:37], v[26:27], v[120:121], v[38:39]
	v_pk_mul_f32 v[28:29], v[34:35], v[34:35]
	v_pk_mul_f32 v[26:27], v[36:37], v[36:37]
	v_pk_fma_f32 v[28:29], v[32:33], v[32:33], v[28:29]
	v_pk_fma_f32 v[26:27], v[30:31], v[30:31], v[26:27]
	s_nop 0
	v_add_f32_e32 v26, v26, v27
	v_add_f32_e32 v27, v28, v29
	v_add_f32_e32 v38, v26, v27
	v_cvt_pk_bf16_f32 v26, v30, v31
	v_cvt_pk_bf16_f32 v27, v32, v33
	v_cvt_pk_bf16_f32 v28, v36, v37
	v_cvt_pk_bf16_f32 v29, v34, v35
	s_cbranch_vccnz .Lmy_wt_g4b_24
	global_store_dwordx4 v[118:119], v[26:29], off

.Lmy_wt_g4b_27r:
	s_and_saveexec_b64 s[68:69], s[38:39]
	s_cbranch_execz .LBB0_1189
	v_lshlrev_b64 v[20:21], 6, v[116:117]
	v_lshl_add_u64 v[20:21], s[58:59], 0, v[20:21]
	v_lshl_add_u64 v[20:21], s[56:57], 2, v[20:21]
	s_lshl_b32 s48, s92, 2
	v_lshl_add_u64 v[20:21], v[20:21], 0, s[48:49]
	s_waitcnt lgkmcnt(0)
	v_add_f32_e32 v18, v18, v19
	global_store_dword v[20:21], v18, off
.LBB0_1189:
	s_or_b64 exec, exec, s[68:69]
	s_waitcnt vmcnt(13)
	v_lshlrev_b32_e32 v18, 16, v70
	s_waitcnt lgkmcnt(0)
	v_and_b32_e32 v19, 0xffff0000, v70
	v_lshlrev_b32_e32 v20, 16, v71
	v_and_b32_e32 v21, 0xffff0000, v71
	v_lshlrev_b32_e32 v22, 16, v72
	v_and_b32_e32 v23, 0xffff0000, v72
	v_lshlrev_b32_e32 v24, 16, v73
	v_and_b32_e32 v25, 0xffff0000, v73
	v_pk_fma_f32 v[14:15], v[14:15], v[128:129], v[18:19]
	v_pk_fma_f32 v[16:17], v[16:17], v[130:131], v[20:21]
	v_pk_fma_f32 v[18:19], v[12:13], v[122:123], v[24:25]
	v_pk_fma_f32 v[20:21], v[10:11], v[120:121], v[22:23]
	v_pk_mul_f32 v[12:13], v[18:19], v[18:19]
	v_pk_mul_f32 v[10:11], v[20:21], v[20:21]
	v_pk_fma_f32 v[12:13], v[16:17], v[16:17], v[12:13]
	v_pk_fma_f32 v[10:11], v[14:15], v[14:15], v[10:11]
	s_nop 0
	v_add_f32_e32 v10, v10, v11
	v_add_f32_e32 v11, v12, v13
	v_add_f32_e32 v22, v10, v11
	v_cvt_pk_bf16_f32 v10, v14, v15
	v_cvt_pk_bf16_f32 v11, v16, v17
	v_cvt_pk_bf16_f32 v12, v20, v21
	v_cvt_pk_bf16_f32 v13, v18, v19
	s_cbranch_vccnz .Lmy_wt_g4b_28
	global_store_dwordx4 v[76:77], v[10:13], off

.Lmy_wt_g4b_31r:
	s_and_saveexec_b64 s[68:69], s[38:39]
	s_cbranch_execz .LBB0_1191
	v_lshlrev_b64 v[4:5], 6, v[74:75]
	v_lshl_add_u64 v[4:5], s[58:59], 0, v[4:5]
	v_lshl_add_u64 v[4:5], s[56:57], 2, v[4:5]
	s_lshl_b32 s48, s92, 2
	v_lshl_add_u64 v[4:5], v[4:5], 0, s[48:49]
	s_waitcnt lgkmcnt(0)
	v_add_f32_e32 v2, v2, v3
	global_store_dword v[4:5], v2, off
